# EpiResid load hoist + xattn/mixerC units remapped so K/V-sharing tiles run on one XCD (L2 reuse)
# speedup vs baseline: 1.0018x; 1.0018x over previous
.LBB0_858:
	s_or_b64 exec, exec, s[0:1]
	v_readlane_b32 s0, v244, 53
	v_readlane_b32 s1, v244, 54
	v_mov_b32_e32 v140, v190
	s_and_b64 vcc, exec, s[0:1]
	s_waitcnt lgkmcnt(0)
	s_barrier
	s_cbranch_vccnz .LBB0_863
	v_bfe_u32 v0, v140, 2, 2
	v_and_b32_e32 v1, 3, v140
	v_bfe_u32 v141, v140, 4, 2
	v_lshl_or_b32 v1, v0, 3, v1
	v_lshlrev_b32_e32 v4, 8, v1
	v_bitop3_b32 v5, v1, v141, 11 bitop3:0x6c
	v_lshl_or_b32 v143, v5, 4, v4
	v_or_b32_e32 v5, 4, v141
	v_bitop3_b32 v6, v1, v5, 11 bitop3:0x6c
	v_lshl_or_b32 v144, v6, 4, v4
	v_or_b32_e32 v6, 8, v141
	v_bitop3_b32 v7, v1, v6, 11 bitop3:0x6c
	v_lshlrev_b32_e32 v128, 3, v141
	v_lshlrev_b32_e32 v3, 3, v140
	v_lshl_or_b32 v145, v7, 4, v4
	v_or_b32_e32 v7, 12, v141
	v_or_b32_e32 v0, v128, v0
	v_bfe_u32 v2, v140, 1, 1
	v_and_b32_e32 v3, 8, v3
	v_bitop3_b32 v8, v1, v7, 11 bitop3:0x6c
	v_lshl_or_b32 v146, v8, 4, v4
	v_lshl_or_b32 v4, v0, 8, v3
	v_bitop3_b32 v8, v0, v2, 11 bitop3:0x6c
	v_lshl_or_b32 v147, v8, 4, v4
	v_or_b32_e32 v8, 2, v2
	v_bitop3_b32 v9, v0, v8, 11 bitop3:0x6c
	v_lshl_or_b32 v148, v9, 4, v4
	v_or_b32_e32 v9, 4, v2
	v_bitop3_b32 v10, v0, v9, 11 bitop3:0x6c
	v_lshl_or_b32 v149, v10, 4, v4
	v_or_b32_e32 v10, 6, v2
	v_bitop3_b32 v11, v0, v10, 11 bitop3:0x6c
	v_lshl_or_b32 v150, v11, 4, v4
	v_or_b32_e32 v11, 8, v2
	v_bitop3_b32 v12, v0, v11, 11 bitop3:0x6c
	v_lshl_or_b32 v151, v12, 4, v4
	v_or_b32_e32 v12, 10, v2
	v_bitop3_b32 v13, v0, v12, 11 bitop3:0x6c
	v_lshl_or_b32 v152, v13, 4, v4
	v_or_b32_e32 v13, 12, v2
	v_bitop3_b32 v14, v0, v13, 11 bitop3:0x6c
	v_lshl_or_b32 v153, v14, 4, v4
	v_or_b32_e32 v14, 14, v2
	v_bitop3_b32 v15, v0, v14, 11 bitop3:0x6c
	v_or_b32_e32 v1, 4, v1
	v_lshl_or_b32 v154, v15, 4, v4
	v_lshlrev_b32_e32 v4, 8, v1
	v_bitop3_b32 v5, v1, v5, 15 bitop3:0x6c
	v_bitop3_b32 v15, v1, v141, 15 bitop3:0x6c
	v_lshl_or_b32 v156, v5, 4, v4
	v_bitop3_b32 v5, v1, v6, 15 bitop3:0x6c
	v_bitop3_b32 v1, v1, v7, 15 bitop3:0x6c
	v_or_b32_e32 v0, 4, v0
	v_lshl_or_b32 v158, v1, 4, v4
	v_lshl_or_b32 v1, v0, 8, v3
	v_bitop3_b32 v2, v0, v2, 15 bitop3:0x6c
	v_lshl_or_b32 v159, v2, 4, v1
	v_bitop3_b32 v2, v0, v8, 15 bitop3:0x6c
	v_lshl_or_b32 v160, v2, 4, v1
	v_bitop3_b32 v2, v0, v9, 15 bitop3:0x6c
	v_lshl_or_b32 v161, v2, 4, v1
	v_bitop3_b32 v2, v0, v10, 15 bitop3:0x6c
	v_lshl_or_b32 v162, v2, 4, v1
	v_bitop3_b32 v2, v0, v11, 15 bitop3:0x6c
	v_lshl_or_b32 v163, v2, 4, v1
	v_bitop3_b32 v2, v0, v12, 15 bitop3:0x6c
	v_lshl_or_b32 v164, v2, 4, v1
	v_bitop3_b32 v2, v0, v13, 15 bitop3:0x6c
	v_bitop3_b32 v0, v0, v14, 15 bitop3:0x6c
	v_mov_b32_e32 v129, 0
	v_lshl_or_b32 v155, v15, 4, v4
	v_lshl_or_b32 v165, v2, 4, v1
	v_lshl_or_b32 v166, v0, 4, v1
	v_lshlrev_b32_e32 v0, 2, v141
	v_lshl_add_u64 v[2:3], s[92:93], 0, v[128:129]
	s_mov_b64 s[0:1], 0x1dd00080
	v_and_b32_e32 v142, 15, v140
	v_lshl_or_b32 v157, v5, 4, v4
	s_lshl_b32 s12, s2, 5
	s_lshl_b32 s13, s94, 5
	v_lshlrev_b32_e32 v167, 13, v141
	v_lshl_add_u64 v[130:131], v[2:3], 0, s[0:1]
	s_lshl_b32 s14, s2, 7
	s_lshl_b32 s15, s94, 7
	s_mov_b32 s1, 0
	v_lshlrev_b32_e32 v132, 1, v128
	v_mov_b32_e32 v133, v129
	v_add_u32_e32 v168, 0, v143
	s_add_i32 s16, 0, 0x10000
	v_lshlrev_b32_e32 v134, 1, v0
	v_add_u32_e32 v169, 0, v155
	v_mbcnt_hi_u32_b32 v170, -1, v191
	s_mov_b32 s17, s2
	s_mov_b32 s98, s2
.LBB0_860:
	s_mov_b32 s17, s98
	s_cmpk_lg_i32 s94, 0x100
	s_cbranch_scc1 .Lxa_map_860
	s_and_b32 s99, s98, 7
	s_lshl_b32 s99, s99, 1
	s_bfe_u32 s17, s98, 0x10007
	s_add_i32 s99, s99, s17
	s_lshr_b32 s17, s98, 8
	s_lshl_b32 s17, s17, 4
	s_add_i32 s99, s99, s17
	s_lshl_b32 s99, s99, 4
	s_bfe_u32 s17, s98, 0x40003
	s_or_b32 s17, s99, s17
.Lxa_map_860:
	s_lshl_b32 s12, s17, 5
	s_lshl_b32 s14, s17, 7
	s_lshl_b32 s0, s12, 1
	s_and_b32 s23, s0, 0xc00
	s_and_b32 s0, s14, 0x780
	v_or_b32_e32 v128, s0, v142
	s_ashr_i32 s10, s17, 6
	v_readfirstlane_b32 s0, v140
	s_ashr_i32 s4, s0, 6
	s_ashr_i32 s11, s10, 31
	s_lshl_b32 s0, s17, 7
	s_lshl_b64 s[6:7], s[10:11], 11
	s_and_b32 s0, s0, 0x780
	s_lshl_b32 s10, s10, 8
	s_lshl_b32 s8, s4, 4
	v_or_b32_e32 v0, s0, v142
	s_lshl_b32 s0, s17, 5
	s_ashr_i32 s11, s10, 31
	s_ashr_i32 s9, s8, 31
	s_and_b32 s22, s0, 0x600
	s_lshl_b64 s[10:11], s[10:11], 13
	s_add_u32 s5, s84, s10
	v_or_b32_e32 v0, s6, v0
	v_mov_b32_e32 v1, s7
	s_addc_u32 s25, s85, s11
	s_lshl_b32 s0, s22, 1
	v_lshl_add_u64 v[0:1], v[0:1], 0, s[8:9]
	s_add_u32 s24, s5, s0
	v_lshlrev_b64 v[136:137], 11, v[0:1]
	s_addc_u32 s25, s25, 0
	s_lshl_b32 s5, s4, 2
	v_lshlrev_b64 v[0:1], 12, v[0:1]
	v_bitop3_b32 v3, s5, v140, v141 bitop3:0x36
	v_lshl_add_u64 v[0:1], s[74:75], 0, v[0:1]
	v_lshlrev_b32_e32 v3, 4, v3
	v_lshl_add_u64 v[0:1], v[0:1], 0, s[0:1]
	s_lshl_b32 s0, s4, 10
	v_or_b32_e32 v2, s5, v141
	v_and_b32_e32 v135, 0xf0, v3
	s_add_i32 s0, s0, 0
	v_lshl_or_b32 v2, v2, 13, v135
	v_mov_b32_e32 v3, v129
	s_mov_b32 m0, s0
	v_lshl_add_u64 v[138:139], s[24:25], 0, v[2:3]
	global_load_lds_dwordx4 v2, s[24:25]
	s_mov_b64 s[24:25], 0x40000
	s_add_i32 s5, s0, 0x2000
	v_lshl_add_u64 v[2:3], v[138:139], 0, s[24:25]
	s_mov_b32 m0, s5
	s_mov_b64 s[24:25], 0x80000
	global_load_lds_dwordx4 v[2:3], off
	v_lshl_add_u64 v[2:3], v[138:139], 0, s[24:25]
	s_add_i32 s24, s0, 0x4000
	s_mov_b32 m0, s24
	s_mov_b64 s[26:27], 0xc0000
	s_add_i32 s25, s0, 0x6000
	global_load_lds_dwordx4 v[2:3], off
	v_lshl_add_u64 v[2:3], v[138:139], 0, s[26:27]
	s_mov_b32 m0, s25
	s_mov_b64 s[26:27], 0x100000
	global_load_lds_dwordx4 v[2:3], off
	v_lshl_add_u64 v[2:3], v[138:139], 0, s[26:27]
	s_add_i32 s26, s0, 0x8000
	s_mov_b32 m0, s26
	s_mov_b64 s[28:29], 0x140000
	s_add_i32 s27, s0, 0xa000
	global_load_lds_dwordx4 v[2:3], off
	v_lshl_add_u64 v[2:3], v[138:139], 0, s[28:29]
	s_mov_b32 m0, s27
	s_mov_b64 s[28:29], 0x180000
	global_load_lds_dwordx4 v[2:3], off
	v_lshl_add_u64 v[2:3], v[138:139], 0, s[28:29]
	s_add_i32 s28, s0, 0xc000
	s_mov_b32 m0, s28
	s_mov_b64 s[30:31], 0x1c0000
	s_add_i32 s29, s0, 0xe000
	global_load_lds_dwordx4 v[2:3], off
	v_lshl_add_u64 v[2:3], v[138:139], 0, s[30:31]
	s_mov_b32 m0, s29
	v_lshl_add_u64 v[112:113], v[0:1], 0, v[132:133]
	global_load_lds_dwordx4 v[2:3], off
	s_waitcnt vmcnt(0)
	s_waitcnt vmcnt(0) lgkmcnt(0)
	s_barrier
	global_load_dwordx4 v[12:15], v[112:113], off
	global_load_dwordx4 v[8:11], v[112:113], off offset:64
	global_load_dwordx4 v[4:7], v[112:113], off offset:128
	global_load_dwordx4 v[0:3], v[112:113], off offset:192
	ds_read_b128 v[16:19], v168
	v_add_u32_e32 v114, 0, v144
	ds_read_b128 v[24:27], v114
	ds_read_b128 v[20:23], v169
	v_add_u32_e32 v115, 0, v156
	v_add_u32_e32 v116, 0, v145
	v_add_u32_e32 v117, 0, v157
	v_add_u32_e32 v118, 0, v146
	v_add_u32_e32 v119, 0, v158
	s_mov_b64 s[40:41], 0x100
	s_add_i32 s39, s0, 0x10000
	s_add_i32 s38, s0, 0x12000
	s_waitcnt vmcnt(3) lgkmcnt(2)
	v_mfma_f32_16x16x32_bf16 v[16:19], v[16:19], v[12:15], 0
	s_mov_b32 m0, s39
	s_add_i32 s37, s0, 0x14000
	s_add_i32 s36, s0, 0x16000
	s_waitcnt vmcnt(2) lgkmcnt(1)
	v_mfma_f32_16x16x32_bf16 v[16:19], v[24:27], v[8:11], v[16:19]
	ds_read_b128 v[24:27], v115
	s_add_i32 s35, s0, 0x18000
	s_add_i32 s34, s0, 0x1a000
	s_waitcnt lgkmcnt(1)
	v_mfma_f32_16x16x32_bf16 v[20:23], v[20:23], v[12:15], 0
	s_add_i32 s31, s0, 0x1c000
	s_add_i32 s30, s0, 0x1e000
	v_add_u32_e32 v171, s16, v143
	s_waitcnt lgkmcnt(0)
	v_mfma_f32_16x16x32_bf16 v[20:23], v[24:27], v[8:11], v[20:23]
	ds_read_b128 v[24:27], v116
	v_add_u32_e32 v172, s16, v155
	v_add_u32_e32 v173, s16, v144
	s_waitcnt vmcnt(1) lgkmcnt(0)
	v_mfma_f32_16x16x32_bf16 v[16:19], v[24:27], v[4:7], v[16:19]
	ds_read_b128 v[24:27], v117
	v_add_u32_e32 v174, s16, v156
	v_add_u32_e32 v175, s16, v145
	s_waitcnt lgkmcnt(0)
	v_mfma_f32_16x16x32_bf16 v[20:23], v[24:27], v[4:7], v[20:23]
	ds_read_b128 v[24:27], v118
	v_add_u32_e32 v176, s16, v157
	v_add_u32_e32 v177, s16, v146
	s_waitcnt vmcnt(0) lgkmcnt(0)
	v_mfma_f32_16x16x32_bf16 v[24:27], v[24:27], v[0:3], v[16:19]
	s_nop 2
	ds_read_b128 v[16:19], v119
	v_add_u32_e32 v178, s16, v158
	s_waitcnt lgkmcnt(0)
	v_mfma_f32_16x16x32_bf16 v[28:31], v[16:19], v[0:3], v[20:23]
	v_lshl_add_u64 v[16:17], v[138:139], 0, s[40:41]
	s_mov_b64 s[40:41], 0x1c0100
	v_lshl_add_u64 v[18:19], v[138:139], 0, s[40:41]
	s_mov_b64 s[40:41], 0x180100
	v_lshl_add_u64 v[20:21], v[138:139], 0, s[40:41]
	s_mov_b64 s[40:41], 0x140100
	v_lshl_add_u64 v[22:23], v[138:139], 0, s[40:41]
	s_mov_b64 s[40:41], 0x100100
	v_lshl_add_u64 v[32:33], v[138:139], 0, s[40:41]
	s_mov_b64 s[40:41], 0xc0100
	v_lshl_add_u64 v[34:35], v[138:139], 0, s[40:41]
	s_mov_b64 s[40:41], 0x80100
	v_lshl_add_u64 v[36:37], v[138:139], 0, s[40:41]
	s_mov_b64 s[40:41], 0x40100
	v_lshl_add_u64 v[38:39], v[138:139], 0, s[40:41]
	global_load_lds_dwordx4 v[16:17], off
	s_mov_b32 m0, s38
	s_mov_b64 s[40:41], 0x200
	global_load_lds_dwordx4 v[38:39], off
	s_mov_b32 m0, s37
	s_nop 0
	global_load_lds_dwordx4 v[36:37], off
	s_mov_b32 m0, s36
	s_nop 0
	global_load_lds_dwordx4 v[34:35], off
	s_mov_b32 m0, s35
	s_nop 0
	global_load_lds_dwordx4 v[32:33], off
	s_mov_b32 m0, s34
	s_nop 0
	global_load_lds_dwordx4 v[22:23], off
	s_mov_b32 m0, s31
	s_nop 0
	global_load_lds_dwordx4 v[20:21], off
	s_mov_b32 m0, s30
	s_nop 0
	global_load_lds_dwordx4 v[18:19], off
	ds_read_b128 v[16:19], v168 offset:8192
	ds_read_b128 v[32:35], v114 offset:8192
	s_waitcnt lgkmcnt(0)
	v_mfma_f32_16x16x32_bf16 v[16:19], v[16:19], v[12:15], 0
	ds_read_b128 v[20:23], v169 offset:8192
	s_mov_b32 m0, s0
	v_mfma_f32_16x16x32_bf16 v[16:19], v[32:35], v[8:11], v[16:19]
	ds_read_b128 v[32:35], v115 offset:8192
	s_waitcnt lgkmcnt(0)
	v_mfma_f32_16x16x32_bf16 v[20:23], v[20:23], v[12:15], 0
	v_mfma_f32_16x16x32_bf16 v[20:23], v[32:35], v[8:11], v[20:23]
	ds_read_b128 v[32:35], v116 offset:8192
	s_waitcnt lgkmcnt(0)
	v_mfma_f32_16x16x32_bf16 v[16:19], v[32:35], v[4:7], v[16:19]
	ds_read_b128 v[32:35], v117 offset:8192
	s_waitcnt lgkmcnt(0)
	v_mfma_f32_16x16x32_bf16 v[20:23], v[32:35], v[4:7], v[20:23]
	ds_read_b128 v[32:35], v118 offset:8192
	s_waitcnt lgkmcnt(0)
	v_mfma_f32_16x16x32_bf16 v[72:75], v[32:35], v[0:3], v[16:19]
	s_nop 2
	ds_read_b128 v[16:19], v119 offset:8192
	s_waitcnt lgkmcnt(0)
	v_mfma_f32_16x16x32_bf16 v[76:79], v[16:19], v[0:3], v[20:23]
	ds_read_b128 v[16:19], v119 offset:16384
	s_nop 1
	ds_read_b128 v[20:23], v118 offset:16384
	ds_read_b128 v[32:35], v117 offset:16384
	ds_read_b128 v[36:39], v116 offset:16384
	ds_read_b128 v[40:43], v115 offset:16384
	ds_read_b128 v[44:47], v114 offset:16384
	ds_read_b128 v[48:51], v169 offset:16384
	ds_read_b128 v[52:55], v168 offset:16384
	s_waitcnt lgkmcnt(0)
	v_mfma_f32_16x16x32_bf16 v[52:55], v[52:55], v[12:15], 0
	v_mfma_f32_16x16x32_bf16 v[48:51], v[48:51], v[12:15], 0
	v_mfma_f32_16x16x32_bf16 v[44:47], v[44:47], v[8:11], v[52:55]
	v_mfma_f32_16x16x32_bf16 v[40:43], v[40:43], v[8:11], v[48:51]
	v_mfma_f32_16x16x32_bf16 v[36:39], v[36:39], v[4:7], v[44:47]
	v_mfma_f32_16x16x32_bf16 v[32:35], v[32:35], v[4:7], v[40:43]
	v_mfma_f32_16x16x32_bf16 v[68:71], v[20:23], v[0:3], v[36:39]
	v_mfma_f32_16x16x32_bf16 v[64:67], v[16:19], v[0:3], v[32:35]
	ds_read_b128 v[16:19], v119 offset:24576
	ds_read_b128 v[20:23], v118 offset:24576
	s_nop 3
	ds_read_b128 v[32:35], v117 offset:24576
	ds_read_b128 v[36:39], v116 offset:24576
	ds_read_b128 v[40:43], v115 offset:24576
	ds_read_b128 v[44:47], v114 offset:24576
	ds_read_b128 v[48:51], v169 offset:24576
	ds_read_b128 v[52:55], v168 offset:24576
	s_waitcnt lgkmcnt(0)
	v_mfma_f32_16x16x32_bf16 v[52:55], v[52:55], v[12:15], 0
	v_mfma_f32_16x16x32_bf16 v[48:51], v[48:51], v[12:15], 0
	v_mfma_f32_16x16x32_bf16 v[44:47], v[44:47], v[8:11], v[52:55]
	v_mfma_f32_16x16x32_bf16 v[40:43], v[40:43], v[8:11], v[48:51]
	v_mfma_f32_16x16x32_bf16 v[36:39], v[36:39], v[4:7], v[44:47]
	v_mfma_f32_16x16x32_bf16 v[32:35], v[32:35], v[4:7], v[40:43]
	v_mfma_f32_16x16x32_bf16 v[60:63], v[20:23], v[0:3], v[36:39]
	v_mfma_f32_16x16x32_bf16 v[56:59], v[16:19], v[0:3], v[32:35]
	ds_read_b128 v[16:19], v119 offset:32768
	ds_read_b128 v[20:23], v118 offset:32768
	s_nop 3
	ds_read_b128 v[32:35], v117 offset:32768
	ds_read_b128 v[36:39], v116 offset:32768
	ds_read_b128 v[40:43], v115 offset:32768
	ds_read_b128 v[44:47], v114 offset:32768
	ds_read_b128 v[48:51], v169 offset:32768
	ds_read_b128 v[52:55], v168 offset:32768
	s_waitcnt lgkmcnt(0)
	v_mfma_f32_16x16x32_bf16 v[52:55], v[52:55], v[12:15], 0
	v_mfma_f32_16x16x32_bf16 v[48:51], v[48:51], v[12:15], 0
	v_mfma_f32_16x16x32_bf16 v[44:47], v[44:47], v[8:11], v[52:55]
	v_mfma_f32_16x16x32_bf16 v[40:43], v[40:43], v[8:11], v[48:51]
	v_mfma_f32_16x16x32_bf16 v[36:39], v[36:39], v[4:7], v[44:47]
	v_mfma_f32_16x16x32_bf16 v[32:35], v[32:35], v[4:7], v[40:43]
	v_mfma_f32_16x16x32_bf16 v[52:55], v[20:23], v[0:3], v[36:39]
	v_mfma_f32_16x16x32_bf16 v[48:51], v[16:19], v[0:3], v[32:35]
	ds_read_b128 v[16:19], v119 offset:40960
	ds_read_b128 v[20:23], v118 offset:40960
	s_nop 3
	ds_read_b128 v[32:35], v117 offset:40960
	ds_read_b128 v[36:39], v116 offset:40960
	ds_read_b128 v[40:43], v115 offset:40960
	ds_read_b128 v[44:47], v114 offset:40960
	ds_read_b128 v[80:83], v169 offset:40960
	ds_read_b128 v[84:87], v168 offset:40960
	s_waitcnt lgkmcnt(0)
	v_mfma_f32_16x16x32_bf16 v[84:87], v[84:87], v[12:15], 0
	v_mfma_f32_16x16x32_bf16 v[80:83], v[80:83], v[12:15], 0
	v_mfma_f32_16x16x32_bf16 v[44:47], v[44:47], v[8:11], v[84:87]
	v_mfma_f32_16x16x32_bf16 v[40:43], v[40:43], v[8:11], v[80:83]
	v_mfma_f32_16x16x32_bf16 v[36:39], v[36:39], v[4:7], v[44:47]
	v_mfma_f32_16x16x32_bf16 v[32:35], v[32:35], v[4:7], v[40:43]
	v_mfma_f32_16x16x32_bf16 v[44:47], v[20:23], v[0:3], v[36:39]
	v_mfma_f32_16x16x32_bf16 v[40:43], v[16:19], v[0:3], v[32:35]
	ds_read_b128 v[16:19], v119 offset:49152
	ds_read_b128 v[20:23], v118 offset:49152
	s_nop 3
	ds_read_b128 v[32:35], v117 offset:49152
	ds_read_b128 v[36:39], v116 offset:49152
	ds_read_b128 v[80:83], v115 offset:49152
	ds_read_b128 v[84:87], v114 offset:49152
	ds_read_b128 v[88:91], v169 offset:49152
	ds_read_b128 v[92:95], v168 offset:49152
	s_waitcnt lgkmcnt(0)
	v_mfma_f32_16x16x32_bf16 v[92:95], v[92:95], v[12:15], 0
	v_mfma_f32_16x16x32_bf16 v[88:91], v[88:91], v[12:15], 0
	v_mfma_f32_16x16x32_bf16 v[84:87], v[84:87], v[8:11], v[92:95]
	v_mfma_f32_16x16x32_bf16 v[80:83], v[80:83], v[8:11], v[88:91]
	v_mfma_f32_16x16x32_bf16 v[36:39], v[36:39], v[4:7], v[84:87]
	v_mfma_f32_16x16x32_bf16 v[32:35], v[32:35], v[4:7], v[80:83]
	v_mfma_f32_16x16x32_bf16 v[36:39], v[20:23], v[0:3], v[36:39]
	v_mfma_f32_16x16x32_bf16 v[32:35], v[16:19], v[0:3], v[32:35]
	ds_read_b128 v[16:19], v119 offset:57344
	ds_read_b128 v[20:23], v118 offset:57344
	s_nop 1
	ds_read_b128 v[80:83], v117 offset:57344
	ds_read_b128 v[84:87], v116 offset:57344
	ds_read_b128 v[88:91], v115 offset:57344
	ds_read_b128 v[92:95], v114 offset:57344
	ds_read_b128 v[96:99], v169 offset:57344
	ds_read_b128 v[100:103], v168 offset:57344
	s_waitcnt lgkmcnt(0)
	v_mfma_f32_16x16x32_bf16 v[100:103], v[100:103], v[12:15], 0
	v_mfma_f32_16x16x32_bf16 v[12:15], v[96:99], v[12:15], 0
	v_mfma_f32_16x16x32_bf16 v[92:95], v[92:95], v[8:11], v[100:103]
	v_mfma_f32_16x16x32_bf16 v[8:11], v[88:91], v[8:11], v[12:15]
	v_mfma_f32_16x16x32_bf16 v[12:15], v[84:87], v[4:7], v[92:95]
	v_mfma_f32_16x16x32_bf16 v[4:7], v[80:83], v[4:7], v[8:11]
	v_mfma_f32_16x16x32_bf16 v[12:15], v[20:23], v[0:3], v[12:15]
	v_mfma_f32_16x16x32_bf16 v[8:11], v[16:19], v[0:3], v[4:7]
	s_waitcnt vmcnt(0)
	s_waitcnt vmcnt(0)
	s_barrier
	global_load_dwordx4 v[20:23], v[112:113], off offset:256
	global_load_dwordx4 v[16:19], v[112:113], off offset:320
	s_nop 1
	global_load_dwordx4 v[4:7], v[112:113], off offset:384
	global_load_dwordx4 v[0:3], v[112:113], off offset:448
	ds_read_b128 v[80:83], v171
	s_waitcnt vmcnt(3) lgkmcnt(0)
	v_mfma_f32_16x16x32_bf16 v[24:27], v[80:83], v[20:23], v[24:27]
	ds_read_b128 v[80:83], v172
	s_waitcnt lgkmcnt(0)
	v_mfma_f32_16x16x32_bf16 v[28:31], v[80:83], v[20:23], v[28:31]
	ds_read_b128 v[80:83], v173
	s_waitcnt vmcnt(2) lgkmcnt(0)
	v_mfma_f32_16x16x32_bf16 v[24:27], v[80:83], v[16:19], v[24:27]
	ds_read_b128 v[80:83], v174
	s_waitcnt lgkmcnt(0)
	v_mfma_f32_16x16x32_bf16 v[28:31], v[80:83], v[16:19], v[28:31]
	ds_read_b128 v[80:83], v175
	s_waitcnt vmcnt(1) lgkmcnt(0)
	v_mfma_f32_16x16x32_bf16 v[24:27], v[80:83], v[4:7], v[24:27]
	ds_read_b128 v[80:83], v176
	s_waitcnt lgkmcnt(0)
	v_mfma_f32_16x16x32_bf16 v[28:31], v[80:83], v[4:7], v[28:31]
	ds_read_b128 v[80:83], v177
	s_waitcnt vmcnt(0) lgkmcnt(0)
	v_mfma_f32_16x16x32_bf16 v[24:27], v[80:83], v[0:3], v[24:27]
	ds_read_b128 v[80:83], v178
	s_waitcnt lgkmcnt(0)
	v_mfma_f32_16x16x32_bf16 v[28:31], v[80:83], v[0:3], v[28:31]
	v_lshl_add_u64 v[80:81], v[138:139], 0, s[40:41]
	s_mov_b64 s[40:41], 0x1c0200
	v_lshl_add_u64 v[82:83], v[138:139], 0, s[40:41]
	s_mov_b64 s[40:41], 0x180200
	v_lshl_add_u64 v[84:85], v[138:139], 0, s[40:41]
	s_mov_b64 s[40:41], 0x140200
	v_lshl_add_u64 v[86:87], v[138:139], 0, s[40:41]
	s_mov_b64 s[40:41], 0x100200
	v_lshl_add_u64 v[88:89], v[138:139], 0, s[40:41]
	s_mov_b64 s[40:41], 0xc0200
	v_lshl_add_u64 v[90:91], v[138:139], 0, s[40:41]
	s_mov_b64 s[40:41], 0x80200
	v_lshl_add_u64 v[92:93], v[138:139], 0, s[40:41]
	s_mov_b64 s[40:41], 0x40200
	v_lshl_add_u64 v[94:95], v[138:139], 0, s[40:41]
	global_load_lds_dwordx4 v[80:81], off
	s_mov_b32 m0, s5
	s_add_i32 s40, 0, 0x12000
	global_load_lds_dwordx4 v[94:95], off
	s_mov_b32 m0, s24
	v_add_u32_e32 v179, s40, v143
	global_load_lds_dwordx4 v[92:93], off
	s_mov_b32 m0, s25
	v_add_u32_e32 v180, s40, v155
	global_load_lds_dwordx4 v[90:91], off
	s_mov_b32 m0, s26
	v_add_u32_e32 v181, s40, v144
	global_load_lds_dwordx4 v[88:89], off
	s_mov_b32 m0, s27
	v_add_u32_e32 v182, s40, v156
	global_load_lds_dwordx4 v[86:87], off
	s_mov_b32 m0, s28
	v_add_u32_e32 v183, s40, v145
	global_load_lds_dwordx4 v[84:85], off
	s_mov_b32 m0, s29
	v_add_u32_e32 v184, s40, v157
	global_load_lds_dwordx4 v[82:83], off
	ds_read_b128 v[80:83], v179
	s_waitcnt lgkmcnt(0)
	v_mfma_f32_16x16x32_bf16 v[72:75], v[80:83], v[20:23], v[72:75]
	ds_read_b128 v[80:83], v180
	v_add_u32_e32 v185, s40, v146
	v_add_u32_e32 v186, s40, v158
	s_waitcnt lgkmcnt(0)
	v_mfma_f32_16x16x32_bf16 v[76:79], v[80:83], v[20:23], v[76:79]
	ds_read_b128 v[80:83], v181
	s_add_i32 s40, 0, 0x14000
	v_add_u32_e32 v195, s40, v155
	s_waitcnt lgkmcnt(0)
	v_mfma_f32_16x16x32_bf16 v[72:75], v[80:83], v[16:19], v[72:75]
	ds_read_b128 v[80:83], v182
	v_add_u32_e32 v196, s40, v143
	v_add_u32_e32 v193, s40, v156
	s_waitcnt lgkmcnt(0)
	v_mfma_f32_16x16x32_bf16 v[76:79], v[80:83], v[16:19], v[76:79]
	ds_read_b128 v[80:83], v183
	v_add_u32_e32 v194, s40, v144
	v_add_u32_e32 v189, s40, v157
	s_waitcnt lgkmcnt(0)
	v_mfma_f32_16x16x32_bf16 v[72:75], v[80:83], v[4:7], v[72:75]
	ds_read_b128 v[80:83], v184
	v_add_u32_e32 v192, s40, v145
	v_add_u32_e32 v187, s40, v158
	s_waitcnt lgkmcnt(0)
	v_mfma_f32_16x16x32_bf16 v[76:79], v[80:83], v[4:7], v[76:79]
	ds_read_b128 v[80:83], v185
	v_add_u32_e32 v188, s40, v146
	s_add_i32 s40, 0, 0x16000
	s_waitcnt lgkmcnt(0)
	v_mfma_f32_16x16x32_bf16 v[72:75], v[80:83], v[0:3], v[72:75]
	ds_read_b128 v[80:83], v186
	v_add_u32_e32 v203, s40, v155
	v_add_u32_e32 v204, s40, v143
	s_waitcnt lgkmcnt(0)
	v_mfma_f32_16x16x32_bf16 v[76:79], v[80:83], v[0:3], v[76:79]
	ds_read_b128 v[104:107], v195
	ds_read_b128 v[108:111], v196
	ds_read_b128 v[96:99], v193
	ds_read_b128 v[100:103], v194
	ds_read_b128 v[88:91], v189
	ds_read_b128 v[92:95], v192
	s_waitcnt lgkmcnt(0)
	v_mfma_f32_16x16x32_bf16 v[68:71], v[108:111], v[20:23], v[68:71]
	ds_read_b128 v[80:83], v187
	ds_read_b128 v[84:87], v188
	v_add_u32_e32 v201, s40, v156
	v_mfma_f32_16x16x32_bf16 v[64:67], v[104:107], v[20:23], v[64:67]
	v_add_u32_e32 v202, s40, v144
	v_add_u32_e32 v199, s40, v157
	v_add_u32_e32 v200, s40, v145
	v_mfma_f32_16x16x32_bf16 v[68:71], v[100:103], v[16:19], v[68:71]
	v_add_u32_e32 v197, s40, v158
	v_add_u32_e32 v198, s40, v146
	s_add_i32 s40, 0, 0x18000
	v_mfma_f32_16x16x32_bf16 v[64:67], v[96:99], v[16:19], v[64:67]
	v_add_u32_e32 v211, s40, v155
	v_add_u32_e32 v212, s40, v143
	v_add_u32_e32 v209, s40, v156
	v_mfma_f32_16x16x32_bf16 v[68:71], v[92:95], v[4:7], v[68:71]
	v_add_u32_e32 v210, s40, v144
	v_add_u32_e32 v207, s40, v157
	v_add_u32_e32 v208, s40, v145
	v_mfma_f32_16x16x32_bf16 v[64:67], v[88:91], v[4:7], v[64:67]
	v_add_u32_e32 v205, s40, v158
	v_add_u32_e32 v206, s40, v146
	s_add_i32 s40, 0, 0x1a000
	s_waitcnt lgkmcnt(0)
	v_mfma_f32_16x16x32_bf16 v[68:71], v[84:87], v[0:3], v[68:71]
	v_add_u32_e32 v219, s40, v155
	v_add_u32_e32 v220, s40, v143
	v_add_u32_e32 v217, s40, v156
	v_mfma_f32_16x16x32_bf16 v[64:67], v[80:83], v[0:3], v[64:67]
	ds_read_b128 v[104:107], v203
	ds_read_b128 v[108:111], v204
	ds_read_b128 v[96:99], v201
	ds_read_b128 v[100:103], v202
	ds_read_b128 v[88:91], v199
	ds_read_b128 v[92:95], v200
	s_waitcnt lgkmcnt(0)
	v_mfma_f32_16x16x32_bf16 v[60:63], v[108:111], v[20:23], v[60:63]
	ds_read_b128 v[80:83], v197
	ds_read_b128 v[84:87], v198
	v_add_u32_e32 v218, s40, v144
	v_mfma_f32_16x16x32_bf16 v[56:59], v[104:107], v[20:23], v[56:59]
	v_add_u32_e32 v215, s40, v157
	v_add_u32_e32 v216, s40, v145
	v_add_u32_e32 v213, s40, v158
	v_mfma_f32_16x16x32_bf16 v[60:63], v[100:103], v[16:19], v[60:63]
	v_add_u32_e32 v214, s40, v146
	s_add_i32 s40, 0, 0x1c000
	v_add_u32_e32 v227, s40, v155
	v_mfma_f32_16x16x32_bf16 v[56:59], v[96:99], v[16:19], v[56:59]
	v_add_u32_e32 v228, s40, v143
	v_add_u32_e32 v225, s40, v156
	v_add_u32_e32 v226, s40, v144
	v_mfma_f32_16x16x32_bf16 v[60:63], v[92:95], v[4:7], v[60:63]
	v_add_u32_e32 v223, s40, v157
	v_add_u32_e32 v224, s40, v145
	v_add_u32_e32 v221, s40, v158
	v_mfma_f32_16x16x32_bf16 v[56:59], v[88:91], v[4:7], v[56:59]
	v_add_u32_e32 v222, s40, v146
	s_add_i32 s40, 0, 0x1e000
	v_add_u32_e32 v235, s40, v155
	s_waitcnt lgkmcnt(0)
	v_mfma_f32_16x16x32_bf16 v[60:63], v[84:87], v[0:3], v[60:63]
	v_add_u32_e32 v236, s40, v143
	v_add_u32_e32 v233, s40, v156
	v_add_u32_e32 v234, s40, v144
	v_mfma_f32_16x16x32_bf16 v[56:59], v[80:83], v[0:3], v[56:59]
	ds_read_b128 v[104:107], v211
	ds_read_b128 v[108:111], v212
	ds_read_b128 v[96:99], v209
	ds_read_b128 v[100:103], v210
	ds_read_b128 v[88:91], v207
	ds_read_b128 v[92:95], v208
	s_waitcnt lgkmcnt(0)
	v_mfma_f32_16x16x32_bf16 v[52:55], v[108:111], v[20:23], v[52:55]
	ds_read_b128 v[80:83], v205
	ds_read_b128 v[84:87], v206
	v_add_u32_e32 v231, s40, v157
	v_mfma_f32_16x16x32_bf16 v[48:51], v[104:107], v[20:23], v[48:51]
	v_add_u32_e32 v232, s40, v145
	v_add_u32_e32 v229, s40, v158
	v_add_u32_e32 v230, s40, v146
	v_mfma_f32_16x16x32_bf16 v[52:55], v[100:103], v[16:19], v[52:55]
	s_mov_b64 s[40:41], 0x300
	s_mov_b32 m0, s39
	v_mfma_f32_16x16x32_bf16 v[48:51], v[96:99], v[16:19], v[48:51]
	v_mfma_f32_16x16x32_bf16 v[52:55], v[92:95], v[4:7], v[52:55]
	v_mfma_f32_16x16x32_bf16 v[48:51], v[88:91], v[4:7], v[48:51]
	s_waitcnt lgkmcnt(0)
	v_mfma_f32_16x16x32_bf16 v[52:55], v[84:87], v[0:3], v[52:55]
	v_mfma_f32_16x16x32_bf16 v[48:51], v[80:83], v[0:3], v[48:51]
	ds_read_b128 v[104:107], v219
	ds_read_b128 v[108:111], v220
	ds_read_b128 v[96:99], v217
	ds_read_b128 v[100:103], v218
	ds_read_b128 v[88:91], v215
	ds_read_b128 v[92:95], v216
	s_waitcnt lgkmcnt(0)
	v_mfma_f32_16x16x32_bf16 v[44:47], v[108:111], v[20:23], v[44:47]
	ds_read_b128 v[80:83], v213
	ds_read_b128 v[84:87], v214
	v_mfma_f32_16x16x32_bf16 v[40:43], v[104:107], v[20:23], v[40:43]
	v_mfma_f32_16x16x32_bf16 v[44:47], v[100:103], v[16:19], v[44:47]
	v_mfma_f32_16x16x32_bf16 v[40:43], v[96:99], v[16:19], v[40:43]
	v_mfma_f32_16x16x32_bf16 v[44:47], v[92:95], v[4:7], v[44:47]
	v_mfma_f32_16x16x32_bf16 v[40:43], v[88:91], v[4:7], v[40:43]
	s_waitcnt lgkmcnt(0)
	v_mfma_f32_16x16x32_bf16 v[44:47], v[84:87], v[0:3], v[44:47]
	v_mfma_f32_16x16x32_bf16 v[40:43], v[80:83], v[0:3], v[40:43]
	ds_read_b128 v[104:107], v227
	ds_read_b128 v[108:111], v228
	ds_read_b128 v[96:99], v225
	ds_read_b128 v[100:103], v226
	ds_read_b128 v[88:91], v223
	ds_read_b128 v[92:95], v224
	s_waitcnt lgkmcnt(0)
	v_mfma_f32_16x16x32_bf16 v[36:39], v[108:111], v[20:23], v[36:39]
	ds_read_b128 v[80:83], v221
	ds_read_b128 v[84:87], v222
	v_mfma_f32_16x16x32_bf16 v[32:35], v[104:107], v[20:23], v[32:35]
	v_mfma_f32_16x16x32_bf16 v[36:39], v[100:103], v[16:19], v[36:39]
	v_mfma_f32_16x16x32_bf16 v[32:35], v[96:99], v[16:19], v[32:35]
	v_mfma_f32_16x16x32_bf16 v[36:39], v[92:95], v[4:7], v[36:39]
	v_mfma_f32_16x16x32_bf16 v[32:35], v[88:91], v[4:7], v[32:35]
	s_waitcnt lgkmcnt(0)
	v_mfma_f32_16x16x32_bf16 v[36:39], v[84:87], v[0:3], v[36:39]
	v_mfma_f32_16x16x32_bf16 v[32:35], v[80:83], v[0:3], v[32:35]
	ds_read_b128 v[104:107], v235
	ds_read_b128 v[108:111], v236
	ds_read_b128 v[96:99], v233
	ds_read_b128 v[100:103], v234
	ds_read_b128 v[88:91], v231
	ds_read_b128 v[92:95], v232
	s_waitcnt lgkmcnt(0)
	v_mfma_f32_16x16x32_bf16 v[12:15], v[108:111], v[20:23], v[12:15]
	ds_read_b128 v[80:83], v229
	ds_read_b128 v[84:87], v230
	v_mfma_f32_16x16x32_bf16 v[8:11], v[104:107], v[20:23], v[8:11]
	v_mfma_f32_16x16x32_bf16 v[12:15], v[100:103], v[16:19], v[12:15]
	v_mfma_f32_16x16x32_bf16 v[8:11], v[96:99], v[16:19], v[8:11]
	v_mfma_f32_16x16x32_bf16 v[12:15], v[92:95], v[4:7], v[12:15]
	v_mfma_f32_16x16x32_bf16 v[4:7], v[88:91], v[4:7], v[8:11]
	s_waitcnt lgkmcnt(0)
	v_mfma_f32_16x16x32_bf16 v[12:15], v[84:87], v[0:3], v[12:15]
	v_mfma_f32_16x16x32_bf16 v[16:19], v[80:83], v[0:3], v[4:7]
	s_waitcnt vmcnt(0)
	s_waitcnt vmcnt(0)
	s_barrier
	global_load_dwordx4 v[84:87], v[112:113], off offset:512
	global_load_dwordx4 v[80:83], v[112:113], off offset:576
	global_load_dwordx4 v[20:23], v[112:113], off offset:640
	global_load_dwordx4 v[8:11], v[112:113], off offset:704
	ds_read_b128 v[0:3], v168
	s_waitcnt vmcnt(3) lgkmcnt(0)
	v_mfma_f32_16x16x32_bf16 v[0:3], v[0:3], v[84:87], v[24:27]
	ds_read_b128 v[4:7], v169
	s_nop 1
	ds_read_b128 v[24:27], v114
	s_waitcnt vmcnt(2) lgkmcnt(0)
	v_mfma_f32_16x16x32_bf16 v[0:3], v[24:27], v[80:83], v[0:3]
	ds_read_b128 v[24:27], v115
	v_mfma_f32_16x16x32_bf16 v[4:7], v[4:7], v[84:87], v[28:31]
	s_waitcnt lgkmcnt(0)
	v_mfma_f32_16x16x32_bf16 v[4:7], v[24:27], v[80:83], v[4:7]
	ds_read_b128 v[24:27], v116
	s_waitcnt vmcnt(1) lgkmcnt(0)
	v_mfma_f32_16x16x32_bf16 v[0:3], v[24:27], v[20:23], v[0:3]
	ds_read_b128 v[24:27], v117
	s_waitcnt lgkmcnt(0)
	v_mfma_f32_16x16x32_bf16 v[4:7], v[24:27], v[20:23], v[4:7]
	ds_read_b128 v[24:27], v118
	s_waitcnt vmcnt(0) lgkmcnt(0)
	v_mfma_f32_16x16x32_bf16 v[0:3], v[24:27], v[8:11], v[0:3]
	ds_read_b128 v[24:27], v119
	s_waitcnt lgkmcnt(0)
	v_mfma_f32_16x16x32_bf16 v[4:7], v[24:27], v[8:11], v[4:7]
	v_lshl_add_u64 v[24:25], v[138:139], 0, s[40:41]
	s_mov_b64 s[40:41], 0x1c0300
	v_lshl_add_u64 v[26:27], v[138:139], 0, s[40:41]
	s_mov_b64 s[40:41], 0x180300
	v_lshl_add_u64 v[28:29], v[138:139], 0, s[40:41]
	s_mov_b64 s[40:41], 0x140300
	v_lshl_add_u64 v[30:31], v[138:139], 0, s[40:41]
	s_mov_b64 s[40:41], 0x100300
	v_lshl_add_u64 v[88:89], v[138:139], 0, s[40:41]
	s_mov_b64 s[40:41], 0xc0300
	v_lshl_add_u64 v[90:91], v[138:139], 0, s[40:41]
	s_mov_b64 s[40:41], 0x80300
	v_lshl_add_u64 v[92:93], v[138:139], 0, s[40:41]
	s_mov_b64 s[40:41], 0x40300
	v_lshl_add_u64 v[94:95], v[138:139], 0, s[40:41]
	global_load_lds_dwordx4 v[24:25], off
	s_mov_b32 m0, s38
	s_nop 0
	global_load_lds_dwordx4 v[94:95], off
	s_mov_b32 m0, s37
	s_nop 0
	global_load_lds_dwordx4 v[92:93], off
	s_mov_b32 m0, s36
	s_nop 0
	global_load_lds_dwordx4 v[90:91], off
	s_mov_b32 m0, s35
	s_nop 0
	global_load_lds_dwordx4 v[88:89], off
	s_mov_b32 m0, s34
	s_nop 0
	global_load_lds_dwordx4 v[30:31], off
	s_mov_b32 m0, s31
	s_nop 0
	global_load_lds_dwordx4 v[28:29], off
	s_mov_b32 m0, s30
	s_mov_b64 s[30:31], 0x1000
	global_load_lds_dwordx4 v[26:27], off
	ds_read_b128 v[24:27], v168 offset:8192
	s_waitcnt lgkmcnt(0)
	v_mfma_f32_16x16x32_bf16 v[24:27], v[24:27], v[84:87], v[72:75]
	ds_read_b128 v[28:31], v169 offset:8192
	s_nop 1
	ds_read_b128 v[72:75], v114 offset:8192
	s_mov_b32 m0, s0
	s_waitcnt lgkmcnt(0)
	v_mfma_f32_16x16x32_bf16 v[24:27], v[72:75], v[80:83], v[24:27]
	ds_read_b128 v[72:75], v115 offset:8192
	v_mfma_f32_16x16x32_bf16 v[28:31], v[28:31], v[84:87], v[76:79]
	s_waitcnt lgkmcnt(0)
	v_mfma_f32_16x16x32_bf16 v[28:31], v[72:75], v[80:83], v[28:31]
	ds_read_b128 v[72:75], v116 offset:8192
	s_waitcnt lgkmcnt(0)
	v_mfma_f32_16x16x32_bf16 v[24:27], v[72:75], v[20:23], v[24:27]
	ds_read_b128 v[72:75], v117 offset:8192
	s_waitcnt lgkmcnt(0)
	v_mfma_f32_16x16x32_bf16 v[28:31], v[72:75], v[20:23], v[28:31]
	ds_read_b128 v[72:75], v118 offset:8192
	s_waitcnt lgkmcnt(0)
	v_mfma_f32_16x16x32_bf16 v[96:99], v[72:75], v[8:11], v[24:27]
	s_nop 2
	ds_read_b128 v[24:27], v119 offset:8192
	s_waitcnt lgkmcnt(0)
	v_mfma_f32_16x16x32_bf16 v[100:103], v[24:27], v[8:11], v[28:31]
	s_nop 2
	ds_read_b128 v[28:31], v119 offset:16384
	ds_read_b128 v[24:27], v118 offset:16384
	ds_read_b128 v[72:75], v117 offset:16384
	ds_read_b128 v[76:79], v116 offset:16384
	ds_read_b128 v[88:91], v115 offset:16384
	ds_read_b128 v[92:95], v114 offset:16384
	ds_read_b128 v[104:107], v169 offset:16384
	ds_read_b128 v[108:111], v168 offset:16384
	s_waitcnt lgkmcnt(0)
	v_mfma_f32_16x16x32_bf16 v[68:71], v[108:111], v[84:87], v[68:71]
	v_mfma_f32_16x16x32_bf16 v[64:67], v[104:107], v[84:87], v[64:67]
	v_mfma_f32_16x16x32_bf16 v[68:71], v[92:95], v[80:83], v[68:71]
	v_mfma_f32_16x16x32_bf16 v[64:67], v[88:91], v[80:83], v[64:67]
	v_mfma_f32_16x16x32_bf16 v[68:71], v[76:79], v[20:23], v[68:71]
	v_mfma_f32_16x16x32_bf16 v[64:67], v[72:75], v[20:23], v[64:67]
	v_mfma_f32_16x16x32_bf16 v[24:27], v[24:27], v[8:11], v[68:71]
	v_mfma_f32_16x16x32_bf16 v[28:31], v[28:31], v[8:11], v[64:67]
	s_nop 4
	ds_read_b128 v[68:71], v119 offset:24576
	ds_read_b128 v[64:67], v118 offset:24576
	ds_read_b128 v[72:75], v117 offset:24576
	ds_read_b128 v[76:79], v116 offset:24576
	ds_read_b128 v[88:91], v115 offset:24576
	ds_read_b128 v[92:95], v114 offset:24576
	ds_read_b128 v[104:107], v169 offset:24576
	ds_read_b128 v[108:111], v168 offset:24576
	s_waitcnt lgkmcnt(0)
	v_mfma_f32_16x16x32_bf16 v[60:63], v[108:111], v[84:87], v[60:63]
	v_mfma_f32_16x16x32_bf16 v[56:59], v[104:107], v[84:87], v[56:59]
	v_mfma_f32_16x16x32_bf16 v[60:63], v[92:95], v[80:83], v[60:63]
	v_mfma_f32_16x16x32_bf16 v[56:59], v[88:91], v[80:83], v[56:59]
	v_mfma_f32_16x16x32_bf16 v[60:63], v[76:79], v[20:23], v[60:63]
	v_mfma_f32_16x16x32_bf16 v[56:59], v[72:75], v[20:23], v[56:59]
	v_mfma_f32_16x16x32_bf16 v[64:67], v[64:67], v[8:11], v[60:63]
	v_mfma_f32_16x16x32_bf16 v[68:71], v[68:71], v[8:11], v[56:59]
	s_nop 5
	ds_read_b128 v[56:59], v119 offset:32768
	ds_read_b128 v[60:63], v118 offset:32768
	ds_read_b128 v[72:75], v117 offset:32768
	ds_read_b128 v[76:79], v116 offset:32768
	ds_read_b128 v[88:91], v115 offset:32768
	ds_read_b128 v[92:95], v114 offset:32768
	ds_read_b128 v[104:107], v169 offset:32768
	ds_read_b128 v[108:111], v168 offset:32768
	s_waitcnt lgkmcnt(0)
	v_mfma_f32_16x16x32_bf16 v[52:55], v[108:111], v[84:87], v[52:55]
	v_mfma_f32_16x16x32_bf16 v[48:51], v[104:107], v[84:87], v[48:51]
	v_mfma_f32_16x16x32_bf16 v[52:55], v[92:95], v[80:83], v[52:55]
	v_mfma_f32_16x16x32_bf16 v[48:51], v[88:91], v[80:83], v[48:51]
	v_mfma_f32_16x16x32_bf16 v[52:55], v[76:79], v[20:23], v[52:55]
	v_mfma_f32_16x16x32_bf16 v[48:51], v[72:75], v[20:23], v[48:51]
	v_mfma_f32_16x16x32_bf16 v[72:75], v[60:63], v[8:11], v[52:55]
	v_mfma_f32_16x16x32_bf16 v[76:79], v[56:59], v[8:11], v[48:51]
	s_nop 5
	ds_read_b128 v[48:51], v119 offset:40960
	ds_read_b128 v[52:55], v118 offset:40960
	ds_read_b128 v[56:59], v117 offset:40960
	ds_read_b128 v[60:63], v116 offset:40960
	ds_read_b128 v[88:91], v115 offset:40960
	ds_read_b128 v[92:95], v114 offset:40960
	ds_read_b128 v[104:107], v169 offset:40960
	ds_read_b128 v[108:111], v168 offset:40960
	s_waitcnt lgkmcnt(0)
	v_mfma_f32_16x16x32_bf16 v[44:47], v[108:111], v[84:87], v[44:47]
	v_mfma_f32_16x16x32_bf16 v[40:43], v[104:107], v[84:87], v[40:43]
	v_mfma_f32_16x16x32_bf16 v[44:47], v[92:95], v[80:83], v[44:47]
	v_mfma_f32_16x16x32_bf16 v[40:43], v[88:91], v[80:83], v[40:43]
	v_mfma_f32_16x16x32_bf16 v[44:47], v[60:63], v[20:23], v[44:47]
	v_mfma_f32_16x16x32_bf16 v[40:43], v[56:59], v[20:23], v[40:43]
	v_mfma_f32_16x16x32_bf16 v[88:91], v[52:55], v[8:11], v[44:47]
	v_mfma_f32_16x16x32_bf16 v[92:95], v[48:51], v[8:11], v[40:43]
	s_nop 5
	ds_read_b128 v[40:43], v119 offset:49152
	ds_read_b128 v[44:47], v118 offset:49152
	ds_read_b128 v[48:51], v117 offset:49152
	ds_read_b128 v[52:55], v116 offset:49152
	ds_read_b128 v[56:59], v115 offset:49152
	ds_read_b128 v[60:63], v114 offset:49152
	ds_read_b128 v[104:107], v169 offset:49152
	ds_read_b128 v[108:111], v168 offset:49152
	s_waitcnt lgkmcnt(0)
	v_mfma_f32_16x16x32_bf16 v[36:39], v[108:111], v[84:87], v[36:39]
	v_mfma_f32_16x16x32_bf16 v[32:35], v[104:107], v[84:87], v[32:35]
	v_mfma_f32_16x16x32_bf16 v[36:39], v[60:63], v[80:83], v[36:39]
	v_mfma_f32_16x16x32_bf16 v[32:35], v[56:59], v[80:83], v[32:35]
	v_mfma_f32_16x16x32_bf16 v[36:39], v[52:55], v[20:23], v[36:39]
	v_mfma_f32_16x16x32_bf16 v[32:35], v[48:51], v[20:23], v[32:35]
	v_mfma_f32_16x16x32_bf16 v[104:107], v[44:47], v[8:11], v[36:39]
	v_mfma_f32_16x16x32_bf16 v[108:111], v[40:43], v[8:11], v[32:35]
	s_nop 5
	ds_read_b128 v[32:35], v119 offset:57344
	ds_read_b128 v[36:39], v118 offset:57344
	ds_read_b128 v[40:43], v117 offset:57344
	ds_read_b128 v[44:47], v116 offset:57344
	ds_read_b128 v[48:51], v115 offset:57344
	ds_read_b128 v[52:55], v114 offset:57344
	ds_read_b128 v[56:59], v169 offset:57344
	ds_read_b128 v[60:63], v168 offset:57344
	s_waitcnt lgkmcnt(0)
	v_mfma_f32_16x16x32_bf16 v[12:15], v[60:63], v[84:87], v[12:15]
	v_mfma_f32_16x16x32_bf16 v[16:19], v[56:59], v[84:87], v[16:19]
	v_mfma_f32_16x16x32_bf16 v[12:15], v[52:55], v[80:83], v[12:15]
	v_mfma_f32_16x16x32_bf16 v[16:19], v[48:51], v[80:83], v[16:19]
	v_mfma_f32_16x16x32_bf16 v[12:15], v[44:47], v[20:23], v[12:15]
	v_mfma_f32_16x16x32_bf16 v[16:19], v[40:43], v[20:23], v[16:19]
	v_mfma_f32_16x16x32_bf16 v[80:83], v[36:39], v[8:11], v[12:15]
	v_mfma_f32_16x16x32_bf16 v[84:87], v[32:35], v[8:11], v[16:19]
	s_waitcnt vmcnt(0)
	s_waitcnt vmcnt(0)
	s_barrier
	global_load_dwordx4 v[124:127], v[112:113], off offset:768
	global_load_dwordx4 v[120:123], v[112:113], off offset:832
	global_load_dwordx4 v[116:119], v[112:113], off offset:896
	s_nop 0
	global_load_dwordx4 v[112:115], v[112:113], off offset:960
	ds_read_b128 v[8:11], v171
	s_waitcnt vmcnt(3) lgkmcnt(0)
	v_mfma_f32_16x16x32_bf16 v[0:3], v[8:11], v[124:127], v[0:3]
	ds_read_b128 v[8:11], v172
	v_lshl_add_u64 v[12:13], v[138:139], 0, s[30:31]
	s_mov_b64 s[30:31], 0x1c1000
	s_waitcnt lgkmcnt(0)
	v_mfma_f32_16x16x32_bf16 v[4:7], v[8:11], v[124:127], v[4:7]
	ds_read_b128 v[8:11], v173
	s_waitcnt vmcnt(2) lgkmcnt(0)
	v_mfma_f32_16x16x32_bf16 v[0:3], v[8:11], v[120:123], v[0:3]
	ds_read_b128 v[8:11], v174
	s_waitcnt lgkmcnt(0)
	v_mfma_f32_16x16x32_bf16 v[4:7], v[8:11], v[120:123], v[4:7]
	ds_read_b128 v[8:11], v175
	s_waitcnt vmcnt(1) lgkmcnt(0)
	v_mfma_f32_16x16x32_bf16 v[0:3], v[8:11], v[116:119], v[0:3]
	ds_read_b128 v[8:11], v176
	s_waitcnt lgkmcnt(0)
	v_mfma_f32_16x16x32_bf16 v[4:7], v[8:11], v[116:119], v[4:7]
	ds_read_b128 v[8:11], v177
	s_waitcnt vmcnt(0) lgkmcnt(0)
	v_mfma_f32_16x16x32_bf16 v[52:55], v[8:11], v[112:115], v[0:3]
	s_nop 2
	ds_read_b128 v[0:3], v178
	s_waitcnt lgkmcnt(0)
	v_mfma_f32_16x16x32_bf16 v[44:47], v[0:3], v[112:115], v[4:7]
	v_lshl_add_u64 v[0:1], v[138:139], 0, s[30:31]
	s_mov_b64 s[30:31], 0x181000
	v_lshl_add_u64 v[2:3], v[138:139], 0, s[30:31]
	s_mov_b64 s[30:31], 0x141000
	v_lshl_add_u64 v[4:5], v[138:139], 0, s[30:31]
	s_mov_b64 s[30:31], 0x101000
	v_lshl_add_u64 v[6:7], v[138:139], 0, s[30:31]
	s_mov_b64 s[30:31], 0xc1000
	v_lshl_add_u64 v[8:9], v[138:139], 0, s[30:31]
	s_mov_b64 s[30:31], 0x81000
	v_lshl_add_u64 v[10:11], v[138:139], 0, s[30:31]
	s_mov_b64 s[30:31], 0x41000
	v_lshl_add_u64 v[14:15], v[138:139], 0, s[30:31]
	global_load_lds_dwordx4 v[12:13], off
	s_mov_b32 m0, s5
	s_mov_b32 s5, 0xf149f2ca
	global_load_lds_dwordx4 v[14:15], off
	s_mov_b32 m0, s24
	s_nop 0
	global_load_lds_dwordx4 v[10:11], off
	s_mov_b32 m0, s25
	s_nop 0
	global_load_lds_dwordx4 v[8:9], off
	s_mov_b32 m0, s26
	s_nop 0
	global_load_lds_dwordx4 v[6:7], off
	s_mov_b32 m0, s27
	s_nop 0
	global_load_lds_dwordx4 v[4:5], off
	s_mov_b32 m0, s28
	s_nop 0
	global_load_lds_dwordx4 v[2:3], off
	s_mov_b32 m0, s29
	s_nop 0
	global_load_lds_dwordx4 v[0:1], off
	ds_read_b128 v[0:3], v179
	ds_read_b128 v[4:7], v180
	ds_read_b128 v[8:11], v181
	s_waitcnt lgkmcnt(0)
	v_mfma_f32_16x16x32_bf16 v[0:3], v[0:3], v[124:127], v[96:99]
	v_mfma_f32_16x16x32_bf16 v[0:3], v[8:11], v[120:123], v[0:3]
	ds_read_b128 v[8:11], v182
	v_mfma_f32_16x16x32_bf16 v[4:7], v[4:7], v[124:127], v[100:103]
	s_waitcnt lgkmcnt(0)
	v_mfma_f32_16x16x32_bf16 v[4:7], v[8:11], v[120:123], v[4:7]
	ds_read_b128 v[8:11], v183
	s_waitcnt lgkmcnt(0)
	v_mfma_f32_16x16x32_bf16 v[0:3], v[8:11], v[116:119], v[0:3]
	ds_read_b128 v[8:11], v184
	s_waitcnt lgkmcnt(0)
	v_mfma_f32_16x16x32_bf16 v[4:7], v[8:11], v[116:119], v[4:7]
	ds_read_b128 v[8:11], v185
	s_waitcnt lgkmcnt(0)
	v_mfma_f32_16x16x32_bf16 v[60:63], v[8:11], v[112:115], v[0:3]
	s_nop 2
	ds_read_b128 v[0:3], v186
	s_waitcnt lgkmcnt(0)
	v_mfma_f32_16x16x32_bf16 v[56:59], v[0:3], v[112:115], v[4:7]
	ds_read_b128 v[0:3], v187
	s_nop 1
	ds_read_b128 v[4:7], v188
	ds_read_b128 v[8:11], v189
	ds_read_b128 v[12:15], v192
	ds_read_b128 v[16:19], v193
	ds_read_b128 v[20:23], v194
	ds_read_b128 v[32:35], v195
	ds_read_b128 v[36:39], v196
	s_waitcnt lgkmcnt(0)
	v_mfma_f32_16x16x32_bf16 v[24:27], v[36:39], v[124:127], v[24:27]
	v_mfma_f32_16x16x32_bf16 v[28:31], v[32:35], v[124:127], v[28:31]
	v_mfma_f32_16x16x32_bf16 v[20:23], v[20:23], v[120:123], v[24:27]
	v_mfma_f32_16x16x32_bf16 v[16:19], v[16:19], v[120:123], v[28:31]
	v_mfma_f32_16x16x32_bf16 v[12:15], v[12:15], v[116:119], v[20:23]
	v_mfma_f32_16x16x32_bf16 v[8:11], v[8:11], v[116:119], v[16:19]
	v_mfma_f32_16x16x32_bf16 v[48:51], v[4:7], v[112:115], v[12:15]
	v_mfma_f32_16x16x32_bf16 v[40:43], v[0:3], v[112:115], v[8:11]
	ds_read_b128 v[0:3], v197
	ds_read_b128 v[4:7], v198
	s_nop 3
	ds_read_b128 v[8:11], v199
	ds_read_b128 v[12:15], v200
	ds_read_b128 v[16:19], v201
	ds_read_b128 v[20:23], v202
	ds_read_b128 v[24:27], v203
	ds_read_b128 v[28:31], v204
	s_waitcnt lgkmcnt(0)
	v_mfma_f32_16x16x32_bf16 v[28:31], v[28:31], v[124:127], v[64:67]
	v_mfma_f32_16x16x32_bf16 v[24:27], v[24:27], v[124:127], v[68:71]
	v_mfma_f32_16x16x32_bf16 v[20:23], v[20:23], v[120:123], v[28:31]
	v_mfma_f32_16x16x32_bf16 v[16:19], v[16:19], v[120:123], v[24:27]
	v_mfma_f32_16x16x32_bf16 v[12:15], v[12:15], v[116:119], v[20:23]
	v_mfma_f32_16x16x32_bf16 v[8:11], v[8:11], v[116:119], v[16:19]
	v_mfma_f32_16x16x32_bf16 v[36:39], v[4:7], v[112:115], v[12:15]
	v_mfma_f32_16x16x32_bf16 v[32:35], v[0:3], v[112:115], v[8:11]
	ds_read_b128 v[0:3], v205
	ds_read_b128 v[4:7], v206
	s_nop 3
	ds_read_b128 v[8:11], v207
	ds_read_b128 v[12:15], v208
	ds_read_b128 v[16:19], v209
	ds_read_b128 v[20:23], v210
	ds_read_b128 v[24:27], v211
	ds_read_b128 v[28:31], v212
	s_waitcnt lgkmcnt(0)
	v_mfma_f32_16x16x32_bf16 v[28:31], v[28:31], v[124:127], v[72:75]
	v_mfma_f32_16x16x32_bf16 v[24:27], v[24:27], v[124:127], v[76:79]
	v_mfma_f32_16x16x32_bf16 v[20:23], v[20:23], v[120:123], v[28:31]
	v_mfma_f32_16x16x32_bf16 v[16:19], v[16:19], v[120:123], v[24:27]
	v_mfma_f32_16x16x32_bf16 v[12:15], v[12:15], v[116:119], v[20:23]
	v_mfma_f32_16x16x32_bf16 v[8:11], v[8:11], v[116:119], v[16:19]
	v_mfma_f32_16x16x32_bf16 v[28:31], v[4:7], v[112:115], v[12:15]
	v_mfma_f32_16x16x32_bf16 v[24:27], v[0:3], v[112:115], v[8:11]
	ds_read_b128 v[0:3], v213
	ds_read_b128 v[4:7], v214
	s_nop 3
	ds_read_b128 v[8:11], v215
	ds_read_b128 v[12:15], v216
	ds_read_b128 v[16:19], v217
	ds_read_b128 v[20:23], v218
	ds_read_b128 v[64:67], v219
	ds_read_b128 v[68:71], v220
	s_waitcnt lgkmcnt(0)
	v_mfma_f32_16x16x32_bf16 v[68:71], v[68:71], v[124:127], v[88:91]
	v_mfma_f32_16x16x32_bf16 v[64:67], v[64:67], v[124:127], v[92:95]
	v_mfma_f32_16x16x32_bf16 v[20:23], v[20:23], v[120:123], v[68:71]
	v_mfma_f32_16x16x32_bf16 v[16:19], v[16:19], v[120:123], v[64:67]
	v_mfma_f32_16x16x32_bf16 v[12:15], v[12:15], v[116:119], v[20:23]
	v_mfma_f32_16x16x32_bf16 v[8:11], v[8:11], v[116:119], v[16:19]
	v_mfma_f32_16x16x32_bf16 v[20:23], v[4:7], v[112:115], v[12:15]
	v_mfma_f32_16x16x32_bf16 v[16:19], v[0:3], v[112:115], v[8:11]
	ds_read_b128 v[0:3], v221
	ds_read_b128 v[4:7], v222
	s_nop 3
	ds_read_b128 v[8:11], v223
	ds_read_b128 v[12:15], v224
	ds_read_b128 v[64:67], v225
	ds_read_b128 v[68:71], v226
	ds_read_b128 v[72:75], v227
	ds_read_b128 v[76:79], v228
	s_waitcnt lgkmcnt(0)
	v_mfma_f32_16x16x32_bf16 v[76:79], v[76:79], v[124:127], v[104:107]
	v_mfma_f32_16x16x32_bf16 v[72:75], v[72:75], v[124:127], v[108:111]
	v_mfma_f32_16x16x32_bf16 v[68:71], v[68:71], v[120:123], v[76:79]
	v_mfma_f32_16x16x32_bf16 v[64:67], v[64:67], v[120:123], v[72:75]
	v_mfma_f32_16x16x32_bf16 v[12:15], v[12:15], v[116:119], v[68:71]
	v_mfma_f32_16x16x32_bf16 v[8:11], v[8:11], v[116:119], v[64:67]
	v_mfma_f32_16x16x32_bf16 v[12:15], v[4:7], v[112:115], v[12:15]
	v_mfma_f32_16x16x32_bf16 v[8:11], v[0:3], v[112:115], v[8:11]
	ds_read_b128 v[0:3], v229
	ds_read_b128 v[4:7], v230
	s_nop 1
	ds_read_b128 v[64:67], v231
	ds_read_b128 v[68:71], v232
	ds_read_b128 v[72:75], v233
	ds_read_b128 v[76:79], v234
	ds_read_b128 v[88:91], v235
	ds_read_b128 v[92:95], v236
	s_waitcnt lgkmcnt(0)
	v_mfma_f32_16x16x32_bf16 v[84:87], v[88:91], v[124:127], v[84:87]
	v_mfma_f32_16x16x32_bf16 v[72:75], v[72:75], v[120:123], v[84:87]
	v_mfma_f32_16x16x32_bf16 v[64:67], v[64:67], v[116:119], v[72:75]
	v_mfma_f32_16x16x32_bf16 v[0:3], v[0:3], v[112:115], v[64:67]
	v_mfma_f32_16x16x32_bf16 v[80:83], v[92:95], v[124:127], v[80:83]
	s_nop 5
	v_max_f32_e32 v64, v55, v55
	v_max_f32_e32 v65, v54, v54
	v_max_f32_e32 v64, v65, v64
	v_max_f32_e32 v65, v47, v47
	v_max_f32_e32 v66, v46, v46
	v_max_f32_e32 v65, v66, v65
	v_max3_f32 v64, v52, v53, v64
	v_max3_f32 v65, v44, v45, v65
	v_max3_f32 v64, v64, s5, v65
	v_max_f32_e32 v65, v63, v63
	v_max_f32_e32 v66, v62, v62
	v_max_f32_e32 v65, v66, v65
	v_max_f32_e32 v66, v59, v59
	v_max_f32_e32 v67, v58, v58
	v_max_f32_e32 v66, v67, v66
	v_max3_f32 v65, v60, v61, v65
	v_max3_f32 v66, v56, v57, v66
	v_max3_f32 v64, v64, v65, v66
	v_max_f32_e32 v65, v51, v51
	v_max_f32_e32 v66, v50, v50
	v_max_f32_e32 v65, v66, v65
	v_max_f32_e32 v66, v43, v43
	v_max_f32_e32 v67, v42, v42
	v_max_f32_e32 v66, v67, v66
	v_max3_f32 v65, v48, v49, v65
	v_max3_f32 v66, v40, v41, v66
	v_max3_f32 v64, v64, v65, v66
	v_max_f32_e32 v65, v39, v39
	v_max_f32_e32 v66, v38, v38
	v_max_f32_e32 v65, v66, v65
	v_max_f32_e32 v66, v35, v35
	v_max_f32_e32 v67, v34, v34
	v_max_f32_e32 v66, v67, v66
	v_max3_f32 v65, v36, v37, v65
	v_max3_f32 v66, v32, v33, v66
	v_max3_f32 v64, v64, v65, v66
	v_max_f32_e32 v65, v31, v31
	v_max_f32_e32 v66, v30, v30
	v_max_f32_e32 v65, v66, v65
	v_max_f32_e32 v66, v27, v27
	v_max_f32_e32 v67, v26, v26
	v_max_f32_e32 v66, v67, v66
	v_mfma_f32_16x16x32_bf16 v[76:79], v[76:79], v[120:123], v[80:83]
	v_max3_f32 v65, v28, v29, v65
	v_max3_f32 v66, v24, v25, v66
	v_max3_f32 v64, v64, v65, v66
	v_max_f32_e32 v65, v23, v23
	v_max_f32_e32 v66, v22, v22
	v_max_f32_e32 v65, v66, v65
	v_max_f32_e32 v66, v19, v19
	v_max_f32_e32 v67, v18, v18
	v_max_f32_e32 v66, v67, v66
	v_mfma_f32_16x16x32_bf16 v[68:71], v[68:71], v[116:119], v[76:79]
	v_max3_f32 v65, v20, v21, v65
	v_max3_f32 v66, v16, v17, v66
	v_max3_f32 v64, v64, v65, v66
	v_max_f32_e32 v65, v15, v15
	v_max_f32_e32 v66, v14, v14
	v_max_f32_e32 v65, v66, v65
	v_max_f32_e32 v66, v11, v11
	v_max_f32_e32 v67, v10, v10
	v_max_f32_e32 v66, v67, v66
	v_mfma_f32_16x16x32_bf16 v[4:7], v[4:7], v[112:115], v[68:71]
	v_max3_f32 v65, v12, v13, v65
	v_max3_f32 v66, v8, v9, v66
	v_max3_f32 v64, v64, v65, v66
	v_max_f32_e32 v67, v2, v2
	s_nop 3
	v_max_f32_e32 v65, v7, v7
	v_max_f32_e32 v66, v6, v6
	v_max_f32_e32 v65, v66, v65
	v_max_f32_e32 v66, v3, v3
	v_max_f32_e32 v66, v67, v66
	v_max3_f32 v65, v4, v5, v65
	v_max3_f32 v66, v0, v1, v66
	v_max3_f32 v65, v64, v65, v66
	v_and_b32_e32 v66, 64, v170
	v_xor_b32_e32 v64, 16, v170
	v_add_u32_e32 v66, 64, v66
	v_cmp_lt_i32_e32 vcc, v64, v66
	s_or_b32 s5, s10, s23
	s_waitcnt vmcnt(0)
	s_waitcnt vmcnt(0)
	v_cndmask_b32_e32 v64, v170, v64, vcc
	v_lshlrev_b32_e32 v64, 2, v64
	ds_bpermute_b32 v67, v64, v65
	s_barrier
	s_waitcnt lgkmcnt(0)
	v_max_f32_e32 v67, v67, v67
	v_max_f32_e32 v67, v65, v67
	v_xor_b32_e32 v65, 32, v170
	v_cmp_lt_i32_e32 vcc, v65, v66
	s_nop 1
	v_cndmask_b32_e32 v65, v170, v65, vcc
	v_lshlrev_b32_e32 v65, 2, v65
	ds_bpermute_b32 v66, v65, v67
	s_waitcnt lgkmcnt(0)
	v_max_f32_e32 v66, v66, v66
	v_max_f32_e32 v66, v67, v66
	v_sub_f32_e32 v52, v52, v66
	v_mul_f32_e32 v52, 0x3d3504f3, v52
	v_sub_f32_e32 v53, v53, v66
	v_mul_f32_e32 v52, 0x3fb8aa3b, v52
	v_mul_f32_e32 v53, 0x3d3504f3, v53
	v_sub_f32_e32 v54, v54, v66
	v_exp_f32_e32 v52, v52
	v_mul_f32_e32 v53, 0x3fb8aa3b, v53
	v_mul_f32_e32 v54, 0x3d3504f3, v54
	v_sub_f32_e32 v55, v55, v66
	v_exp_f32_e32 v53, v53
	v_mul_f32_e32 v54, 0x3fb8aa3b, v54
	v_mul_f32_e32 v55, 0x3d3504f3, v55
	v_sub_f32_e32 v44, v44, v66
	v_exp_f32_e32 v54, v54
	v_mul_f32_e32 v55, 0x3fb8aa3b, v55
	v_mul_f32_e32 v44, 0x3d3504f3, v44
	v_sub_f32_e32 v45, v45, v66
	v_exp_f32_e32 v55, v55
	v_mul_f32_e32 v44, 0x3fb8aa3b, v44
	v_mul_f32_e32 v45, 0x3d3504f3, v45
	v_sub_f32_e32 v46, v46, v66
	v_add_f32_e32 v67, 0, v52
	v_exp_f32_e32 v44, v44
	v_mul_f32_e32 v45, 0x3fb8aa3b, v45
	v_mul_f32_e32 v46, 0x3d3504f3, v46
	v_sub_f32_e32 v47, v47, v66
	v_add_f32_e32 v67, v53, v67
	v_exp_f32_e32 v45, v45
	v_mul_f32_e32 v46, 0x3fb8aa3b, v46
	v_mul_f32_e32 v47, 0x3d3504f3, v47
	v_sub_f32_e32 v60, v60, v66
	v_add_f32_e32 v67, v54, v67
	v_exp_f32_e32 v46, v46
	v_mul_f32_e32 v47, 0x3fb8aa3b, v47
	v_mul_f32_e32 v60, 0x3d3504f3, v60
	v_sub_f32_e32 v61, v61, v66
	v_add_f32_e32 v67, v55, v67
	v_exp_f32_e32 v47, v47
	v_mul_f32_e32 v60, 0x3fb8aa3b, v60
	v_mul_f32_e32 v61, 0x3d3504f3, v61
	v_sub_f32_e32 v62, v62, v66
	v_add_f32_e32 v67, v44, v67
	v_exp_f32_e32 v60, v60
	v_mul_f32_e32 v61, 0x3fb8aa3b, v61
	v_mul_f32_e32 v62, 0x3d3504f3, v62
	v_sub_f32_e32 v63, v63, v66
	v_add_f32_e32 v67, v45, v67
	v_exp_f32_e32 v61, v61
	v_mul_f32_e32 v62, 0x3fb8aa3b, v62
	v_mul_f32_e32 v63, 0x3d3504f3, v63
	v_sub_f32_e32 v56, v56, v66
	v_add_f32_e32 v67, v46, v67
	v_exp_f32_e32 v62, v62
	v_mul_f32_e32 v63, 0x3fb8aa3b, v63
	v_mul_f32_e32 v56, 0x3d3504f3, v56
	v_sub_f32_e32 v57, v57, v66
	v_add_f32_e32 v67, v47, v67
	v_exp_f32_e32 v63, v63
	v_mul_f32_e32 v56, 0x3fb8aa3b, v56
	v_mul_f32_e32 v57, 0x3d3504f3, v57
	v_sub_f32_e32 v58, v58, v66
	v_add_f32_e32 v67, v60, v67
	v_exp_f32_e32 v56, v56
	v_mul_f32_e32 v57, 0x3fb8aa3b, v57
	v_mul_f32_e32 v58, 0x3d3504f3, v58
	v_sub_f32_e32 v59, v59, v66
	v_add_f32_e32 v67, v61, v67
	v_exp_f32_e32 v57, v57
	v_mul_f32_e32 v58, 0x3fb8aa3b, v58
	v_mul_f32_e32 v59, 0x3d3504f3, v59
	v_sub_f32_e32 v48, v48, v66
	v_add_f32_e32 v67, v62, v67
	v_exp_f32_e32 v58, v58
	v_mul_f32_e32 v59, 0x3fb8aa3b, v59
	v_mul_f32_e32 v48, 0x3d3504f3, v48
	v_sub_f32_e32 v49, v49, v66
	v_add_f32_e32 v67, v63, v67
	v_exp_f32_e32 v59, v59
	v_mul_f32_e32 v48, 0x3fb8aa3b, v48
	v_mul_f32_e32 v49, 0x3d3504f3, v49
	v_sub_f32_e32 v50, v50, v66
	v_add_f32_e32 v67, v56, v67
	v_exp_f32_e32 v48, v48
	v_mul_f32_e32 v49, 0x3fb8aa3b, v49
	v_mul_f32_e32 v50, 0x3d3504f3, v50
	v_sub_f32_e32 v51, v51, v66
	v_add_f32_e32 v67, v57, v67
	v_exp_f32_e32 v49, v49
	v_mul_f32_e32 v50, 0x3fb8aa3b, v50
	v_mul_f32_e32 v51, 0x3d3504f3, v51
	v_sub_f32_e32 v40, v40, v66
	v_add_f32_e32 v67, v58, v67
	v_exp_f32_e32 v50, v50
	v_mul_f32_e32 v51, 0x3fb8aa3b, v51
	v_mul_f32_e32 v40, 0x3d3504f3, v40
	v_sub_f32_e32 v41, v41, v66
	v_add_f32_e32 v67, v59, v67
	v_exp_f32_e32 v51, v51
	v_mul_f32_e32 v40, 0x3fb8aa3b, v40
	v_mul_f32_e32 v41, 0x3d3504f3, v41
	v_sub_f32_e32 v42, v42, v66
	v_add_f32_e32 v67, v48, v67
	v_exp_f32_e32 v40, v40
	v_mul_f32_e32 v41, 0x3fb8aa3b, v41
	v_mul_f32_e32 v42, 0x3d3504f3, v42
	v_sub_f32_e32 v43, v43, v66
	v_add_f32_e32 v67, v49, v67
	v_exp_f32_e32 v41, v41
	v_mul_f32_e32 v42, 0x3fb8aa3b, v42
	v_mul_f32_e32 v43, 0x3d3504f3, v43
	v_sub_f32_e32 v36, v36, v66
	v_add_f32_e32 v67, v50, v67
	v_exp_f32_e32 v42, v42
	v_mul_f32_e32 v43, 0x3fb8aa3b, v43
	v_mul_f32_e32 v36, 0x3d3504f3, v36
	v_sub_f32_e32 v37, v37, v66
	v_add_f32_e32 v67, v51, v67
	v_exp_f32_e32 v43, v43
	v_mul_f32_e32 v36, 0x3fb8aa3b, v36
	v_mul_f32_e32 v37, 0x3d3504f3, v37
	v_sub_f32_e32 v38, v38, v66
	v_add_f32_e32 v67, v40, v67
	v_exp_f32_e32 v36, v36
	v_mul_f32_e32 v37, 0x3fb8aa3b, v37
	v_mul_f32_e32 v38, 0x3d3504f3, v38
	v_sub_f32_e32 v39, v39, v66
	v_add_f32_e32 v67, v41, v67
	v_exp_f32_e32 v37, v37
	v_mul_f32_e32 v38, 0x3fb8aa3b, v38
	v_mul_f32_e32 v39, 0x3d3504f3, v39
	v_sub_f32_e32 v32, v32, v66
	v_add_f32_e32 v67, v42, v67
	v_exp_f32_e32 v38, v38
	v_mul_f32_e32 v39, 0x3fb8aa3b, v39
	v_mul_f32_e32 v32, 0x3d3504f3, v32
	v_sub_f32_e32 v33, v33, v66
	v_add_f32_e32 v67, v43, v67
	v_exp_f32_e32 v39, v39
	v_mul_f32_e32 v32, 0x3fb8aa3b, v32
	v_mul_f32_e32 v33, 0x3d3504f3, v33
	v_sub_f32_e32 v34, v34, v66
	v_add_f32_e32 v67, v36, v67
	v_exp_f32_e32 v32, v32
	v_mul_f32_e32 v33, 0x3fb8aa3b, v33
	v_mul_f32_e32 v34, 0x3d3504f3, v34
	v_sub_f32_e32 v35, v35, v66
	v_add_f32_e32 v67, v37, v67
	v_exp_f32_e32 v33, v33
	v_mul_f32_e32 v34, 0x3fb8aa3b, v34
	v_mul_f32_e32 v35, 0x3d3504f3, v35
	v_sub_f32_e32 v28, v28, v66
	v_add_f32_e32 v67, v38, v67
	v_exp_f32_e32 v34, v34
	v_mul_f32_e32 v35, 0x3fb8aa3b, v35
	v_mul_f32_e32 v28, 0x3d3504f3, v28
	v_add_f32_e32 v67, v39, v67
	v_exp_f32_e32 v35, v35
	v_mul_f32_e32 v28, 0x3fb8aa3b, v28
	v_add_f32_e32 v67, v32, v67
	v_exp_f32_e32 v68, v28
	v_add_f32_e32 v67, v33, v67
	v_sub_f32_e32 v29, v29, v66
	v_add_f32_e32 v67, v34, v67
	v_mul_f32_e32 v29, 0x3d3504f3, v29
	v_add_f32_e32 v67, v35, v67
	v_mul_f32_e32 v29, 0x3fb8aa3b, v29
	v_add_f32_e32 v28, v68, v67
	v_exp_f32_e32 v67, v29
	v_sub_f32_e32 v29, v30, v66
	v_mul_f32_e32 v29, 0x3d3504f3, v29
	v_sub_f32_e32 v25, v25, v66
	v_mul_f32_e32 v29, 0x3fb8aa3b, v29
	v_mul_f32_e32 v25, 0x3d3504f3, v25
	v_exp_f32_e32 v69, v29
	v_sub_f32_e32 v29, v31, v66
	v_mul_f32_e32 v25, 0x3fb8aa3b, v25
	v_mul_f32_e32 v29, 0x3d3504f3, v29
	v_sub_f32_e32 v24, v24, v66
	v_exp_f32_e32 v72, v25
	v_sub_f32_e32 v25, v26, v66
	v_mul_f32_e32 v29, 0x3fb8aa3b, v29
	v_mul_f32_e32 v24, 0x3d3504f3, v24
	v_mul_f32_e32 v25, 0x3d3504f3, v25
	v_sub_f32_e32 v21, v21, v66
	v_exp_f32_e32 v70, v29
	v_mul_f32_e32 v24, 0x3fb8aa3b, v24
	v_mul_f32_e32 v25, 0x3fb8aa3b, v25
	v_mul_f32_e32 v21, 0x3d3504f3, v21
	v_exp_f32_e32 v71, v24
	v_exp_f32_e32 v73, v25
	v_sub_f32_e32 v25, v27, v66
	v_mul_f32_e32 v21, 0x3fb8aa3b, v21
	v_add_f32_e32 v28, v67, v28
	v_mul_f32_e32 v25, 0x3d3504f3, v25
	v_sub_f32_e32 v20, v20, v66
	v_exp_f32_e32 v76, v21
	v_sub_f32_e32 v21, v22, v66
	v_add_f32_e32 v28, v69, v28
	v_mul_f32_e32 v25, 0x3fb8aa3b, v25
	v_mul_f32_e32 v20, 0x3d3504f3, v20
	v_mul_f32_e32 v21, 0x3d3504f3, v21
	v_sub_f32_e32 v17, v17, v66
	v_add_f32_e32 v28, v70, v28
	v_exp_f32_e32 v74, v25
	v_mul_f32_e32 v20, 0x3fb8aa3b, v20
	v_mul_f32_e32 v21, 0x3fb8aa3b, v21
	v_mul_f32_e32 v17, 0x3d3504f3, v17
	v_add_f32_e32 v24, v71, v28
	v_exp_f32_e32 v75, v20
	v_exp_f32_e32 v77, v21
	v_sub_f32_e32 v21, v23, v66
	v_mul_f32_e32 v17, 0x3fb8aa3b, v17
	v_add_f32_e32 v24, v72, v24
	v_mul_f32_e32 v21, 0x3d3504f3, v21
	v_sub_f32_e32 v16, v16, v66
	v_exp_f32_e32 v80, v17
	v_sub_f32_e32 v17, v18, v66
	v_add_f32_e32 v24, v73, v24
	v_mul_f32_e32 v21, 0x3fb8aa3b, v21
	v_mul_f32_e32 v16, 0x3d3504f3, v16
	v_mul_f32_e32 v17, 0x3d3504f3, v17
	v_add_f32_e32 v24, v74, v24
	v_exp_f32_e32 v78, v21
	v_mul_f32_e32 v16, 0x3fb8aa3b, v16
	v_mul_f32_e32 v17, 0x3fb8aa3b, v17
	v_add_f32_e32 v20, v75, v24
	v_exp_f32_e32 v79, v16
	v_exp_f32_e32 v81, v17
	v_sub_f32_e32 v17, v19, v66
	v_add_f32_e32 v20, v76, v20
	v_mul_f32_e32 v17, 0x3d3504f3, v17
	v_sub_f32_e32 v12, v12, v66
	v_add_f32_e32 v20, v77, v20
	v_mul_f32_e32 v17, 0x3fb8aa3b, v17
	v_mul_f32_e32 v12, 0x3d3504f3, v12
	v_sub_f32_e32 v13, v13, v66
	v_sub_f32_e32 v9, v9, v66
	v_add_f32_e32 v20, v78, v20
	v_exp_f32_e32 v82, v17
	v_mul_f32_e32 v12, 0x3fb8aa3b, v12
	v_mul_f32_e32 v13, 0x3d3504f3, v13
	v_sub_f32_e32 v14, v14, v66
	v_mul_f32_e32 v9, 0x3d3504f3, v9
	v_add_f32_e32 v16, v79, v20
	v_exp_f32_e32 v12, v12
	v_mul_f32_e32 v13, 0x3fb8aa3b, v13
	v_mul_f32_e32 v14, 0x3d3504f3, v14
	v_sub_f32_e32 v15, v15, v66
	v_mul_f32_e32 v9, 0x3fb8aa3b, v9
	v_add_f32_e32 v16, v80, v16
	v_exp_f32_e32 v13, v13
	v_mul_f32_e32 v14, 0x3fb8aa3b, v14
	v_mul_f32_e32 v15, 0x3d3504f3, v15
	v_sub_f32_e32 v8, v8, v66
	v_exp_f32_e32 v84, v9
	v_sub_f32_e32 v9, v10, v66
	v_add_f32_e32 v16, v81, v16
	v_exp_f32_e32 v14, v14
	v_mul_f32_e32 v15, 0x3fb8aa3b, v15
	v_mul_f32_e32 v8, 0x3d3504f3, v8
	v_mul_f32_e32 v9, 0x3d3504f3, v9
	v_sub_f32_e32 v5, v5, v66
	v_add_f32_e32 v16, v82, v16
	v_exp_f32_e32 v15, v15
	v_mul_f32_e32 v8, 0x3fb8aa3b, v8
	v_mul_f32_e32 v9, 0x3fb8aa3b, v9
	v_mul_f32_e32 v5, 0x3d3504f3, v5
	v_add_f32_e32 v16, v12, v16
	v_exp_f32_e32 v83, v8
	v_exp_f32_e32 v85, v9
	v_sub_f32_e32 v9, v11, v66
	v_mul_f32_e32 v5, 0x3fb8aa3b, v5
	v_add_f32_e32 v16, v13, v16
	v_mul_f32_e32 v9, 0x3d3504f3, v9
	v_sub_f32_e32 v4, v4, v66
	v_exp_f32_e32 v88, v5
	v_sub_f32_e32 v5, v6, v66
	v_add_f32_e32 v16, v14, v16
	v_mul_f32_e32 v9, 0x3fb8aa3b, v9
	v_mul_f32_e32 v4, 0x3d3504f3, v4
	v_mul_f32_e32 v5, 0x3d3504f3, v5
	v_sub_f32_e32 v1, v1, v66
	v_add_f32_e32 v16, v15, v16
	v_exp_f32_e32 v86, v9
	v_mul_f32_e32 v4, 0x3fb8aa3b, v4
	v_mul_f32_e32 v5, 0x3fb8aa3b, v5
	v_mul_f32_e32 v1, 0x3d3504f3, v1
	v_add_f32_e32 v8, v83, v16
	v_exp_f32_e32 v87, v4
	v_exp_f32_e32 v89, v5
	v_sub_f32_e32 v5, v7, v66
	v_mul_f32_e32 v1, 0x3fb8aa3b, v1
	v_add_f32_e32 v8, v84, v8
	v_mul_f32_e32 v5, 0x3d3504f3, v5
	v_sub_f32_e32 v0, v0, v66
	v_exp_f32_e32 v92, v1
	v_sub_f32_e32 v1, v2, v66
	v_add_f32_e32 v8, v85, v8
	v_mul_f32_e32 v5, 0x3fb8aa3b, v5
	v_mul_f32_e32 v0, 0x3d3504f3, v0
	v_mul_f32_e32 v1, 0x3d3504f3, v1
	v_add_f32_e32 v8, v86, v8
	v_exp_f32_e32 v90, v5
	v_mul_f32_e32 v0, 0x3fb8aa3b, v0
	v_mul_f32_e32 v1, 0x3fb8aa3b, v1
	v_add_f32_e32 v4, v87, v8
	v_exp_f32_e32 v91, v0
	v_exp_f32_e32 v93, v1
	v_sub_f32_e32 v1, v3, v66
	v_add_f32_e32 v4, v88, v4
	v_mul_f32_e32 v1, 0x3d3504f3, v1
	v_add_f32_e32 v4, v89, v4
	v_mul_f32_e32 v1, 0x3fb8aa3b, v1
	v_add_f32_e32 v4, v90, v4
	v_exp_f32_e32 v3, v1
	v_add_f32_e32 v0, v91, v4
	v_add_f32_e32 v0, v92, v0
	v_add_f32_e32 v0, v93, v0
	v_add_f32_e32 v0, v3, v0
	ds_bpermute_b32 v1, v64, v0
	v_cvt_pk_bf16_f32 v18, v32, v33
	v_cvt_pk_bf16_f32 v19, v34, v35
	v_cvt_pk_bf16_f32 v16, v36, v37
	v_cvt_pk_bf16_f32 v24, v52, v53
	s_waitcnt lgkmcnt(0)
	v_add_f32_e32 v0, v0, v1
	ds_bpermute_b32 v1, v65, v0
	v_cvt_pk_bf16_f32 v25, v54, v55
	v_cvt_pk_bf16_f32 v26, v44, v45
	v_cvt_pk_bf16_f32 v27, v46, v47
	v_cvt_pk_bf16_f32 v28, v60, v61
	s_waitcnt lgkmcnt(0)
	v_add_f32_e32 v64, v0, v1
	v_div_scale_f32 v32, s[24:25], v64, v64, 1.0
	v_rcp_f32_e32 v33, v32
	v_cvt_pk_bf16_f32 v29, v62, v63
	v_cvt_pk_bf16_f32 v30, v56, v57
	v_cvt_pk_bf16_f32 v31, v58, v59
	v_fma_f32 v34, -v32, v33, 1.0
	v_fmac_f32_e32 v33, v34, v33
	v_div_scale_f32 v34, vcc, 1.0, v64, 1.0
	v_mul_f32_e32 v35, v34, v33
	v_fma_f32 v36, -v32, v35, v34
	v_fmac_f32_e32 v35, v36, v33
	v_fma_f32 v32, -v32, v35, v34
	v_lshl_or_b32 v34, s4, 15, v167
	s_add_u32 s4, s92, s5
	s_addc_u32 s5, s93, s11
	s_add_u32 s6, s6, s8
	s_addc_u32 s7, s7, s9
	v_lshl_add_u64 v[36:37], s[6:7], 0, v[128:129]
	v_div_fmas_f32 v32, v32, v33, v35
	v_lshlrev_b64 v[36:37], 12, v[36:37]
	v_div_fixup_f32 v32, v32, v64, 1.0
	v_add_u32_e32 v34, v34, v135
	v_mov_b32_e32 v35, v129
	v_or_b32_e32 v36, s23, v36
	v_cvt_pk_bf16_f32 v20, v48, v49
	v_cvt_pk_bf16_f32 v21, v50, v51
	v_cvt_pk_bf16_f32 v22, v40, v41
	v_cvt_pk_bf16_f32 v23, v42, v43
	v_cvt_pk_bf16_f32 v17, v38, v39
	v_cvt_pk_bf16_f32 v4, v68, v67
	v_cvt_pk_bf16_f32 v5, v69, v70
	v_cvt_pk_bf16_f32 v6, v71, v72
	v_cvt_pk_bf16_f32 v7, v73, v74
	v_cvt_pk_bf16_f32 v8, v75, v76
	v_cvt_pk_bf16_f32 v9, v77, v78
	v_cvt_pk_bf16_f32 v10, v79, v80
	v_cvt_pk_bf16_f32 v11, v81, v82
	v_cvt_pk_bf16_f32 v12, v12, v13
	v_cvt_pk_bf16_f32 v13, v14, v15
	v_cvt_pk_bf16_f32 v14, v83, v84
	v_cvt_pk_bf16_f32 v15, v85, v86
	v_cvt_pk_bf16_f32 v0, v87, v88
	v_cvt_pk_bf16_f32 v1, v89, v90
	v_cvt_pk_bf16_f32 v2, v91, v92
	v_cvt_pk_bf16_f32 v3, v93, v3
	v_mov_b32_e32 v33, v32
	v_lshl_add_u64 v[34:35], s[4:5], 0, v[34:35]
	v_lshl_add_u64 v[36:37], v[130:131], 0, v[36:37]
	s_mov_b64 s[6:7], 0
	s_mov_b32 s4, 0
.LBB0_861:
	s_and_b32 s5, s4, 0x10000
	s_add_i32 s4, s4, 0x10000
	s_and_b32 s10, s4, 0x10000
	v_lshl_add_u64 v[38:39], v[34:35], 0, s[6:7]
	s_mov_b64 s[8:9], 0x30001100
	s_add_i32 s10, s0, s10
	v_lshl_add_u64 v[40:41], v[38:39], 0, s[8:9]
	s_mov_b32 m0, s10
	s_mov_b64 s[8:9], 0x30041100
	global_load_lds_dwordx4 v[40:41], off
	v_lshl_add_u64 v[40:41], v[38:39], 0, s[8:9]
	s_add_i32 m0, s10, 0x2000
	s_mov_b64 s[8:9], 0x30081100
	global_load_lds_dwordx4 v[40:41], off
	v_lshl_add_u64 v[40:41], v[38:39], 0, s[8:9]
	s_add_i32 m0, s10, 0x4000
	s_mov_b64 s[8:9], 0x300c1100
	global_load_lds_dwordx4 v[40:41], off
	v_lshl_add_u64 v[40:41], v[38:39], 0, s[8:9]
	s_add_i32 m0, s10, 0x6000
	s_mov_b64 s[8:9], 0x30101100
	global_load_lds_dwordx4 v[40:41], off
	v_lshl_add_u64 v[40:41], v[38:39], 0, s[8:9]
	s_add_i32 m0, s10, 0x8000
	s_mov_b64 s[8:9], 0x30141100
	global_load_lds_dwordx4 v[40:41], off
	v_lshl_add_u64 v[40:41], v[38:39], 0, s[8:9]
	s_add_i32 m0, s10, 0xa000
	s_mov_b64 s[8:9], 0x30181100
	global_load_lds_dwordx4 v[40:41], off
	v_lshl_add_u64 v[40:41], v[38:39], 0, s[8:9]
	s_add_i32 m0, s10, 0xc000
	s_mov_b64 s[8:9], 0x301c1100
	s_add_i32 s5, s5, 0
	global_load_lds_dwordx4 v[40:41], off
	v_lshl_add_u64 v[38:39], v[38:39], 0, s[8:9]
	s_add_i32 m0, s10, 0xe000
	v_add_u32_e32 v48, s5, v147
	global_load_lds_dwordx4 v[38:39], off
	v_add_u32_e32 v49, s5, v159
	ds_read_b64_tr_b16 v[40:41], v48
	ds_read_b64_tr_b16 v[42:43], v49
	ds_read_b64_tr_b16 v[44:45], v48 offset:8192
	ds_read_b64_tr_b16 v[46:47], v49 offset:8192
	s_waitcnt lgkmcnt(0)
	v_mfma_f32_16x16x32_bf16 v[40:43], v[40:43], v[24:27], 0
	v_lshl_add_u64 v[38:39], v[36:37], 0, s[6:7]
	s_add_u32 s6, s6, 0x100
	s_addc_u32 s7, s7, 0
	v_mfma_f32_16x16x32_bf16 v[40:43], v[44:47], v[28:31], v[40:43]
	ds_read_b64_tr_b16 v[44:45], v48 offset:16384
	ds_read_b64_tr_b16 v[46:47], v49 offset:16384
	s_cmpk_lg_i32 s6, 0x300
	s_waitcnt lgkmcnt(0)
	v_mfma_f32_16x16x32_bf16 v[40:43], v[44:47], v[20:23], v[40:43]
	ds_read_b64_tr_b16 v[44:45], v48 offset:24576
	ds_read_b64_tr_b16 v[46:47], v49 offset:24576
	s_waitcnt lgkmcnt(0)
	v_mfma_f32_16x16x32_bf16 v[40:43], v[44:47], v[16:19], v[40:43]
	ds_read_b64_tr_b16 v[44:45], v48 offset:32768
	ds_read_b64_tr_b16 v[46:47], v49 offset:32768
	s_waitcnt lgkmcnt(0)
	v_mfma_f32_16x16x32_bf16 v[40:43], v[44:47], v[4:7], v[40:43]
	ds_read_b64_tr_b16 v[44:45], v48 offset:40960
	ds_read_b64_tr_b16 v[46:47], v49 offset:40960
	s_waitcnt lgkmcnt(0)
	v_mfma_f32_16x16x32_bf16 v[40:43], v[44:47], v[8:11], v[40:43]
	ds_read_b64_tr_b16 v[44:45], v48 offset:49152
	ds_read_b64_tr_b16 v[46:47], v49 offset:49152
	s_waitcnt lgkmcnt(0)
	v_mfma_f32_16x16x32_bf16 v[40:43], v[44:47], v[12:15], v[40:43]
	ds_read_b64_tr_b16 v[44:45], v48 offset:57344
	ds_read_b64_tr_b16 v[46:47], v49 offset:57344
	v_add_u32_e32 v48, s5, v148
	v_add_u32_e32 v49, s5, v160
	s_waitcnt lgkmcnt(0)
	v_mfma_f32_16x16x32_bf16 v[40:43], v[44:47], v[0:3], v[40:43]
	s_nop 7
	v_pk_mul_f32 v[40:41], v[32:33], v[40:41]
	v_pk_mul_f32 v[42:43], v[32:33], v[42:43]
	v_cvt_pk_bf16_f32 v40, v40, v41
	v_cvt_pk_bf16_f32 v41, v42, v43
	global_store_dwordx2 v[38:39], v[40:41], off offset:-128
	ds_read_b64_tr_b16 v[40:41], v48
	ds_read_b64_tr_b16 v[42:43], v49
	ds_read_b64_tr_b16 v[44:45], v48 offset:8192
	ds_read_b64_tr_b16 v[46:47], v49 offset:8192
	s_waitcnt lgkmcnt(0)
	v_mfma_f32_16x16x32_bf16 v[40:43], v[40:43], v[24:27], 0
	v_mfma_f32_16x16x32_bf16 v[40:43], v[44:47], v[28:31], v[40:43]
	ds_read_b64_tr_b16 v[44:45], v48 offset:16384
	ds_read_b64_tr_b16 v[46:47], v49 offset:16384
	s_waitcnt lgkmcnt(0)
	v_mfma_f32_16x16x32_bf16 v[40:43], v[44:47], v[20:23], v[40:43]
	ds_read_b64_tr_b16 v[44:45], v48 offset:24576
	ds_read_b64_tr_b16 v[46:47], v49 offset:24576
	s_waitcnt lgkmcnt(0)
	v_mfma_f32_16x16x32_bf16 v[40:43], v[44:47], v[16:19], v[40:43]
	ds_read_b64_tr_b16 v[44:45], v48 offset:32768
	ds_read_b64_tr_b16 v[46:47], v49 offset:32768
	s_waitcnt lgkmcnt(0)
	v_mfma_f32_16x16x32_bf16 v[40:43], v[44:47], v[4:7], v[40:43]
	ds_read_b64_tr_b16 v[44:45], v48 offset:40960
	ds_read_b64_tr_b16 v[46:47], v49 offset:40960
	s_waitcnt lgkmcnt(0)
	v_mfma_f32_16x16x32_bf16 v[40:43], v[44:47], v[8:11], v[40:43]
	ds_read_b64_tr_b16 v[44:45], v48 offset:49152
	ds_read_b64_tr_b16 v[46:47], v49 offset:49152
	s_waitcnt lgkmcnt(0)
	v_mfma_f32_16x16x32_bf16 v[40:43], v[44:47], v[12:15], v[40:43]
	ds_read_b64_tr_b16 v[44:45], v48 offset:57344
	ds_read_b64_tr_b16 v[46:47], v49 offset:57344
	v_add_u32_e32 v48, s5, v149
	v_add_u32_e32 v49, s5, v161
	s_waitcnt lgkmcnt(0)
	v_mfma_f32_16x16x32_bf16 v[40:43], v[44:47], v[0:3], v[40:43]
	s_nop 7
	v_pk_mul_f32 v[40:41], v[32:33], v[40:41]
	v_pk_mul_f32 v[42:43], v[32:33], v[42:43]
	v_cvt_pk_bf16_f32 v40, v40, v41
	v_cvt_pk_bf16_f32 v41, v42, v43
	global_store_dwordx2 v[38:39], v[40:41], off offset:-96
	ds_read_b64_tr_b16 v[40:41], v48
	ds_read_b64_tr_b16 v[42:43], v49
	ds_read_b64_tr_b16 v[44:45], v48 offset:8192
	ds_read_b64_tr_b16 v[46:47], v49 offset:8192
	s_waitcnt lgkmcnt(0)
	v_mfma_f32_16x16x32_bf16 v[40:43], v[40:43], v[24:27], 0
	v_mfma_f32_16x16x32_bf16 v[40:43], v[44:47], v[28:31], v[40:43]
	ds_read_b64_tr_b16 v[44:45], v48 offset:16384
	ds_read_b64_tr_b16 v[46:47], v49 offset:16384
	s_waitcnt lgkmcnt(0)
	v_mfma_f32_16x16x32_bf16 v[40:43], v[44:47], v[20:23], v[40:43]
	ds_read_b64_tr_b16 v[44:45], v48 offset:24576
	ds_read_b64_tr_b16 v[46:47], v49 offset:24576
	s_waitcnt lgkmcnt(0)
	v_mfma_f32_16x16x32_bf16 v[40:43], v[44:47], v[16:19], v[40:43]
	ds_read_b64_tr_b16 v[44:45], v48 offset:32768
	ds_read_b64_tr_b16 v[46:47], v49 offset:32768
	s_waitcnt lgkmcnt(0)
	v_mfma_f32_16x16x32_bf16 v[40:43], v[44:47], v[4:7], v[40:43]
	ds_read_b64_tr_b16 v[44:45], v48 offset:40960
	ds_read_b64_tr_b16 v[46:47], v49 offset:40960
	s_waitcnt lgkmcnt(0)
	v_mfma_f32_16x16x32_bf16 v[40:43], v[44:47], v[8:11], v[40:43]
	ds_read_b64_tr_b16 v[44:45], v48 offset:49152
	ds_read_b64_tr_b16 v[46:47], v49 offset:49152
	s_waitcnt lgkmcnt(0)
	v_mfma_f32_16x16x32_bf16 v[40:43], v[44:47], v[12:15], v[40:43]
	ds_read_b64_tr_b16 v[44:45], v48 offset:57344
	ds_read_b64_tr_b16 v[46:47], v49 offset:57344
	v_add_u32_e32 v48, s5, v150
	v_add_u32_e32 v49, s5, v162
	s_waitcnt lgkmcnt(0)
	v_mfma_f32_16x16x32_bf16 v[40:43], v[44:47], v[0:3], v[40:43]
	s_nop 7
	v_pk_mul_f32 v[40:41], v[32:33], v[40:41]
	v_pk_mul_f32 v[42:43], v[32:33], v[42:43]
	v_cvt_pk_bf16_f32 v40, v40, v41
	v_cvt_pk_bf16_f32 v41, v42, v43
	global_store_dwordx2 v[38:39], v[40:41], off offset:-64
	ds_read_b64_tr_b16 v[40:41], v48
	ds_read_b64_tr_b16 v[42:43], v49
	ds_read_b64_tr_b16 v[44:45], v48 offset:8192
	ds_read_b64_tr_b16 v[46:47], v49 offset:8192
	s_waitcnt lgkmcnt(0)
	v_mfma_f32_16x16x32_bf16 v[40:43], v[40:43], v[24:27], 0
	v_mfma_f32_16x16x32_bf16 v[40:43], v[44:47], v[28:31], v[40:43]
	ds_read_b64_tr_b16 v[44:45], v48 offset:16384
	ds_read_b64_tr_b16 v[46:47], v49 offset:16384
	s_waitcnt lgkmcnt(0)
	v_mfma_f32_16x16x32_bf16 v[40:43], v[44:47], v[20:23], v[40:43]
	ds_read_b64_tr_b16 v[44:45], v48 offset:24576
	ds_read_b64_tr_b16 v[46:47], v49 offset:24576
	s_waitcnt lgkmcnt(0)
	v_mfma_f32_16x16x32_bf16 v[40:43], v[44:47], v[16:19], v[40:43]
	ds_read_b64_tr_b16 v[44:45], v48 offset:32768
	ds_read_b64_tr_b16 v[46:47], v49 offset:32768
	s_waitcnt lgkmcnt(0)
	v_mfma_f32_16x16x32_bf16 v[40:43], v[44:47], v[4:7], v[40:43]
	ds_read_b64_tr_b16 v[44:45], v48 offset:40960
	ds_read_b64_tr_b16 v[46:47], v49 offset:40960
	s_waitcnt lgkmcnt(0)
	v_mfma_f32_16x16x32_bf16 v[40:43], v[44:47], v[8:11], v[40:43]
	ds_read_b64_tr_b16 v[44:45], v48 offset:49152
	ds_read_b64_tr_b16 v[46:47], v49 offset:49152
	s_waitcnt lgkmcnt(0)
	v_mfma_f32_16x16x32_bf16 v[40:43], v[44:47], v[12:15], v[40:43]
	ds_read_b64_tr_b16 v[44:45], v48 offset:57344
	ds_read_b64_tr_b16 v[46:47], v49 offset:57344
	v_add_u32_e32 v48, s5, v151
	v_add_u32_e32 v49, s5, v163
	s_waitcnt lgkmcnt(0)
	v_mfma_f32_16x16x32_bf16 v[40:43], v[44:47], v[0:3], v[40:43]
	s_nop 7
	v_pk_mul_f32 v[40:41], v[32:33], v[40:41]
	v_pk_mul_f32 v[42:43], v[32:33], v[42:43]
	v_cvt_pk_bf16_f32 v40, v40, v41
	v_cvt_pk_bf16_f32 v41, v42, v43
	global_store_dwordx2 v[38:39], v[40:41], off offset:-32
	ds_read_b64_tr_b16 v[40:41], v48
	ds_read_b64_tr_b16 v[42:43], v49
	ds_read_b64_tr_b16 v[44:45], v48 offset:8192
	ds_read_b64_tr_b16 v[46:47], v49 offset:8192
	s_waitcnt lgkmcnt(0)
	v_mfma_f32_16x16x32_bf16 v[40:43], v[40:43], v[24:27], 0
	v_mfma_f32_16x16x32_bf16 v[40:43], v[44:47], v[28:31], v[40:43]
	ds_read_b64_tr_b16 v[44:45], v48 offset:16384
	ds_read_b64_tr_b16 v[46:47], v49 offset:16384
	s_waitcnt lgkmcnt(0)
	v_mfma_f32_16x16x32_bf16 v[40:43], v[44:47], v[20:23], v[40:43]
	ds_read_b64_tr_b16 v[44:45], v48 offset:24576
	ds_read_b64_tr_b16 v[46:47], v49 offset:24576
	s_waitcnt lgkmcnt(0)
	v_mfma_f32_16x16x32_bf16 v[40:43], v[44:47], v[16:19], v[40:43]
	ds_read_b64_tr_b16 v[44:45], v48 offset:32768
	ds_read_b64_tr_b16 v[46:47], v49 offset:32768
	s_waitcnt lgkmcnt(0)
	v_mfma_f32_16x16x32_bf16 v[40:43], v[44:47], v[4:7], v[40:43]
	ds_read_b64_tr_b16 v[44:45], v48 offset:40960
	ds_read_b64_tr_b16 v[46:47], v49 offset:40960
	s_waitcnt lgkmcnt(0)
	v_mfma_f32_16x16x32_bf16 v[40:43], v[44:47], v[8:11], v[40:43]
	ds_read_b64_tr_b16 v[44:45], v48 offset:49152
	ds_read_b64_tr_b16 v[46:47], v49 offset:49152
	s_waitcnt lgkmcnt(0)
	v_mfma_f32_16x16x32_bf16 v[40:43], v[44:47], v[12:15], v[40:43]
	ds_read_b64_tr_b16 v[44:45], v48 offset:57344
	ds_read_b64_tr_b16 v[46:47], v49 offset:57344
	v_add_u32_e32 v48, s5, v152
	v_add_u32_e32 v49, s5, v164
	s_waitcnt lgkmcnt(0)
	v_mfma_f32_16x16x32_bf16 v[40:43], v[44:47], v[0:3], v[40:43]
	s_nop 7
	v_pk_mul_f32 v[40:41], v[32:33], v[40:41]
	v_pk_mul_f32 v[42:43], v[32:33], v[42:43]
	v_cvt_pk_bf16_f32 v40, v40, v41
	v_cvt_pk_bf16_f32 v41, v42, v43
	global_store_dwordx2 v[38:39], v[40:41], off
	ds_read_b64_tr_b16 v[40:41], v48
	ds_read_b64_tr_b16 v[42:43], v49
	ds_read_b64_tr_b16 v[44:45], v48 offset:8192
	ds_read_b64_tr_b16 v[46:47], v49 offset:8192
	s_waitcnt lgkmcnt(0)
	v_mfma_f32_16x16x32_bf16 v[40:43], v[40:43], v[24:27], 0
	v_mfma_f32_16x16x32_bf16 v[40:43], v[44:47], v[28:31], v[40:43]
	ds_read_b64_tr_b16 v[44:45], v48 offset:16384
	ds_read_b64_tr_b16 v[46:47], v49 offset:16384
	s_waitcnt lgkmcnt(0)
	v_mfma_f32_16x16x32_bf16 v[40:43], v[44:47], v[20:23], v[40:43]
	ds_read_b64_tr_b16 v[44:45], v48 offset:24576
	ds_read_b64_tr_b16 v[46:47], v49 offset:24576
	s_waitcnt lgkmcnt(0)
	v_mfma_f32_16x16x32_bf16 v[40:43], v[44:47], v[16:19], v[40:43]
	ds_read_b64_tr_b16 v[44:45], v48 offset:32768
	ds_read_b64_tr_b16 v[46:47], v49 offset:32768
	s_waitcnt lgkmcnt(0)
	v_mfma_f32_16x16x32_bf16 v[40:43], v[44:47], v[4:7], v[40:43]
	ds_read_b64_tr_b16 v[44:45], v48 offset:40960
	ds_read_b64_tr_b16 v[46:47], v49 offset:40960
	s_waitcnt lgkmcnt(0)
	v_mfma_f32_16x16x32_bf16 v[40:43], v[44:47], v[8:11], v[40:43]
	ds_read_b64_tr_b16 v[44:45], v48 offset:49152
	ds_read_b64_tr_b16 v[46:47], v49 offset:49152
	s_waitcnt lgkmcnt(0)
	v_mfma_f32_16x16x32_bf16 v[40:43], v[44:47], v[12:15], v[40:43]
	ds_read_b64_tr_b16 v[44:45], v48 offset:57344
	ds_read_b64_tr_b16 v[46:47], v49 offset:57344
	v_add_u32_e32 v48, s5, v153
	v_add_u32_e32 v49, s5, v165
	s_waitcnt lgkmcnt(0)
	v_mfma_f32_16x16x32_bf16 v[40:43], v[44:47], v[0:3], v[40:43]
	s_nop 7
	v_pk_mul_f32 v[40:41], v[32:33], v[40:41]
	v_pk_mul_f32 v[42:43], v[32:33], v[42:43]
	v_cvt_pk_bf16_f32 v40, v40, v41
	v_cvt_pk_bf16_f32 v41, v42, v43
	global_store_dwordx2 v[38:39], v[40:41], off offset:32
	ds_read_b64_tr_b16 v[40:41], v48
	ds_read_b64_tr_b16 v[42:43], v49
	ds_read_b64_tr_b16 v[44:45], v48 offset:8192
	ds_read_b64_tr_b16 v[46:47], v49 offset:8192
	s_waitcnt lgkmcnt(0)
	v_mfma_f32_16x16x32_bf16 v[40:43], v[40:43], v[24:27], 0
	v_mfma_f32_16x16x32_bf16 v[40:43], v[44:47], v[28:31], v[40:43]
	ds_read_b64_tr_b16 v[44:45], v48 offset:16384
	ds_read_b64_tr_b16 v[46:47], v49 offset:16384
	s_waitcnt lgkmcnt(0)
	v_mfma_f32_16x16x32_bf16 v[40:43], v[44:47], v[20:23], v[40:43]
	ds_read_b64_tr_b16 v[44:45], v48 offset:24576
	ds_read_b64_tr_b16 v[46:47], v49 offset:24576
	s_waitcnt lgkmcnt(0)
	v_mfma_f32_16x16x32_bf16 v[40:43], v[44:47], v[16:19], v[40:43]
	ds_read_b64_tr_b16 v[44:45], v48 offset:32768
	ds_read_b64_tr_b16 v[46:47], v49 offset:32768
	s_waitcnt lgkmcnt(0)
	v_mfma_f32_16x16x32_bf16 v[40:43], v[44:47], v[4:7], v[40:43]
	ds_read_b64_tr_b16 v[44:45], v48 offset:40960
	ds_read_b64_tr_b16 v[46:47], v49 offset:40960
	s_waitcnt lgkmcnt(0)
	v_mfma_f32_16x16x32_bf16 v[40:43], v[44:47], v[8:11], v[40:43]
	ds_read_b64_tr_b16 v[44:45], v48 offset:49152
	ds_read_b64_tr_b16 v[46:47], v49 offset:49152
	s_waitcnt lgkmcnt(0)
	v_mfma_f32_16x16x32_bf16 v[40:43], v[44:47], v[12:15], v[40:43]
	ds_read_b64_tr_b16 v[44:45], v48 offset:57344
	ds_read_b64_tr_b16 v[46:47], v49 offset:57344
	v_add_u32_e32 v48, s5, v154
	v_add_u32_e32 v49, s5, v166
	s_waitcnt lgkmcnt(0)
	v_mfma_f32_16x16x32_bf16 v[40:43], v[44:47], v[0:3], v[40:43]
	s_nop 7
	v_pk_mul_f32 v[40:41], v[32:33], v[40:41]
	v_pk_mul_f32 v[42:43], v[32:33], v[42:43]
	v_cvt_pk_bf16_f32 v40, v40, v41
	v_cvt_pk_bf16_f32 v41, v42, v43
	global_store_dwordx2 v[38:39], v[40:41], off offset:64
	ds_read_b64_tr_b16 v[40:41], v48
	ds_read_b64_tr_b16 v[42:43], v49
	ds_read_b64_tr_b16 v[44:45], v48 offset:8192
	ds_read_b64_tr_b16 v[46:47], v49 offset:8192
	s_waitcnt lgkmcnt(0)
	v_mfma_f32_16x16x32_bf16 v[40:43], v[40:43], v[24:27], 0
	v_mfma_f32_16x16x32_bf16 v[40:43], v[44:47], v[28:31], v[40:43]
	ds_read_b64_tr_b16 v[44:45], v48 offset:16384
	ds_read_b64_tr_b16 v[46:47], v49 offset:16384
	s_waitcnt lgkmcnt(0)
	v_mfma_f32_16x16x32_bf16 v[40:43], v[44:47], v[20:23], v[40:43]
	ds_read_b64_tr_b16 v[44:45], v48 offset:24576
	ds_read_b64_tr_b16 v[46:47], v49 offset:24576
	s_waitcnt lgkmcnt(0)
	v_mfma_f32_16x16x32_bf16 v[40:43], v[44:47], v[16:19], v[40:43]
	ds_read_b64_tr_b16 v[44:45], v48 offset:32768
	ds_read_b64_tr_b16 v[46:47], v49 offset:32768
	s_waitcnt lgkmcnt(0)
	v_mfma_f32_16x16x32_bf16 v[40:43], v[44:47], v[4:7], v[40:43]
	ds_read_b64_tr_b16 v[44:45], v48 offset:40960
	ds_read_b64_tr_b16 v[46:47], v49 offset:40960
	s_waitcnt lgkmcnt(0)
	v_mfma_f32_16x16x32_bf16 v[40:43], v[44:47], v[8:11], v[40:43]
	ds_read_b64_tr_b16 v[44:45], v48 offset:49152
	ds_read_b64_tr_b16 v[46:47], v49 offset:49152
	s_waitcnt lgkmcnt(0)
	v_mfma_f32_16x16x32_bf16 v[40:43], v[44:47], v[12:15], v[40:43]
	ds_read_b64_tr_b16 v[44:45], v48 offset:57344
	ds_read_b64_tr_b16 v[46:47], v49 offset:57344
	s_waitcnt lgkmcnt(0)
	v_mfma_f32_16x16x32_bf16 v[40:43], v[44:47], v[0:3], v[40:43]
	s_nop 7
	v_pk_mul_f32 v[40:41], v[32:33], v[40:41]
	v_pk_mul_f32 v[42:43], v[32:33], v[42:43]
	v_cvt_pk_bf16_f32 v40, v40, v41
	v_cvt_pk_bf16_f32 v41, v42, v43
	global_store_dwordx2 v[38:39], v[40:41], off offset:96
	s_waitcnt vmcnt(0)
	s_waitcnt vmcnt(0)
	s_barrier
	s_cbranch_scc1 .LBB0_861
	v_add_u32_e32 v50, s16, v147
	ds_read_b64_tr_b16 v[34:35], v50
	v_add_u32_e32 v52, s16, v159
	ds_read_b64_tr_b16 v[36:37], v52
	ds_read_b64_tr_b16 v[40:41], v52 offset:8192
	ds_read_b64_tr_b16 v[38:39], v50 offset:8192
	ds_read_b64_tr_b16 v[42:43], v50 offset:16384
	ds_read_b64_tr_b16 v[46:47], v50 offset:24576
	ds_read_b64_tr_b16 v[44:45], v52 offset:16384
	ds_read_b64_tr_b16 v[48:49], v52 offset:24576
	s_lshl_b32 s0, s22, 1
	v_mov_b32_e32 v135, v129
	v_add_u32_e32 v54, s16, v148
	v_add_u32_e32 v55, s16, v160
	v_add_u32_e32 v56, s16, v149
	v_add_u32_e32 v57, s16, v161
	s_waitcnt lgkmcnt(6)
	v_mfma_f32_16x16x32_bf16 v[34:37], v[34:37], v[24:27], 0
	s_add_i32 s98, s98, s94
	s_nop 0
	s_nop 0
	s_waitcnt lgkmcnt(4)
	v_mfma_f32_16x16x32_bf16 v[34:37], v[38:41], v[28:31], v[34:37]
	ds_read_b64_tr_b16 v[38:39], v50 offset:32768
	s_cmpk_gt_i32 s98, 0x1ff
	s_waitcnt lgkmcnt(2)
	v_mfma_f32_16x16x32_bf16 v[34:37], v[42:45], v[20:23], v[34:37]
	ds_read_b64_tr_b16 v[40:41], v52 offset:32768
	ds_read_b64_tr_b16 v[44:45], v52 offset:40960
	s_waitcnt lgkmcnt(3)
	v_mfma_f32_16x16x32_bf16 v[34:37], v[46:49], v[16:19], v[34:37]
	ds_read_b64_tr_b16 v[42:43], v50 offset:40960
	ds_read_b64_tr_b16 v[46:47], v50 offset:49152
	ds_read_b64_tr_b16 v[50:51], v50 offset:57344
	ds_read_b64_tr_b16 v[48:49], v52 offset:49152
	ds_read_b64_tr_b16 v[52:53], v52 offset:57344
	s_waitcnt lgkmcnt(6)
	v_mfma_f32_16x16x32_bf16 v[34:37], v[38:41], v[4:7], v[34:37]
	v_lshl_add_u64 v[40:41], v[136:137], 1, s[60:61]
	s_waitcnt lgkmcnt(4)
	v_mfma_f32_16x16x32_bf16 v[34:37], v[42:45], v[8:11], v[34:37]
	s_waitcnt lgkmcnt(1)
	v_mfma_f32_16x16x32_bf16 v[36:39], v[46:49], v[12:15], v[34:37]
	s_waitcnt lgkmcnt(0)
	v_mfma_f32_16x16x32_bf16 v[36:39], v[50:53], v[0:3], v[36:39]
	s_nop 3
	v_lshl_add_u64 v[34:35], v[40:41], 0, s[0:1]
	v_lshl_add_u64 v[34:35], v[34:35], 0, v[134:135]
	s_nop 1
	v_pk_mul_f32 v[36:37], v[32:33], v[36:37]
	v_pk_mul_f32 v[38:39], v[32:33], v[38:39]
	v_cvt_pk_bf16_f32 v36, v36, v37
	v_cvt_pk_bf16_f32 v37, v38, v39
	global_store_dwordx2 v[34:35], v[36:37], off offset:768
	ds_read_b64_tr_b16 v[36:37], v54
	ds_read_b64_tr_b16 v[38:39], v55
	ds_read_b64_tr_b16 v[42:43], v55 offset:8192
	ds_read_b64_tr_b16 v[40:41], v54 offset:8192
	ds_read_b64_tr_b16 v[44:45], v54 offset:16384
	ds_read_b64_tr_b16 v[48:49], v54 offset:24576
	ds_read_b64_tr_b16 v[46:47], v55 offset:16384
	ds_read_b64_tr_b16 v[50:51], v55 offset:24576
	s_waitcnt lgkmcnt(6)
	v_mfma_f32_16x16x32_bf16 v[36:39], v[36:39], v[24:27], 0
	s_waitcnt lgkmcnt(4)
	v_mfma_f32_16x16x32_bf16 v[36:39], v[40:43], v[28:31], v[36:39]
	ds_read_b64_tr_b16 v[40:41], v54 offset:32768
	s_waitcnt lgkmcnt(2)
	v_mfma_f32_16x16x32_bf16 v[36:39], v[44:47], v[20:23], v[36:39]
	ds_read_b64_tr_b16 v[42:43], v55 offset:32768
	ds_read_b64_tr_b16 v[46:47], v55 offset:40960
	s_waitcnt lgkmcnt(3)
	v_mfma_f32_16x16x32_bf16 v[36:39], v[48:51], v[16:19], v[36:39]
	ds_read_b64_tr_b16 v[44:45], v54 offset:40960
	ds_read_b64_tr_b16 v[48:49], v54 offset:49152
	ds_read_b64_tr_b16 v[52:53], v54 offset:57344
	ds_read_b64_tr_b16 v[50:51], v55 offset:49152
	ds_read_b64_tr_b16 v[54:55], v55 offset:57344
	s_waitcnt lgkmcnt(6)
	v_mfma_f32_16x16x32_bf16 v[36:39], v[40:43], v[4:7], v[36:39]
	s_waitcnt lgkmcnt(4)
	v_mfma_f32_16x16x32_bf16 v[36:39], v[44:47], v[8:11], v[36:39]
	s_waitcnt lgkmcnt(1)
	v_mfma_f32_16x16x32_bf16 v[36:39], v[48:51], v[12:15], v[36:39]
	s_waitcnt lgkmcnt(0)
	v_mfma_f32_16x16x32_bf16 v[36:39], v[52:55], v[0:3], v[36:39]
	s_nop 7
	v_pk_mul_f32 v[36:37], v[32:33], v[36:37]
	v_pk_mul_f32 v[38:39], v[32:33], v[38:39]
	v_cvt_pk_bf16_f32 v36, v36, v37
	v_cvt_pk_bf16_f32 v37, v38, v39
	global_store_dwordx2 v[34:35], v[36:37], off offset:800
	ds_read_b64_tr_b16 v[36:37], v56
	ds_read_b64_tr_b16 v[38:39], v57
	ds_read_b64_tr_b16 v[42:43], v57 offset:8192
	ds_read_b64_tr_b16 v[40:41], v56 offset:8192
	ds_read_b64_tr_b16 v[44:45], v56 offset:16384
	ds_read_b64_tr_b16 v[48:49], v56 offset:24576
	ds_read_b64_tr_b16 v[46:47], v57 offset:16384
	ds_read_b64_tr_b16 v[50:51], v57 offset:24576
	s_waitcnt lgkmcnt(6)
	v_mfma_f32_16x16x32_bf16 v[36:39], v[36:39], v[24:27], 0
	s_waitcnt lgkmcnt(4)
	v_mfma_f32_16x16x32_bf16 v[36:39], v[40:43], v[28:31], v[36:39]
	ds_read_b64_tr_b16 v[40:41], v56 offset:32768
	s_waitcnt lgkmcnt(2)
	v_mfma_f32_16x16x32_bf16 v[36:39], v[44:47], v[20:23], v[36:39]
	ds_read_b64_tr_b16 v[42:43], v57 offset:32768
	ds_read_b64_tr_b16 v[46:47], v57 offset:40960
	s_waitcnt lgkmcnt(3)
	v_mfma_f32_16x16x32_bf16 v[36:39], v[48:51], v[16:19], v[36:39]
	ds_read_b64_tr_b16 v[44:45], v56 offset:40960
	ds_read_b64_tr_b16 v[48:49], v56 offset:49152
	ds_read_b64_tr_b16 v[52:53], v56 offset:57344
	ds_read_b64_tr_b16 v[50:51], v57 offset:49152
	ds_read_b64_tr_b16 v[54:55], v57 offset:57344
	v_add_u32_e32 v56, s16, v150
	v_add_u32_e32 v57, s16, v162
	s_waitcnt lgkmcnt(6)
	v_mfma_f32_16x16x32_bf16 v[36:39], v[40:43], v[4:7], v[36:39]
	s_waitcnt lgkmcnt(4)
	v_mfma_f32_16x16x32_bf16 v[36:39], v[44:47], v[8:11], v[36:39]
	s_waitcnt lgkmcnt(1)
	v_mfma_f32_16x16x32_bf16 v[36:39], v[48:51], v[12:15], v[36:39]
	s_waitcnt lgkmcnt(0)
	v_mfma_f32_16x16x32_bf16 v[36:39], v[52:55], v[0:3], v[36:39]
	s_nop 7
	v_pk_mul_f32 v[36:37], v[32:33], v[36:37]
	v_pk_mul_f32 v[38:39], v[32:33], v[38:39]
	v_cvt_pk_bf16_f32 v36, v36, v37
	v_cvt_pk_bf16_f32 v37, v38, v39
	global_store_dwordx2 v[34:35], v[36:37], off offset:832
	ds_read_b64_tr_b16 v[36:37], v56
	ds_read_b64_tr_b16 v[38:39], v57
	ds_read_b64_tr_b16 v[42:43], v57 offset:8192
	ds_read_b64_tr_b16 v[40:41], v56 offset:8192
	ds_read_b64_tr_b16 v[44:45], v56 offset:16384
	ds_read_b64_tr_b16 v[48:49], v56 offset:24576
	ds_read_b64_tr_b16 v[46:47], v57 offset:16384
	ds_read_b64_tr_b16 v[50:51], v57 offset:24576
	s_waitcnt lgkmcnt(6)
	v_mfma_f32_16x16x32_bf16 v[36:39], v[36:39], v[24:27], 0
	s_waitcnt lgkmcnt(4)
	v_mfma_f32_16x16x32_bf16 v[36:39], v[40:43], v[28:31], v[36:39]
	ds_read_b64_tr_b16 v[40:41], v56 offset:32768
	s_waitcnt lgkmcnt(2)
	v_mfma_f32_16x16x32_bf16 v[36:39], v[44:47], v[20:23], v[36:39]
	ds_read_b64_tr_b16 v[42:43], v57 offset:32768
	ds_read_b64_tr_b16 v[46:47], v57 offset:40960
	s_waitcnt lgkmcnt(3)
	v_mfma_f32_16x16x32_bf16 v[36:39], v[48:51], v[16:19], v[36:39]
	ds_read_b64_tr_b16 v[44:45], v56 offset:40960
	ds_read_b64_tr_b16 v[48:49], v56 offset:49152
	ds_read_b64_tr_b16 v[52:53], v56 offset:57344
	ds_read_b64_tr_b16 v[50:51], v57 offset:49152
	ds_read_b64_tr_b16 v[54:55], v57 offset:57344
	v_add_u32_e32 v56, s16, v151
	v_add_u32_e32 v57, s16, v163
	s_waitcnt lgkmcnt(6)
	v_mfma_f32_16x16x32_bf16 v[36:39], v[40:43], v[4:7], v[36:39]
	s_waitcnt lgkmcnt(4)
	v_mfma_f32_16x16x32_bf16 v[36:39], v[44:47], v[8:11], v[36:39]
	s_waitcnt lgkmcnt(1)
	v_mfma_f32_16x16x32_bf16 v[36:39], v[48:51], v[12:15], v[36:39]
	s_waitcnt lgkmcnt(0)
	v_mfma_f32_16x16x32_bf16 v[36:39], v[52:55], v[0:3], v[36:39]
	s_nop 7
	v_pk_mul_f32 v[36:37], v[32:33], v[36:37]
	v_pk_mul_f32 v[38:39], v[32:33], v[38:39]
	v_cvt_pk_bf16_f32 v36, v36, v37
	v_cvt_pk_bf16_f32 v37, v38, v39
	global_store_dwordx2 v[34:35], v[36:37], off offset:864
	ds_read_b64_tr_b16 v[36:37], v56
	ds_read_b64_tr_b16 v[38:39], v57
	ds_read_b64_tr_b16 v[42:43], v57 offset:8192
	ds_read_b64_tr_b16 v[40:41], v56 offset:8192
	ds_read_b64_tr_b16 v[44:45], v56 offset:16384
	ds_read_b64_tr_b16 v[48:49], v56 offset:24576
	ds_read_b64_tr_b16 v[46:47], v57 offset:16384
	ds_read_b64_tr_b16 v[50:51], v57 offset:24576
	s_waitcnt lgkmcnt(6)
	v_mfma_f32_16x16x32_bf16 v[36:39], v[36:39], v[24:27], 0
	s_waitcnt lgkmcnt(4)
	v_mfma_f32_16x16x32_bf16 v[36:39], v[40:43], v[28:31], v[36:39]
	ds_read_b64_tr_b16 v[40:41], v56 offset:32768
	s_waitcnt lgkmcnt(2)
	v_mfma_f32_16x16x32_bf16 v[36:39], v[44:47], v[20:23], v[36:39]
	ds_read_b64_tr_b16 v[42:43], v57 offset:32768
	ds_read_b64_tr_b16 v[46:47], v57 offset:40960
	s_waitcnt lgkmcnt(3)
	v_mfma_f32_16x16x32_bf16 v[36:39], v[48:51], v[16:19], v[36:39]
	ds_read_b64_tr_b16 v[44:45], v56 offset:40960
	ds_read_b64_tr_b16 v[48:49], v56 offset:49152
	ds_read_b64_tr_b16 v[52:53], v56 offset:57344
	ds_read_b64_tr_b16 v[50:51], v57 offset:49152
	ds_read_b64_tr_b16 v[54:55], v57 offset:57344
	v_add_u32_e32 v56, s16, v152
	v_add_u32_e32 v57, s16, v164
	s_waitcnt lgkmcnt(6)
	v_mfma_f32_16x16x32_bf16 v[36:39], v[40:43], v[4:7], v[36:39]
	s_waitcnt lgkmcnt(4)
	v_mfma_f32_16x16x32_bf16 v[36:39], v[44:47], v[8:11], v[36:39]
	s_waitcnt lgkmcnt(1)
	v_mfma_f32_16x16x32_bf16 v[36:39], v[48:51], v[12:15], v[36:39]
	s_waitcnt lgkmcnt(0)
	v_mfma_f32_16x16x32_bf16 v[36:39], v[52:55], v[0:3], v[36:39]
	s_nop 7
	v_pk_mul_f32 v[36:37], v[32:33], v[36:37]
	v_pk_mul_f32 v[38:39], v[32:33], v[38:39]
	v_cvt_pk_bf16_f32 v36, v36, v37
	v_cvt_pk_bf16_f32 v37, v38, v39
	global_store_dwordx2 v[34:35], v[36:37], off offset:896
	ds_read_b64_tr_b16 v[36:37], v56
	ds_read_b64_tr_b16 v[38:39], v57
	ds_read_b64_tr_b16 v[42:43], v57 offset:8192
	ds_read_b64_tr_b16 v[40:41], v56 offset:8192
	ds_read_b64_tr_b16 v[44:45], v56 offset:16384
	ds_read_b64_tr_b16 v[48:49], v56 offset:24576
	ds_read_b64_tr_b16 v[46:47], v57 offset:16384
	ds_read_b64_tr_b16 v[50:51], v57 offset:24576
	s_waitcnt lgkmcnt(6)
	v_mfma_f32_16x16x32_bf16 v[36:39], v[36:39], v[24:27], 0
	s_waitcnt lgkmcnt(4)
	v_mfma_f32_16x16x32_bf16 v[36:39], v[40:43], v[28:31], v[36:39]
	ds_read_b64_tr_b16 v[40:41], v56 offset:32768
	s_waitcnt lgkmcnt(2)
	v_mfma_f32_16x16x32_bf16 v[36:39], v[44:47], v[20:23], v[36:39]
	ds_read_b64_tr_b16 v[42:43], v57 offset:32768
	ds_read_b64_tr_b16 v[46:47], v57 offset:40960
	s_waitcnt lgkmcnt(3)
	v_mfma_f32_16x16x32_bf16 v[36:39], v[48:51], v[16:19], v[36:39]
	ds_read_b64_tr_b16 v[44:45], v56 offset:40960
	ds_read_b64_tr_b16 v[48:49], v56 offset:49152
	ds_read_b64_tr_b16 v[52:53], v56 offset:57344
	ds_read_b64_tr_b16 v[50:51], v57 offset:49152
	ds_read_b64_tr_b16 v[54:55], v57 offset:57344
	v_add_u32_e32 v56, s16, v153
	v_add_u32_e32 v57, s16, v165
	s_waitcnt lgkmcnt(6)
	v_mfma_f32_16x16x32_bf16 v[36:39], v[40:43], v[4:7], v[36:39]
	s_waitcnt lgkmcnt(4)
	v_mfma_f32_16x16x32_bf16 v[36:39], v[44:47], v[8:11], v[36:39]
	s_waitcnt lgkmcnt(1)
	v_mfma_f32_16x16x32_bf16 v[36:39], v[48:51], v[12:15], v[36:39]
	s_waitcnt lgkmcnt(0)
	v_mfma_f32_16x16x32_bf16 v[36:39], v[52:55], v[0:3], v[36:39]
	s_nop 7
	v_pk_mul_f32 v[36:37], v[32:33], v[36:37]
	v_pk_mul_f32 v[38:39], v[32:33], v[38:39]
	v_cvt_pk_bf16_f32 v36, v36, v37
	v_cvt_pk_bf16_f32 v37, v38, v39
	global_store_dwordx2 v[34:35], v[36:37], off offset:928
	ds_read_b64_tr_b16 v[36:37], v56
	ds_read_b64_tr_b16 v[38:39], v57
	ds_read_b64_tr_b16 v[42:43], v57 offset:8192
	ds_read_b64_tr_b16 v[40:41], v56 offset:8192
	ds_read_b64_tr_b16 v[44:45], v56 offset:16384
	ds_read_b64_tr_b16 v[48:49], v56 offset:24576
	ds_read_b64_tr_b16 v[46:47], v57 offset:16384
	ds_read_b64_tr_b16 v[50:51], v57 offset:24576
	s_waitcnt lgkmcnt(6)
	v_mfma_f32_16x16x32_bf16 v[36:39], v[36:39], v[24:27], 0
	s_waitcnt lgkmcnt(4)
	v_mfma_f32_16x16x32_bf16 v[36:39], v[40:43], v[28:31], v[36:39]
	ds_read_b64_tr_b16 v[40:41], v56 offset:32768
	s_waitcnt lgkmcnt(2)
	v_mfma_f32_16x16x32_bf16 v[36:39], v[44:47], v[20:23], v[36:39]
	ds_read_b64_tr_b16 v[42:43], v57 offset:32768
	ds_read_b64_tr_b16 v[46:47], v57 offset:40960
	s_waitcnt lgkmcnt(3)
	v_mfma_f32_16x16x32_bf16 v[36:39], v[48:51], v[16:19], v[36:39]
	ds_read_b64_tr_b16 v[44:45], v56 offset:40960
	ds_read_b64_tr_b16 v[48:49], v56 offset:49152
	ds_read_b64_tr_b16 v[52:53], v56 offset:57344
	ds_read_b64_tr_b16 v[50:51], v57 offset:49152
	ds_read_b64_tr_b16 v[54:55], v57 offset:57344
	v_add_u32_e32 v56, s16, v154
	v_add_u32_e32 v57, s16, v166
	s_waitcnt lgkmcnt(6)
	v_mfma_f32_16x16x32_bf16 v[36:39], v[40:43], v[4:7], v[36:39]
	s_waitcnt lgkmcnt(4)
	v_mfma_f32_16x16x32_bf16 v[36:39], v[44:47], v[8:11], v[36:39]
	s_waitcnt lgkmcnt(1)
	v_mfma_f32_16x16x32_bf16 v[36:39], v[48:51], v[12:15], v[36:39]
	s_waitcnt lgkmcnt(0)
	v_mfma_f32_16x16x32_bf16 v[36:39], v[52:55], v[0:3], v[36:39]
	s_nop 7
	v_pk_mul_f32 v[36:37], v[32:33], v[36:37]
	v_pk_mul_f32 v[38:39], v[32:33], v[38:39]
	v_cvt_pk_bf16_f32 v36, v36, v37
	v_cvt_pk_bf16_f32 v37, v38, v39
	global_store_dwordx2 v[34:35], v[36:37], off offset:960
	ds_read_b64_tr_b16 v[36:37], v56
	ds_read_b64_tr_b16 v[38:39], v57
	ds_read_b64_tr_b16 v[42:43], v57 offset:8192
	ds_read_b64_tr_b16 v[40:41], v56 offset:8192
	ds_read_b64_tr_b16 v[44:45], v56 offset:16384
	ds_read_b64_tr_b16 v[48:49], v56 offset:24576
	ds_read_b64_tr_b16 v[46:47], v57 offset:16384
	ds_read_b64_tr_b16 v[50:51], v57 offset:24576
	s_waitcnt lgkmcnt(6)
	v_mfma_f32_16x16x32_bf16 v[24:27], v[36:39], v[24:27], 0
	s_waitcnt lgkmcnt(4)
	v_mfma_f32_16x16x32_bf16 v[24:27], v[40:43], v[28:31], v[24:27]
	ds_read_b64_tr_b16 v[28:29], v56 offset:32768
	s_waitcnt lgkmcnt(2)
	v_mfma_f32_16x16x32_bf16 v[20:23], v[44:47], v[20:23], v[24:27]
	ds_read_b64_tr_b16 v[30:31], v57 offset:32768
	s_nop 3
	ds_read_b64_tr_b16 v[24:25], v57 offset:40960
	s_waitcnt lgkmcnt(3)
	v_mfma_f32_16x16x32_bf16 v[16:19], v[48:51], v[16:19], v[20:23]
	s_nop 2
	ds_read_b64_tr_b16 v[22:23], v56 offset:40960
	ds_read_b64_tr_b16 v[36:37], v56 offset:49152
	ds_read_b64_tr_b16 v[40:41], v56 offset:57344
	ds_read_b64_tr_b16 v[38:39], v57 offset:49152
	ds_read_b64_tr_b16 v[42:43], v57 offset:57344
	s_waitcnt lgkmcnt(6)
	v_mfma_f32_16x16x32_bf16 v[4:7], v[28:31], v[4:7], v[16:19]
	s_waitcnt lgkmcnt(4)
	v_mfma_f32_16x16x32_bf16 v[4:7], v[22:25], v[8:11], v[4:7]
	s_waitcnt lgkmcnt(1)
	v_mfma_f32_16x16x32_bf16 v[4:7], v[36:39], v[12:15], v[4:7]
	s_waitcnt lgkmcnt(0)
	v_mfma_f32_16x16x32_bf16 v[0:3], v[40:43], v[0:3], v[4:7]
	s_nop 7
	v_pk_mul_f32 v[0:1], v[32:33], v[0:1]
	v_pk_mul_f32 v[2:3], v[32:33], v[2:3]
	v_cvt_pk_bf16_f32 v0, v0, v1
	v_cvt_pk_bf16_f32 v1, v2, v3
	global_store_dwordx2 v[34:35], v[0:1], off offset:992
	s_waitcnt vmcnt(0)
	s_barrier
	s_cbranch_scc0 .LBB0_860

.LBB0_1594:
	s_or_b64 exec, exec, s[0:1]
	v_readlane_b32 s0, v244, 55
	v_readlane_b32 s1, v244, 56
	v_mov_b32_e32 v138, v190
	s_and_b64 vcc, exec, s[0:1]
	s_waitcnt lgkmcnt(0)
	s_barrier
	s_cbranch_vccnz .LBB0_1612
	v_and_b32_e32 v5, 3, v138
	v_lshrrev_b32_e32 v2, 4, v138
	v_or_b32_e32 v9, 4, v5
	v_bfe_u32 v3, v138, 4, 2
	v_bitop3_b32 v10, v2, v138, 3 bitop3:0x28
	v_bitop3_b32 v2, v2, v9, 3 bitop3:0x6c
	v_bfe_u32 v4, v138, 2, 2
	v_bfe_u32 v6, v138, 1, 1
	v_lshlrev_b32_e32 v9, 4, v2
	v_bitop3_b32 v2, v3, v5, 4 bitop3:0x14
	v_lshlrev_b32_e32 v12, 4, v2
	v_bitop3_b32 v2, v4, v6, 4 bitop3:0x36
	v_or_b32_e32 v8, 4, v4
	v_lshlrev_b32_e32 v14, 4, v2
	v_bitop3_b32 v2, v6, v4, 2 bitop3:0x36
	v_lshlrev_b32_e32 v15, 4, v2
	v_bitop3_b32 v2, v6, v8, 2 bitop3:0x36
	v_lshlrev_b32_e32 v16, 4, v2
	v_bitop3_b32 v2, v6, v4, 4 bitop3:0x36
	v_lshlrev_b32_e32 v17, 4, v2
	v_bitop3_b32 v2, v6, v4, 4 bitop3:0x14
	v_lshlrev_b32_e32 v18, 4, v2
	v_bitop3_b32 v2, v6, v4, 6 bitop3:0x36
	v_lshlrev_b32_e32 v19, 4, v2
	v_bitop3_b32 v2, v6, v8, 6 bitop3:0x36
	v_xor_b32_e32 v13, v6, v4
	v_lshlrev_b32_e32 v6, 4, v2
	v_mbcnt_hi_u32_b32 v2, -1, v191
	v_and_b32_e32 v20, 64, v2
	v_cmp_eq_u32_e32 vcc, 0, v3
	v_xor_b32_e32 v8, 16, v2
	v_add_u32_e32 v20, 64, v20
	v_cndmask_b32_e64 v140, 0, 1.0, vcc
	v_cmp_lt_i32_e32 vcc, v8, v20
	v_lshlrev_b32_e32 v141, 3, v138
	v_lshlrev_b32_e32 v0, 3, v3
	v_cndmask_b32_e32 v8, v2, v8, vcc
	v_lshlrev_b32_e32 v142, 2, v8
	v_xor_b32_e32 v8, 32, v2
	v_cmp_lt_i32_e32 vcc, v8, v20
	v_and_b32_e32 v7, 8, v141
	v_bitop3_b32 v11, v3, v5, 4 bitop3:0x36
	v_cndmask_b32_e32 v2, v2, v8, vcc
	v_lshlrev_b32_e32 v8, 7, v4
	v_lshlrev_b32_e32 v143, 2, v2
	v_lshlrev_b32_e32 v2, 2, v3
	v_lshl_or_b32 v3, v3, 10, v8
	v_or3_b32 v6, v3, v6, v7
	v_or3_b32 v8, v3, v14, v7
	v_add_u32_e32 v147, 0xa200, v6
	v_or3_b32 v6, v3, v19, v7
	v_add_u32_e32 v144, 0xa200, v8
	v_or3_b32 v8, v3, v16, v7
	v_add_u32_e32 v148, 0xa000, v6
	v_or3_b32 v6, v3, v17, v7
	v_add_u32_e32 v145, 0xa200, v8
	v_or3_b32 v8, v3, v18, v7
	s_mov_b32 s0, 0xa000
	v_add_u32_e32 v149, 0xa000, v6
	v_or3_b32 v6, v3, v15, v7
	v_lshl_or_b32 v3, v13, 4, v3
	v_or3_b32 v151, v3, v7, s0
	v_lshlrev_b32_e32 v3, 7, v5
	s_movk_i32 s28, 0xa00
	v_and_b32_e32 v139, 15, v138
	v_lshl_or_b32 v3, v4, 10, v3
	s_movk_i32 s0, 0x200
	v_cmp_gt_i32_e64 s[4:5], s28, v138
	v_mov_b32_e32 v1, 0
	v_add_u32_e32 v146, 0xa200, v8
	v_add_u32_e32 v150, 0xa000, v6
	v_or3_b32 v152, v3, v12, s0
	v_or3_b32 v153, v3, v9, s0
	v_lshl_or_b32 v154, v11, 4, v3
	v_lshl_or_b32 v155, v10, 4, v3
	s_lshl_b32 s29, s2, 6
	s_lshl_b32 s30, s94, 6
	v_sub_u32_e32 v156, v0, v139
	s_movk_i32 s31, 0x800
	s_movk_i32 s34, 0x7ff
	s_mov_b32 s35, 0xc2fc0000
	v_lshlrev_b32_e32 v130, 1, v0
	s_mov_b32 s36, 0x14000
	s_mov_b32 s37, 0x28000
	s_movk_i32 s38, 0x81
	s_mov_b32 s39, 0xf149f2ca
	v_lshlrev_b32_e32 v132, 1, v2
	s_mov_b32 s40, 0x10000
	s_mov_b32 s41, 0x20000
	s_mov_b32 s42, 0x30000
	v_mov_b32_e32 v157, 0x42800000
	v_mov_b32_e32 v134, 0x3e000000
	v_mov_b32_e32 v158, 0xf149f2ca
	s_mov_b32 s43, s2
	s_mov_b32 s98, s2
	s_branch .LBB0_1597
.LBB0_1596:
	ds_bpermute_b32 v0, v142, v174
	s_lshl_b64 s[0:1], s[0:1], 23
	s_add_u32 s0, s60, s0
	s_addc_u32 s1, s61, s1
	s_lshl_b32 s8, s10, 1
	s_waitcnt lgkmcnt(0)
	v_add_f32_e32 v0, v174, v0
	s_waitcnt vmcnt(7)
	ds_bpermute_b32 v58, v143, v0
	s_add_u32 s0, s0, s8
	v_mov_b32_e32 v133, v1
	s_addc_u32 s1, s1, 0
	s_add_i32 s98, s98, s94
	s_waitcnt lgkmcnt(0)
	v_add_f32_e32 v0, v0, v58
	v_div_scale_f32 v60, s[8:9], v0, v0, 1.0
	v_rcp_f32_e32 v61, v60
	s_waitcnt vmcnt(6)
	v_div_scale_f32 v62, vcc, 1.0, v0, 1.0
	v_lshl_add_u64 v[58:59], s[0:1], 0, v[132:133]
	v_fma_f32 v63, -v60, v61, 1.0
	v_fmac_f32_e32 v61, v63, v61
	v_mul_f32_e32 v63, v62, v61
	v_fma_f32 v64, -v60, v63, v62
	v_fmac_f32_e32 v63, v64, v61
	v_fma_f32 v60, -v60, v63, v62
	v_div_fmas_f32 v60, v60, v61, v63
	v_div_fixup_f32 v60, v60, v0, 1.0
	v_lshlrev_b32_e32 v0, 12, v160
	v_lshl_add_u64 v[58:59], v[58:59], 0, v[0:1]
	ds_bpermute_b32 v0, v142, v161
	v_pk_mul_f32 v[62:63], v[86:87], v[60:61] op_sel_hi:[1,0]
	v_pk_mul_f32 v[64:65], v[88:89], v[60:61] op_sel_hi:[1,0]
	v_cvt_pk_bf16_f32 v62, v62, v63
	v_cvt_pk_bf16_f32 v63, v64, v65
	s_waitcnt lgkmcnt(0)
	v_add_f32_e32 v0, v161, v0
	global_store_dwordx2 v[58:59], v[62:63], off
	v_pk_mul_f32 v[62:63], v[74:75], v[60:61] op_sel_hi:[1,0]
	v_pk_mul_f32 v[64:65], v[76:77], v[60:61] op_sel_hi:[1,0]
	v_pk_mul_f32 v[54:55], v[54:55], v[60:61] op_sel_hi:[1,0]
	v_pk_mul_f32 v[56:57], v[56:57], v[60:61] op_sel_hi:[1,0]
	ds_bpermute_b32 v61, v143, v0
	v_cvt_pk_bf16_f32 v54, v54, v55
	v_cvt_pk_bf16_f32 v55, v56, v57
	global_store_dwordx2 v[58:59], v[54:55], off offset:64
	s_nop 0
	s_waitcnt lgkmcnt(0)
	v_add_f32_e32 v0, v0, v61
	v_div_scale_f32 v54, s[0:1], v0, v0, 1.0
	v_rcp_f32_e32 v55, v54
	v_pk_mul_f32 v[50:51], v[50:51], v[60:61] op_sel_hi:[1,0]
	v_pk_mul_f32 v[52:53], v[52:53], v[60:61] op_sel_hi:[1,0]
	v_cvt_pk_bf16_f32 v50, v50, v51
	v_cvt_pk_bf16_f32 v51, v52, v53
	global_store_dwordx2 v[58:59], v[50:51], off offset:96
	v_fma_f32 v50, -v54, v55, 1.0
	v_fmac_f32_e32 v55, v50, v55
	v_div_scale_f32 v50, vcc, 1.0, v0, 1.0
	v_mul_f32_e32 v51, v50, v55
	v_fma_f32 v52, -v54, v51, v50
	v_fmac_f32_e32 v51, v52, v55
	v_fma_f32 v50, -v54, v51, v50
	v_div_fmas_f32 v50, v50, v55, v51
	v_div_fixup_f32 v0, v50, v0, 1.0
	v_pk_mul_f32 v[42:43], v[42:43], v[0:1] op_sel_hi:[1,0]
	v_pk_mul_f32 v[44:45], v[44:45], v[0:1] op_sel_hi:[1,0]
	v_cvt_pk_bf16_f32 v42, v42, v43
	v_cvt_pk_bf16_f32 v43, v44, v45
	ds_bpermute_b32 v44, v142, v159
	v_pk_mul_f32 v[46:47], v[46:47], v[0:1] op_sel_hi:[1,0]
	v_pk_mul_f32 v[48:49], v[48:49], v[0:1] op_sel_hi:[1,0]
	v_cvt_pk_bf16_f32 v46, v46, v47
	v_cvt_pk_bf16_f32 v47, v48, v49
	v_add_co_u32_e32 v48, vcc, s40, v58
	v_pk_mul_f32 v[38:39], v[38:39], v[0:1] op_sel_hi:[1,0]
	s_nop 0
	v_addc_co_u32_e32 v49, vcc, 0, v59, vcc
	global_store_dwordx2 v[48:49], v[42:43], off offset:32
	s_waitcnt lgkmcnt(0)
	v_add_f32_e32 v42, v159, v44
	ds_bpermute_b32 v43, v143, v42
	v_pk_mul_f32 v[40:41], v[40:41], v[0:1] op_sel_hi:[1,0]
	v_cvt_pk_bf16_f32 v38, v38, v39
	v_cvt_pk_bf16_f32 v39, v40, v41
	global_store_dwordx2 v[48:49], v[38:39], off offset:64
	s_waitcnt lgkmcnt(0)
	v_add_f32_e32 v38, v42, v43
	v_div_scale_f32 v39, s[0:1], v38, v38, 1.0
	v_rcp_f32_e32 v40, v39
	v_pk_mul_f32 v[34:35], v[34:35], v[0:1] op_sel_hi:[1,0]
	v_pk_mul_f32 v[36:37], v[36:37], v[0:1] op_sel_hi:[1,0]
	v_cvt_pk_bf16_f32 v34, v34, v35
	v_fma_f32 v0, -v39, v40, 1.0
	v_cvt_pk_bf16_f32 v35, v36, v37
	v_fmac_f32_e32 v40, v0, v40
	v_div_scale_f32 v0, vcc, 1.0, v38, 1.0
	global_store_dwordx2 v[48:49], v[34:35], off offset:96
	v_mul_f32_e32 v34, v0, v40
	v_fma_f32 v35, -v39, v34, v0
	v_fmac_f32_e32 v34, v35, v40
	v_fma_f32 v0, -v39, v34, v0
	v_div_fmas_f32 v0, v0, v40, v34
	v_div_fixup_f32 v0, v0, v38, 1.0
	v_pk_mul_f32 v[26:27], v[26:27], v[0:1] op_sel_hi:[1,0]
	v_pk_mul_f32 v[28:29], v[28:29], v[0:1] op_sel_hi:[1,0]
	v_cvt_pk_bf16_f32 v26, v26, v27
	v_cvt_pk_bf16_f32 v27, v28, v29
	ds_bpermute_b32 v28, v142, v131
	v_pk_mul_f32 v[30:31], v[30:31], v[0:1] op_sel_hi:[1,0]
	v_pk_mul_f32 v[32:33], v[32:33], v[0:1] op_sel_hi:[1,0]
	v_cvt_pk_bf16_f32 v30, v30, v31
	v_cvt_pk_bf16_f32 v31, v32, v33
	v_add_co_u32_e32 v32, vcc, s41, v58
	v_pk_mul_f32 v[22:23], v[22:23], v[0:1] op_sel_hi:[1,0]
	s_nop 0
	v_addc_co_u32_e32 v33, vcc, 0, v59, vcc
	global_store_dwordx2 v[32:33], v[26:27], off offset:32
	s_waitcnt lgkmcnt(0)
	v_add_f32_e32 v26, v131, v28
	ds_bpermute_b32 v27, v143, v26
	v_pk_mul_f32 v[24:25], v[24:25], v[0:1] op_sel_hi:[1,0]
	v_cvt_pk_bf16_f32 v22, v22, v23
	v_cvt_pk_bf16_f32 v23, v24, v25
	global_store_dwordx2 v[32:33], v[22:23], off offset:64
	s_waitcnt lgkmcnt(0)
	v_add_f32_e32 v22, v26, v27
	v_div_scale_f32 v23, s[0:1], v22, v22, 1.0
	v_rcp_f32_e32 v24, v23
	v_pk_mul_f32 v[18:19], v[18:19], v[0:1] op_sel_hi:[1,0]
	v_pk_mul_f32 v[20:21], v[20:21], v[0:1] op_sel_hi:[1,0]
	v_cvt_pk_bf16_f32 v18, v18, v19
	v_fma_f32 v0, -v23, v24, 1.0
	v_cvt_pk_bf16_f32 v19, v20, v21
	v_fmac_f32_e32 v24, v0, v24
	v_div_scale_f32 v0, vcc, 1.0, v22, 1.0
	global_store_dwordx2 v[32:33], v[18:19], off offset:96
	v_mul_f32_e32 v18, v0, v24
	v_fma_f32 v19, -v23, v18, v0
	v_fmac_f32_e32 v18, v19, v24
	v_fma_f32 v0, -v23, v18, v0
	v_div_fmas_f32 v0, v0, v24, v18
	v_div_fixup_f32 v0, v0, v22, 1.0
	v_pk_mul_f32 v[14:15], v[14:15], v[0:1] op_sel_hi:[1,0]
	v_pk_mul_f32 v[16:17], v[16:17], v[0:1] op_sel_hi:[1,0]
	v_cvt_pk_bf16_f32 v14, v14, v15
	v_cvt_pk_bf16_f32 v15, v16, v17
	v_add_co_u32_e32 v16, vcc, s42, v58
	v_pk_mul_f32 v[10:11], v[10:11], v[0:1] op_sel_hi:[1,0]
	v_pk_mul_f32 v[12:13], v[12:13], v[0:1] op_sel_hi:[1,0]
	v_pk_mul_f32 v[6:7], v[6:7], v[0:1] op_sel_hi:[1,0]
	v_pk_mul_f32 v[8:9], v[8:9], v[0:1] op_sel_hi:[1,0]
	v_pk_mul_f32 v[2:3], v[2:3], v[0:1] op_sel_hi:[1,0]
	v_pk_mul_f32 v[4:5], v[4:5], v[0:1] op_sel_hi:[1,0]
	v_cvt_pk_bf16_f32 v62, v62, v63
	v_cvt_pk_bf16_f32 v63, v64, v65
	v_addc_co_u32_e32 v17, vcc, 0, v59, vcc
	v_cvt_pk_bf16_f32 v10, v10, v11
	v_cvt_pk_bf16_f32 v11, v12, v13
	v_cvt_pk_bf16_f32 v6, v6, v7
	v_cvt_pk_bf16_f32 v7, v8, v9
	v_cvt_pk_bf16_f32 v2, v2, v3
	v_cvt_pk_bf16_f32 v3, v4, v5
	s_cmpk_gt_i32 s98, 0x3ff
	global_store_dwordx2 v[58:59], v[62:63], off offset:32
	global_store_dwordx2 v[48:49], v[46:47], off
	global_store_dwordx2 v[32:33], v[30:31], off
	global_store_dwordx2 v[16:17], v[14:15], off
	global_store_dwordx2 v[16:17], v[10:11], off offset:32
	global_store_dwordx2 v[16:17], v[6:7], off offset:64
	global_store_dwordx2 v[16:17], v[2:3], off offset:96
	s_barrier
	s_cbranch_scc1 .LBB0_1612
.LBB0_1597:
	s_mov_b32 s43, s98
	s_cmpk_lg_i32 s94, 0x100
	s_cbranch_scc1 .Lmc_map
	s_and_b32 s99, s98, 7
	s_lshr_b32 s43, s98, 8
	s_lshl_b32 s43, s43, 1
	s_lshr_b32 s100, s99, 2
	s_add_i32 s43, s43, s100
	s_lshl_b32 s43, s43, 7
	s_and_b32 s100, s99, 3
	s_lshl_b32 s100, s100, 5
	s_or_b32 s43, s43, s100
	s_bfe_u32 s100, s98, 0x50003
	s_or_b32 s43, s43, s100
.Lmc_map:
	s_lshl_b32 s29, s43, 6
	s_bfe_u32 s1, s43, 0x20005
	s_ashr_i32 s0, s43, 7
	s_lshl_b32 s45, s1, 3
	s_add_i32 s45, s45, s33
	s_mul_i32 s9, s0, 0xa00000
	s_mul_hi_i32 s8, s0, 0xa00000
	s_add_u32 s47, s74, s9
	s_addc_u32 s48, s75, s8
	s_lshl_b32 s8, s45, 2
	v_mov_b32_e32 v0, s8
	v_readlane_b32 s8, v244, 35
	v_readlane_b32 s12, v244, 39
	v_readlane_b32 s13, v244, 40
	s_lshl_b32 s8, s43, 6
	s_and_b32 s46, s8, 0x7c0
	v_readlane_b32 s9, v244, 36
	s_add_i32 s44, s46, 0xffffff80
	v_readlane_b32 s10, v244, 37
	global_load_dword v133, v0, s[12:13]
	v_readlane_b32 s11, v244, 38
	v_readlane_b32 s14, v244, 41
	v_readlane_b32 s15, v244, 42
	v_readlane_b32 s16, v244, 43
	v_readlane_b32 s17, v244, 44
	v_readlane_b32 s18, v244, 45
	v_readlane_b32 s19, v244, 46
	v_readlane_b32 s20, v244, 47
	v_readlane_b32 s21, v244, 48
	v_readlane_b32 s22, v244, 49
	v_readlane_b32 s23, v244, 50
	s_and_saveexec_b64 s[8:9], s[4:5]
	s_cbranch_execz .LBB0_1602
	s_lshl_b32 s1, s1, 7
	s_add_u32 s1, s47, s1
	s_addc_u32 s13, s48, 0
	s_add_u32 s10, s1, 0x1000
	s_addc_u32 s11, s13, 0
	s_add_u32 s12, s1, 0x1200
	s_addc_u32 s13, s13, 0
	s_mov_b64 s[14:15], 0
	v_mov_b32_e32 v10, v141
	v_mov_b32_e32 v11, v138
	s_branch .LBB0_1600

.LBB0_1836:
	s_or_b64 exec, exec, s[0:1]
	v_readlane_b32 s0, v244, 53
	v_readlane_b32 s1, v244, 54
	v_mov_b32_e32 v126, v190
	s_and_b64 vcc, exec, s[0:1]
	s_waitcnt lgkmcnt(0)
	s_barrier
	s_cbranch_vccnz .LBB0_1841
	v_bfe_u32 v0, v126, 2, 2
	v_and_b32_e32 v1, 3, v126
	v_bfe_u32 v127, v126, 4, 2
	v_lshl_or_b32 v1, v0, 3, v1
	v_lshlrev_b32_e32 v4, 8, v1
	v_bitop3_b32 v5, v1, v127, 11 bitop3:0x6c
	v_lshl_or_b32 v129, v5, 4, v4
	v_or_b32_e32 v5, 4, v127
	v_bitop3_b32 v6, v1, v5, 11 bitop3:0x6c
	v_lshl_or_b32 v130, v6, 4, v4
	v_or_b32_e32 v6, 8, v127
	v_bitop3_b32 v7, v1, v6, 11 bitop3:0x6c
	v_lshlrev_b32_e32 v112, 3, v127
	v_lshlrev_b32_e32 v3, 3, v126
	v_lshl_or_b32 v131, v7, 4, v4
	v_or_b32_e32 v7, 12, v127
	v_or_b32_e32 v0, v112, v0
	v_bfe_u32 v2, v126, 1, 1
	v_and_b32_e32 v3, 8, v3
	v_bitop3_b32 v8, v1, v7, 11 bitop3:0x6c
	v_lshl_or_b32 v132, v8, 4, v4
	v_lshl_or_b32 v4, v0, 8, v3
	v_bitop3_b32 v8, v0, v2, 11 bitop3:0x6c
	v_lshl_or_b32 v133, v8, 4, v4
	v_or_b32_e32 v8, 2, v2
	v_bitop3_b32 v9, v0, v8, 11 bitop3:0x6c
	v_lshl_or_b32 v134, v9, 4, v4
	v_or_b32_e32 v9, 4, v2
	v_bitop3_b32 v10, v0, v9, 11 bitop3:0x6c
	v_lshl_or_b32 v135, v10, 4, v4
	v_or_b32_e32 v10, 6, v2
	v_bitop3_b32 v11, v0, v10, 11 bitop3:0x6c
	v_lshl_or_b32 v136, v11, 4, v4
	v_or_b32_e32 v11, 8, v2
	v_bitop3_b32 v12, v0, v11, 11 bitop3:0x6c
	v_lshl_or_b32 v137, v12, 4, v4
	v_or_b32_e32 v12, 10, v2
	v_bitop3_b32 v13, v0, v12, 11 bitop3:0x6c
	v_lshl_or_b32 v138, v13, 4, v4
	v_or_b32_e32 v13, 12, v2
	v_bitop3_b32 v14, v0, v13, 11 bitop3:0x6c
	v_lshl_or_b32 v139, v14, 4, v4
	v_or_b32_e32 v14, 14, v2
	v_bitop3_b32 v15, v0, v14, 11 bitop3:0x6c
	v_or_b32_e32 v1, 4, v1
	v_lshl_or_b32 v140, v15, 4, v4
	v_lshlrev_b32_e32 v4, 8, v1
	v_bitop3_b32 v5, v1, v5, 15 bitop3:0x6c
	v_bitop3_b32 v15, v1, v127, 15 bitop3:0x6c
	v_lshl_or_b32 v142, v5, 4, v4
	v_bitop3_b32 v5, v1, v6, 15 bitop3:0x6c
	v_bitop3_b32 v1, v1, v7, 15 bitop3:0x6c
	v_or_b32_e32 v0, 4, v0
	v_lshl_or_b32 v144, v1, 4, v4
	v_lshl_or_b32 v1, v0, 8, v3
	v_bitop3_b32 v2, v0, v2, 15 bitop3:0x6c
	v_lshl_or_b32 v145, v2, 4, v1
	v_bitop3_b32 v2, v0, v8, 15 bitop3:0x6c
	v_lshl_or_b32 v146, v2, 4, v1
	v_bitop3_b32 v2, v0, v9, 15 bitop3:0x6c
	v_lshl_or_b32 v147, v2, 4, v1
	v_bitop3_b32 v2, v0, v10, 15 bitop3:0x6c
	v_lshl_or_b32 v148, v2, 4, v1
	v_bitop3_b32 v2, v0, v11, 15 bitop3:0x6c
	v_lshl_or_b32 v149, v2, 4, v1
	v_bitop3_b32 v2, v0, v12, 15 bitop3:0x6c
	v_lshl_or_b32 v150, v2, 4, v1
	v_bitop3_b32 v2, v0, v13, 15 bitop3:0x6c
	v_bitop3_b32 v0, v0, v14, 15 bitop3:0x6c
	v_mov_b32_e32 v113, 0
	v_lshl_or_b32 v141, v15, 4, v4
	v_lshl_or_b32 v151, v2, 4, v1
	v_lshl_or_b32 v152, v0, 4, v1
	v_lshlrev_b32_e32 v0, 2, v127
	v_lshl_add_u64 v[2:3], s[92:93], 0, v[112:113]
	s_mov_b64 s[0:1], 0x1dd00080
	v_and_b32_e32 v128, 15, v126
	v_lshl_or_b32 v143, v5, 4, v4
	s_lshl_b32 s52, s2, 5
	s_lshl_b32 s53, s94, 5
	v_lshlrev_b32_e32 v153, 13, v127
	v_lshl_add_u64 v[114:115], v[2:3], 0, s[0:1]
	s_lshl_b32 s54, s2, 7
	s_lshl_b32 s55, s94, 7
	s_mov_b32 s1, 0
	v_lshlrev_b32_e32 v116, 1, v112
	v_mov_b32_e32 v117, v113
	v_add_u32_e32 v154, 0, v129
	s_add_i32 s56, 0, 0x10000
	s_mov_b64 s[4:5], 0x1c1000
	s_mov_b64 s[8:9], 0x181000
	s_mov_b64 s[10:11], 0x141000
	s_mov_b64 s[12:13], 0x101000
	s_mov_b64 s[14:15], 0xc1000
	s_mov_b64 s[16:17], 0x81000
	s_mov_b64 s[18:19], 0x41000
	s_mov_b32 s57, 0xf149f2ca
	v_lshlrev_b32_e32 v118, 1, v0
	v_add_u32_e32 v155, 0, v141
	v_mbcnt_hi_u32_b32 v156, -1, v191
	s_mov_b32 s58, s2
	s_mov_b32 s98, s2
	s_mov_b64 s[20:21], 0x31001100
	s_mov_b64 s[28:29], 0x31041100
	s_mov_b64 s[30:31], 0x31081100
	s_mov_b64 s[34:35], 0x310c1100
	s_mov_b64 s[36:37], 0x31101100
	s_mov_b64 s[38:39], 0x31141100
	s_mov_b64 s[40:41], 0x31181100
	s_mov_b64 s[42:43], 0x311c1100
.LBB0_1838:
	s_mov_b32 s58, s98
	s_cmpk_lg_i32 s94, 0x100
	s_cbranch_scc1 .Lxa_map_1838
	s_and_b32 s99, s98, 7
	s_lshl_b32 s99, s99, 1
	s_bfe_u32 s58, s98, 0x10007
	s_add_i32 s99, s99, s58
	s_lshr_b32 s58, s98, 8
	s_lshl_b32 s58, s58, 4
	s_add_i32 s99, s99, s58
	s_lshl_b32 s99, s99, 4
	s_bfe_u32 s58, s98, 0x40003
	s_or_b32 s58, s99, s58
.Lxa_map_1838:
	s_lshl_b32 s52, s58, 5
	s_lshl_b32 s54, s58, 7
	s_lshl_b32 s0, s52, 1
	s_and_b32 s62, s0, 0xc00
	s_and_b32 s0, s54, 0x780
	v_or_b32_e32 v112, s0, v128
	s_ashr_i32 s48, s58, 6
	v_readfirstlane_b32 s0, v126
	s_ashr_i32 s63, s0, 6
	s_ashr_i32 s49, s48, 31
	s_lshl_b32 s0, s58, 7
	s_lshl_b64 s[44:45], s[48:49], 11
	s_and_b32 s0, s0, 0x780
	s_lshl_b32 s48, s48, 8
	s_lshl_b32 s46, s63, 4
	v_or_b32_e32 v0, s0, v128
	s_lshl_b32 s0, s58, 5
	s_ashr_i32 s49, s48, 31
	s_ashr_i32 s47, s46, 31
	s_and_b32 s59, s0, 0x600
	s_lshl_b64 s[48:49], s[48:49], 13
	s_add_u32 s64, s22, s48
	v_or_b32_e32 v0, s44, v0
	v_mov_b32_e32 v1, s45
	s_addc_u32 s65, s23, s49
	s_lshl_b32 s0, s59, 1
	v_lshl_add_u64 v[0:1], v[0:1], 0, s[46:47]
	s_add_u32 s64, s64, s0
	v_lshlrev_b64 v[120:121], 11, v[0:1]
	s_addc_u32 s65, s65, 0
	s_lshl_b32 s66, s63, 2
	v_lshlrev_b64 v[0:1], 12, v[0:1]
	v_bitop3_b32 v3, s66, v126, v127 bitop3:0x36
	v_lshl_add_u64 v[0:1], s[74:75], 0, v[0:1]
	v_lshlrev_b32_e32 v3, 4, v3
	v_lshl_add_u64 v[0:1], v[0:1], 0, s[0:1]
	s_lshl_b32 s0, s63, 10
	v_or_b32_e32 v2, s66, v127
	v_and_b32_e32 v119, 0xf0, v3
	s_add_i32 s0, s0, 0
	v_lshl_or_b32 v2, v2, 13, v119
	v_mov_b32_e32 v3, v113
	s_mov_b32 m0, s0
	v_lshl_add_u64 v[122:123], s[64:65], 0, v[2:3]
	global_load_lds_dwordx4 v2, s[64:65]
	s_mov_b64 s[64:65], 0x40000
	v_lshl_add_u64 v[2:3], v[122:123], 0, s[64:65]
	s_add_i32 s64, s0, 0x2000
	s_mov_b32 m0, s64
	s_mov_b64 s[66:67], 0x80000
	s_add_i32 s65, s0, 0x4000
	global_load_lds_dwordx4 v[2:3], off
	v_lshl_add_u64 v[2:3], v[122:123], 0, s[66:67]
	s_mov_b32 m0, s65
	s_mov_b64 s[66:67], 0xc0000
	global_load_lds_dwordx4 v[2:3], off
	v_lshl_add_u64 v[2:3], v[122:123], 0, s[66:67]
	s_add_i32 s66, s0, 0x6000
	s_mov_b32 m0, s66
	s_mov_b64 s[80:81], 0x100000
	s_add_i32 s67, s0, 0x8000
	global_load_lds_dwordx4 v[2:3], off
	v_lshl_add_u64 v[2:3], v[122:123], 0, s[80:81]
	s_mov_b32 m0, s67
	s_mov_b64 s[80:81], 0x140000
	s_add_i32 s69, s0, 0xa000
	global_load_lds_dwordx4 v[2:3], off
	v_lshl_add_u64 v[2:3], v[122:123], 0, s[80:81]
	s_mov_b32 m0, s69
	s_mov_b64 s[80:81], 0x180000
	s_add_i32 s71, s0, 0xc000
	global_load_lds_dwordx4 v[2:3], off
	v_lshl_add_u64 v[2:3], v[122:123], 0, s[80:81]
	s_mov_b32 m0, s71
	s_mov_b64 s[80:81], 0x1c0000
	s_add_i32 s77, s0, 0xe000
	global_load_lds_dwordx4 v[2:3], off
	v_lshl_add_u64 v[2:3], v[122:123], 0, s[80:81]
	s_mov_b32 m0, s77
	v_lshl_add_u64 v[124:125], v[0:1], 0, v[116:117]
	global_load_lds_dwordx4 v[2:3], off
	s_waitcnt vmcnt(0)
	s_waitcnt vmcnt(0) lgkmcnt(0)
	s_barrier
	global_load_dwordx4 v[12:15], v[124:125], off
	global_load_dwordx4 v[8:11], v[124:125], off offset:64
	global_load_dwordx4 v[4:7], v[124:125], off offset:128
	global_load_dwordx4 v[0:3], v[124:125], off offset:192
	ds_read_b128 v[16:19], v154
	ds_read_b128 v[20:23], v155
	v_add_u32_e32 v157, 0, v130
	ds_read_b128 v[24:27], v157
	v_add_u32_e32 v158, 0, v142
	v_add_u32_e32 v159, 0, v131
	v_add_u32_e32 v160, 0, v143
	v_add_u32_e32 v161, 0, v132
	v_add_u32_e32 v162, 0, v144
	s_mov_b64 vcc, 0x100
	s_add_i32 s87, s0, 0x10000
	s_waitcnt vmcnt(3) lgkmcnt(2)
	v_mfma_f32_16x16x32_bf16 v[16:19], v[16:19], v[12:15], 0
	s_add_i32 s86, s0, 0x12000
	s_mov_b32 m0, s87
	s_add_i32 s85, s0, 0x14000
	s_waitcnt vmcnt(2) lgkmcnt(0)
	v_mfma_f32_16x16x32_bf16 v[16:19], v[24:27], v[8:11], v[16:19]
	ds_read_b128 v[24:27], v158
	s_add_i32 s84, s0, 0x16000
	s_add_i32 s83, s0, 0x18000
	v_mfma_f32_16x16x32_bf16 v[20:23], v[20:23], v[12:15], 0
	s_add_i32 s82, s0, 0x1a000
	s_add_i32 s81, s0, 0x1c000
	s_add_i32 s80, s0, 0x1e000
	s_waitcnt lgkmcnt(0)
	v_mfma_f32_16x16x32_bf16 v[20:23], v[24:27], v[8:11], v[20:23]
	ds_read_b128 v[24:27], v159
	v_add_u32_e32 v163, s56, v129
	v_add_u32_e32 v164, s56, v141
	s_waitcnt vmcnt(1) lgkmcnt(0)
	v_mfma_f32_16x16x32_bf16 v[16:19], v[24:27], v[4:7], v[16:19]
	ds_read_b128 v[24:27], v160
	v_add_u32_e32 v165, s56, v130
	v_add_u32_e32 v166, s56, v142
	s_waitcnt lgkmcnt(0)
	v_mfma_f32_16x16x32_bf16 v[20:23], v[24:27], v[4:7], v[20:23]
	ds_read_b128 v[24:27], v161
	v_add_u32_e32 v167, s56, v131
	v_add_u32_e32 v168, s56, v143
	s_waitcnt vmcnt(0) lgkmcnt(0)
	v_mfma_f32_16x16x32_bf16 v[24:27], v[24:27], v[0:3], v[16:19]
	s_nop 2
	ds_read_b128 v[16:19], v162
	v_add_u32_e32 v169, s56, v132
	v_add_u32_e32 v170, s56, v144
	s_waitcnt lgkmcnt(0)
	v_mfma_f32_16x16x32_bf16 v[28:31], v[16:19], v[0:3], v[20:23]
	v_lshl_add_u64 v[16:17], v[122:123], 0, vcc
	s_mov_b64 vcc, 0x1c0100
	v_lshl_add_u64 v[18:19], v[122:123], 0, vcc
	s_mov_b64 vcc, 0x180100
	v_lshl_add_u64 v[20:21], v[122:123], 0, vcc
	s_mov_b64 vcc, 0x140100
	v_lshl_add_u64 v[22:23], v[122:123], 0, vcc
	s_mov_b64 vcc, 0x100100
	v_lshl_add_u64 v[32:33], v[122:123], 0, vcc
	s_mov_b64 vcc, 0xc0100
	v_lshl_add_u64 v[34:35], v[122:123], 0, vcc
	s_mov_b64 vcc, 0x80100
	v_lshl_add_u64 v[36:37], v[122:123], 0, vcc
	s_mov_b64 vcc, 0x40100
	v_lshl_add_u64 v[38:39], v[122:123], 0, vcc
	global_load_lds_dwordx4 v[16:17], off
	s_mov_b32 m0, s86
	s_mov_b64 vcc, 0x200
	global_load_lds_dwordx4 v[38:39], off
	s_mov_b32 m0, s85
	s_or_b32 s48, s48, s62
	global_load_lds_dwordx4 v[36:37], off
	s_mov_b32 m0, s84
	s_nop 0
	global_load_lds_dwordx4 v[34:35], off
	s_mov_b32 m0, s83
	s_nop 0
	global_load_lds_dwordx4 v[32:33], off
	s_mov_b32 m0, s82
	s_nop 0
	global_load_lds_dwordx4 v[22:23], off
	s_mov_b32 m0, s81
	s_nop 0
	global_load_lds_dwordx4 v[20:21], off
	s_mov_b32 m0, s80
	s_nop 0
	global_load_lds_dwordx4 v[18:19], off
	ds_read_b128 v[16:19], v154 offset:8192
	ds_read_b128 v[20:23], v155 offset:8192
	ds_read_b128 v[32:35], v157 offset:8192
	s_waitcnt lgkmcnt(0)
	v_mfma_f32_16x16x32_bf16 v[16:19], v[16:19], v[12:15], 0
	s_mov_b32 m0, s0
	v_mfma_f32_16x16x32_bf16 v[16:19], v[32:35], v[8:11], v[16:19]
	ds_read_b128 v[32:35], v158 offset:8192
	v_mfma_f32_16x16x32_bf16 v[20:23], v[20:23], v[12:15], 0
	s_waitcnt lgkmcnt(0)
	v_mfma_f32_16x16x32_bf16 v[20:23], v[32:35], v[8:11], v[20:23]
	ds_read_b128 v[32:35], v159 offset:8192
	s_waitcnt lgkmcnt(0)
	v_mfma_f32_16x16x32_bf16 v[16:19], v[32:35], v[4:7], v[16:19]
	ds_read_b128 v[32:35], v160 offset:8192
	s_waitcnt lgkmcnt(0)
	v_mfma_f32_16x16x32_bf16 v[20:23], v[32:35], v[4:7], v[20:23]
	ds_read_b128 v[32:35], v161 offset:8192
	s_waitcnt lgkmcnt(0)
	v_mfma_f32_16x16x32_bf16 v[72:75], v[32:35], v[0:3], v[16:19]
	s_nop 2
	ds_read_b128 v[16:19], v162 offset:8192
	s_waitcnt lgkmcnt(0)
	v_mfma_f32_16x16x32_bf16 v[76:79], v[16:19], v[0:3], v[20:23]
	ds_read_b128 v[16:19], v162 offset:16384
	s_nop 1
	ds_read_b128 v[20:23], v161 offset:16384
	ds_read_b128 v[32:35], v160 offset:16384
	ds_read_b128 v[36:39], v159 offset:16384
	ds_read_b128 v[40:43], v158 offset:16384
	ds_read_b128 v[44:47], v157 offset:16384
	ds_read_b128 v[48:51], v155 offset:16384
	ds_read_b128 v[52:55], v154 offset:16384
	s_waitcnt lgkmcnt(0)
	v_mfma_f32_16x16x32_bf16 v[52:55], v[52:55], v[12:15], 0
	v_mfma_f32_16x16x32_bf16 v[48:51], v[48:51], v[12:15], 0
	v_mfma_f32_16x16x32_bf16 v[44:47], v[44:47], v[8:11], v[52:55]
	v_mfma_f32_16x16x32_bf16 v[40:43], v[40:43], v[8:11], v[48:51]
	v_mfma_f32_16x16x32_bf16 v[36:39], v[36:39], v[4:7], v[44:47]
	v_mfma_f32_16x16x32_bf16 v[32:35], v[32:35], v[4:7], v[40:43]
	v_mfma_f32_16x16x32_bf16 v[68:71], v[20:23], v[0:3], v[36:39]
	v_mfma_f32_16x16x32_bf16 v[64:67], v[16:19], v[0:3], v[32:35]
	ds_read_b128 v[16:19], v162 offset:24576
	ds_read_b128 v[20:23], v161 offset:24576
	s_nop 3
	ds_read_b128 v[32:35], v160 offset:24576
	ds_read_b128 v[36:39], v159 offset:24576
	ds_read_b128 v[40:43], v158 offset:24576
	ds_read_b128 v[44:47], v157 offset:24576
	ds_read_b128 v[48:51], v155 offset:24576
	ds_read_b128 v[52:55], v154 offset:24576
	s_waitcnt lgkmcnt(0)
	v_mfma_f32_16x16x32_bf16 v[52:55], v[52:55], v[12:15], 0
	v_mfma_f32_16x16x32_bf16 v[48:51], v[48:51], v[12:15], 0
	v_mfma_f32_16x16x32_bf16 v[44:47], v[44:47], v[8:11], v[52:55]
	v_mfma_f32_16x16x32_bf16 v[40:43], v[40:43], v[8:11], v[48:51]
	v_mfma_f32_16x16x32_bf16 v[36:39], v[36:39], v[4:7], v[44:47]
	v_mfma_f32_16x16x32_bf16 v[32:35], v[32:35], v[4:7], v[40:43]
	v_mfma_f32_16x16x32_bf16 v[60:63], v[20:23], v[0:3], v[36:39]
	v_mfma_f32_16x16x32_bf16 v[56:59], v[16:19], v[0:3], v[32:35]
	ds_read_b128 v[16:19], v162 offset:32768
	ds_read_b128 v[20:23], v161 offset:32768
	s_nop 3
	ds_read_b128 v[32:35], v160 offset:32768
	ds_read_b128 v[36:39], v159 offset:32768
	ds_read_b128 v[40:43], v158 offset:32768
	ds_read_b128 v[44:47], v157 offset:32768
	ds_read_b128 v[48:51], v155 offset:32768
	ds_read_b128 v[52:55], v154 offset:32768
	s_waitcnt lgkmcnt(0)
	v_mfma_f32_16x16x32_bf16 v[52:55], v[52:55], v[12:15], 0
	v_mfma_f32_16x16x32_bf16 v[48:51], v[48:51], v[12:15], 0
	v_mfma_f32_16x16x32_bf16 v[44:47], v[44:47], v[8:11], v[52:55]
	v_mfma_f32_16x16x32_bf16 v[40:43], v[40:43], v[8:11], v[48:51]
	v_mfma_f32_16x16x32_bf16 v[36:39], v[36:39], v[4:7], v[44:47]
	v_mfma_f32_16x16x32_bf16 v[32:35], v[32:35], v[4:7], v[40:43]
	v_mfma_f32_16x16x32_bf16 v[52:55], v[20:23], v[0:3], v[36:39]
	v_mfma_f32_16x16x32_bf16 v[48:51], v[16:19], v[0:3], v[32:35]
	ds_read_b128 v[16:19], v162 offset:40960
	ds_read_b128 v[20:23], v161 offset:40960
	s_nop 3
	ds_read_b128 v[32:35], v160 offset:40960
	ds_read_b128 v[36:39], v159 offset:40960
	ds_read_b128 v[40:43], v158 offset:40960
	ds_read_b128 v[44:47], v157 offset:40960
	ds_read_b128 v[80:83], v155 offset:40960
	ds_read_b128 v[84:87], v154 offset:40960
	s_waitcnt lgkmcnt(0)
	v_mfma_f32_16x16x32_bf16 v[84:87], v[84:87], v[12:15], 0
	v_mfma_f32_16x16x32_bf16 v[80:83], v[80:83], v[12:15], 0
	v_mfma_f32_16x16x32_bf16 v[44:47], v[44:47], v[8:11], v[84:87]
	v_mfma_f32_16x16x32_bf16 v[40:43], v[40:43], v[8:11], v[80:83]
	v_mfma_f32_16x16x32_bf16 v[36:39], v[36:39], v[4:7], v[44:47]
	v_mfma_f32_16x16x32_bf16 v[32:35], v[32:35], v[4:7], v[40:43]
	v_mfma_f32_16x16x32_bf16 v[44:47], v[20:23], v[0:3], v[36:39]
	v_mfma_f32_16x16x32_bf16 v[40:43], v[16:19], v[0:3], v[32:35]
	ds_read_b128 v[16:19], v162 offset:49152
	ds_read_b128 v[20:23], v161 offset:49152
	s_nop 3
	ds_read_b128 v[32:35], v160 offset:49152
	ds_read_b128 v[36:39], v159 offset:49152
	ds_read_b128 v[80:83], v158 offset:49152
	ds_read_b128 v[84:87], v157 offset:49152
	ds_read_b128 v[88:91], v155 offset:49152
	ds_read_b128 v[92:95], v154 offset:49152
	s_waitcnt lgkmcnt(0)
	v_mfma_f32_16x16x32_bf16 v[92:95], v[92:95], v[12:15], 0
	v_mfma_f32_16x16x32_bf16 v[88:91], v[88:91], v[12:15], 0
	v_mfma_f32_16x16x32_bf16 v[84:87], v[84:87], v[8:11], v[92:95]
	v_mfma_f32_16x16x32_bf16 v[80:83], v[80:83], v[8:11], v[88:91]
	v_mfma_f32_16x16x32_bf16 v[36:39], v[36:39], v[4:7], v[84:87]
	v_mfma_f32_16x16x32_bf16 v[32:35], v[32:35], v[4:7], v[80:83]
	v_mfma_f32_16x16x32_bf16 v[36:39], v[20:23], v[0:3], v[36:39]
	v_mfma_f32_16x16x32_bf16 v[32:35], v[16:19], v[0:3], v[32:35]
	ds_read_b128 v[16:19], v162 offset:57344
	ds_read_b128 v[20:23], v161 offset:57344
	s_nop 1
	ds_read_b128 v[80:83], v160 offset:57344
	ds_read_b128 v[84:87], v159 offset:57344
	ds_read_b128 v[88:91], v158 offset:57344
	ds_read_b128 v[92:95], v157 offset:57344
	ds_read_b128 v[96:99], v155 offset:57344
	ds_read_b128 v[100:103], v154 offset:57344
	s_waitcnt lgkmcnt(0)
	v_mfma_f32_16x16x32_bf16 v[100:103], v[100:103], v[12:15], 0
	v_mfma_f32_16x16x32_bf16 v[12:15], v[96:99], v[12:15], 0
	v_mfma_f32_16x16x32_bf16 v[92:95], v[92:95], v[8:11], v[100:103]
	v_mfma_f32_16x16x32_bf16 v[8:11], v[88:91], v[8:11], v[12:15]
	v_mfma_f32_16x16x32_bf16 v[12:15], v[84:87], v[4:7], v[92:95]
	v_mfma_f32_16x16x32_bf16 v[4:7], v[80:83], v[4:7], v[8:11]
	v_mfma_f32_16x16x32_bf16 v[12:15], v[20:23], v[0:3], v[12:15]
	v_mfma_f32_16x16x32_bf16 v[8:11], v[16:19], v[0:3], v[4:7]
	s_waitcnt vmcnt(0)
	s_waitcnt vmcnt(0)
	s_barrier
	global_load_dwordx4 v[20:23], v[124:125], off offset:256
	global_load_dwordx4 v[16:19], v[124:125], off offset:320
	s_nop 1
	global_load_dwordx4 v[4:7], v[124:125], off offset:384
	global_load_dwordx4 v[0:3], v[124:125], off offset:448
	ds_read_b128 v[80:83], v163
	s_waitcnt vmcnt(3) lgkmcnt(0)
	v_mfma_f32_16x16x32_bf16 v[24:27], v[80:83], v[20:23], v[24:27]
	ds_read_b128 v[80:83], v164
	s_waitcnt lgkmcnt(0)
	v_mfma_f32_16x16x32_bf16 v[28:31], v[80:83], v[20:23], v[28:31]
	ds_read_b128 v[80:83], v165
	s_waitcnt vmcnt(2) lgkmcnt(0)
	v_mfma_f32_16x16x32_bf16 v[24:27], v[80:83], v[16:19], v[24:27]
	ds_read_b128 v[80:83], v166
	s_waitcnt lgkmcnt(0)
	v_mfma_f32_16x16x32_bf16 v[28:31], v[80:83], v[16:19], v[28:31]
	ds_read_b128 v[80:83], v167
	s_waitcnt vmcnt(1) lgkmcnt(0)
	v_mfma_f32_16x16x32_bf16 v[24:27], v[80:83], v[4:7], v[24:27]
	ds_read_b128 v[80:83], v168
	s_waitcnt lgkmcnt(0)
	v_mfma_f32_16x16x32_bf16 v[28:31], v[80:83], v[4:7], v[28:31]
	ds_read_b128 v[80:83], v169
	s_waitcnt vmcnt(0) lgkmcnt(0)
	v_mfma_f32_16x16x32_bf16 v[24:27], v[80:83], v[0:3], v[24:27]
	ds_read_b128 v[80:83], v170
	s_waitcnt lgkmcnt(0)
	v_mfma_f32_16x16x32_bf16 v[28:31], v[80:83], v[0:3], v[28:31]
	v_lshl_add_u64 v[80:81], v[122:123], 0, vcc
	s_mov_b64 vcc, 0x1c0200
	v_lshl_add_u64 v[82:83], v[122:123], 0, vcc
	s_mov_b64 vcc, 0x180200
	v_lshl_add_u64 v[84:85], v[122:123], 0, vcc
	s_mov_b64 vcc, 0x140200
	v_lshl_add_u64 v[86:87], v[122:123], 0, vcc
	s_mov_b64 vcc, 0x100200
	v_lshl_add_u64 v[88:89], v[122:123], 0, vcc
	s_mov_b64 vcc, 0xc0200
	v_lshl_add_u64 v[90:91], v[122:123], 0, vcc
	s_mov_b64 vcc, 0x80200
	v_lshl_add_u64 v[92:93], v[122:123], 0, vcc
	s_mov_b64 vcc, 0x40200
	v_lshl_add_u64 v[94:95], v[122:123], 0, vcc
	global_load_lds_dwordx4 v[80:81], off
	s_mov_b32 m0, s64
	s_add_i32 vcc_lo, 0, 0x12000
	global_load_lds_dwordx4 v[94:95], off
	s_mov_b32 m0, s65
	v_add_u32_e32 v171, vcc_lo, v129
	global_load_lds_dwordx4 v[92:93], off
	s_mov_b32 m0, s66
	v_add_u32_e32 v172, vcc_lo, v141
	global_load_lds_dwordx4 v[90:91], off
	s_mov_b32 m0, s67
	v_add_u32_e32 v173, vcc_lo, v130
	global_load_lds_dwordx4 v[88:89], off
	s_mov_b32 m0, s69
	v_add_u32_e32 v174, vcc_lo, v142
	global_load_lds_dwordx4 v[86:87], off
	s_mov_b32 m0, s71
	v_add_u32_e32 v175, vcc_lo, v131
	global_load_lds_dwordx4 v[84:85], off
	s_mov_b32 m0, s77
	v_add_u32_e32 v176, vcc_lo, v143
	global_load_lds_dwordx4 v[82:83], off
	ds_read_b128 v[80:83], v171
	s_waitcnt lgkmcnt(0)
	v_mfma_f32_16x16x32_bf16 v[72:75], v[80:83], v[20:23], v[72:75]
	ds_read_b128 v[80:83], v172
	v_add_u32_e32 v177, vcc_lo, v132
	v_add_u32_e32 v178, vcc_lo, v144
	s_waitcnt lgkmcnt(0)
	v_mfma_f32_16x16x32_bf16 v[76:79], v[80:83], v[20:23], v[76:79]
	ds_read_b128 v[80:83], v173
	s_add_i32 vcc_lo, 0, 0x14000
	v_add_u32_e32 v185, vcc_lo, v141
	s_waitcnt lgkmcnt(0)
	v_mfma_f32_16x16x32_bf16 v[72:75], v[80:83], v[16:19], v[72:75]
	ds_read_b128 v[80:83], v174
	v_add_u32_e32 v186, vcc_lo, v129
	v_add_u32_e32 v183, vcc_lo, v142
	s_waitcnt lgkmcnt(0)
	v_mfma_f32_16x16x32_bf16 v[76:79], v[80:83], v[16:19], v[76:79]
	ds_read_b128 v[80:83], v175
	v_add_u32_e32 v184, vcc_lo, v130
	v_add_u32_e32 v181, vcc_lo, v143
	s_waitcnt lgkmcnt(0)
	v_mfma_f32_16x16x32_bf16 v[72:75], v[80:83], v[4:7], v[72:75]
	ds_read_b128 v[80:83], v176
	v_add_u32_e32 v182, vcc_lo, v131
	v_add_u32_e32 v179, vcc_lo, v144
	s_waitcnt lgkmcnt(0)
	v_mfma_f32_16x16x32_bf16 v[76:79], v[80:83], v[4:7], v[76:79]
	ds_read_b128 v[80:83], v177
	v_add_u32_e32 v180, vcc_lo, v132
	s_add_i32 vcc_lo, 0, 0x16000
	s_waitcnt lgkmcnt(0)
	v_mfma_f32_16x16x32_bf16 v[72:75], v[80:83], v[0:3], v[72:75]
	ds_read_b128 v[80:83], v178
	v_add_u32_e32 v195, vcc_lo, v141
	v_add_u32_e32 v196, vcc_lo, v129
	s_waitcnt lgkmcnt(0)
	v_mfma_f32_16x16x32_bf16 v[76:79], v[80:83], v[0:3], v[76:79]
	ds_read_b128 v[104:107], v185
	ds_read_b128 v[108:111], v186
	ds_read_b128 v[96:99], v183
	ds_read_b128 v[100:103], v184
	ds_read_b128 v[88:91], v181
	ds_read_b128 v[92:95], v182
	s_waitcnt lgkmcnt(0)
	v_mfma_f32_16x16x32_bf16 v[68:71], v[108:111], v[20:23], v[68:71]
	ds_read_b128 v[80:83], v179
	ds_read_b128 v[84:87], v180
	v_add_u32_e32 v193, vcc_lo, v142
	v_mfma_f32_16x16x32_bf16 v[64:67], v[104:107], v[20:23], v[64:67]
	v_add_u32_e32 v194, vcc_lo, v130
	v_add_u32_e32 v189, vcc_lo, v143
	v_add_u32_e32 v192, vcc_lo, v131
	v_mfma_f32_16x16x32_bf16 v[68:71], v[100:103], v[16:19], v[68:71]
	v_add_u32_e32 v187, vcc_lo, v144
	v_add_u32_e32 v188, vcc_lo, v132
	s_add_i32 vcc_lo, 0, 0x18000
	v_mfma_f32_16x16x32_bf16 v[64:67], v[96:99], v[16:19], v[64:67]
	v_add_u32_e32 v203, vcc_lo, v141
	v_add_u32_e32 v204, vcc_lo, v129
	v_add_u32_e32 v201, vcc_lo, v142
	v_mfma_f32_16x16x32_bf16 v[68:71], v[92:95], v[4:7], v[68:71]
	v_add_u32_e32 v202, vcc_lo, v130
	v_add_u32_e32 v199, vcc_lo, v143
	v_add_u32_e32 v200, vcc_lo, v131
	v_mfma_f32_16x16x32_bf16 v[64:67], v[88:91], v[4:7], v[64:67]
	v_add_u32_e32 v197, vcc_lo, v144
	v_add_u32_e32 v198, vcc_lo, v132
	s_add_i32 vcc_lo, 0, 0x1a000
	s_waitcnt lgkmcnt(0)
	v_mfma_f32_16x16x32_bf16 v[68:71], v[84:87], v[0:3], v[68:71]
	v_add_u32_e32 v205, vcc_lo, v144
	v_add_u32_e32 v211, vcc_lo, v130
	v_add_u32_e32 v206, vcc_lo, v141
	v_mfma_f32_16x16x32_bf16 v[64:67], v[80:83], v[0:3], v[64:67]
	ds_read_b128 v[104:107], v195
	ds_read_b128 v[108:111], v196
	ds_read_b128 v[96:99], v193
	ds_read_b128 v[100:103], v194
	ds_read_b128 v[88:91], v189
	ds_read_b128 v[92:95], v192
	s_waitcnt lgkmcnt(0)
	v_mfma_f32_16x16x32_bf16 v[60:63], v[108:111], v[20:23], v[60:63]
	ds_read_b128 v[80:83], v187
	ds_read_b128 v[84:87], v188
	v_add_u32_e32 v212, vcc_lo, v129
	v_mfma_f32_16x16x32_bf16 v[56:59], v[104:107], v[20:23], v[56:59]
	v_add_u32_e32 v209, vcc_lo, v131
	v_add_u32_e32 v210, vcc_lo, v142
	v_add_u32_e32 v207, vcc_lo, v132
	v_mfma_f32_16x16x32_bf16 v[60:63], v[100:103], v[16:19], v[60:63]
	v_add_u32_e32 v208, vcc_lo, v143
	s_add_i32 vcc_lo, 0, 0x1c000
	v_add_u32_e32 v219, vcc_lo, v141
	v_mfma_f32_16x16x32_bf16 v[56:59], v[96:99], v[16:19], v[56:59]
	v_add_u32_e32 v220, vcc_lo, v129
	v_add_u32_e32 v217, vcc_lo, v142
	v_add_u32_e32 v218, vcc_lo, v130
	v_mfma_f32_16x16x32_bf16 v[60:63], v[92:95], v[4:7], v[60:63]
	v_add_u32_e32 v215, vcc_lo, v143
	v_add_u32_e32 v216, vcc_lo, v131
	v_add_u32_e32 v213, vcc_lo, v144
	v_mfma_f32_16x16x32_bf16 v[56:59], v[88:91], v[4:7], v[56:59]
	v_add_u32_e32 v214, vcc_lo, v132
	s_add_i32 vcc_lo, 0, 0x1e000
	v_add_u32_e32 v227, vcc_lo, v141
	s_waitcnt lgkmcnt(0)
	v_mfma_f32_16x16x32_bf16 v[60:63], v[84:87], v[0:3], v[60:63]
	v_add_u32_e32 v228, vcc_lo, v129
	v_add_u32_e32 v225, vcc_lo, v142
	v_add_u32_e32 v226, vcc_lo, v130
	v_mfma_f32_16x16x32_bf16 v[56:59], v[80:83], v[0:3], v[56:59]
	ds_read_b128 v[104:107], v203
	ds_read_b128 v[108:111], v204
	ds_read_b128 v[96:99], v201
	ds_read_b128 v[100:103], v202
	ds_read_b128 v[88:91], v199
	ds_read_b128 v[92:95], v200
	s_waitcnt lgkmcnt(0)
	v_mfma_f32_16x16x32_bf16 v[52:55], v[108:111], v[20:23], v[52:55]
	ds_read_b128 v[80:83], v197
	ds_read_b128 v[84:87], v198
	v_add_u32_e32 v223, vcc_lo, v143
	v_mfma_f32_16x16x32_bf16 v[48:51], v[104:107], v[20:23], v[48:51]
	v_add_u32_e32 v224, vcc_lo, v131
	v_add_u32_e32 v221, vcc_lo, v144
	v_add_u32_e32 v222, vcc_lo, v132
	v_mfma_f32_16x16x32_bf16 v[52:55], v[100:103], v[16:19], v[52:55]
	s_mov_b64 vcc, 0x300
	s_mov_b32 m0, s87
	s_add_u32 s48, s92, s48
	v_mfma_f32_16x16x32_bf16 v[48:51], v[96:99], v[16:19], v[48:51]
	s_addc_u32 s49, s93, s49
	s_add_u32 s44, s44, s46
	s_addc_u32 s45, s45, s47
	v_mfma_f32_16x16x32_bf16 v[52:55], v[92:95], v[4:7], v[52:55]
	s_mov_b32 s46, 0
	v_mfma_f32_16x16x32_bf16 v[48:51], v[88:91], v[4:7], v[48:51]
	s_waitcnt lgkmcnt(0)
	v_mfma_f32_16x16x32_bf16 v[52:55], v[84:87], v[0:3], v[52:55]
	v_mfma_f32_16x16x32_bf16 v[48:51], v[80:83], v[0:3], v[48:51]
	ds_read_b128 v[80:83], v205
	ds_read_b128 v[104:107], v206
	ds_read_b128 v[100:103], v211
	ds_read_b128 v[108:111], v212
	ds_read_b128 v[92:95], v209
	ds_read_b128 v[96:99], v210
	ds_read_b128 v[84:87], v207
	ds_read_b128 v[88:91], v208
	s_waitcnt lgkmcnt(0)
	v_mfma_f32_16x16x32_bf16 v[44:47], v[108:111], v[20:23], v[44:47]
	v_mfma_f32_16x16x32_bf16 v[40:43], v[104:107], v[20:23], v[40:43]
	v_mfma_f32_16x16x32_bf16 v[44:47], v[100:103], v[16:19], v[44:47]
	v_mfma_f32_16x16x32_bf16 v[40:43], v[96:99], v[16:19], v[40:43]
	v_mfma_f32_16x16x32_bf16 v[44:47], v[92:95], v[4:7], v[44:47]
	v_mfma_f32_16x16x32_bf16 v[40:43], v[88:91], v[4:7], v[40:43]
	v_mfma_f32_16x16x32_bf16 v[44:47], v[84:87], v[0:3], v[44:47]
	v_mfma_f32_16x16x32_bf16 v[40:43], v[80:83], v[0:3], v[40:43]
	ds_read_b128 v[104:107], v219
	ds_read_b128 v[108:111], v220
	ds_read_b128 v[96:99], v217
	ds_read_b128 v[100:103], v218
	ds_read_b128 v[88:91], v215
	ds_read_b128 v[92:95], v216
	s_waitcnt lgkmcnt(0)
	v_mfma_f32_16x16x32_bf16 v[36:39], v[108:111], v[20:23], v[36:39]
	ds_read_b128 v[80:83], v213
	ds_read_b128 v[84:87], v214
	v_mfma_f32_16x16x32_bf16 v[32:35], v[104:107], v[20:23], v[32:35]
	v_mfma_f32_16x16x32_bf16 v[36:39], v[100:103], v[16:19], v[36:39]
	v_mfma_f32_16x16x32_bf16 v[32:35], v[96:99], v[16:19], v[32:35]
	v_mfma_f32_16x16x32_bf16 v[36:39], v[92:95], v[4:7], v[36:39]
	v_mfma_f32_16x16x32_bf16 v[32:35], v[88:91], v[4:7], v[32:35]
	s_waitcnt lgkmcnt(0)
	v_mfma_f32_16x16x32_bf16 v[36:39], v[84:87], v[0:3], v[36:39]
	v_mfma_f32_16x16x32_bf16 v[32:35], v[80:83], v[0:3], v[32:35]
	ds_read_b128 v[104:107], v227
	ds_read_b128 v[108:111], v228
	ds_read_b128 v[96:99], v225
	ds_read_b128 v[100:103], v226
	ds_read_b128 v[88:91], v223
	ds_read_b128 v[92:95], v224
	s_waitcnt lgkmcnt(0)
	v_mfma_f32_16x16x32_bf16 v[12:15], v[108:111], v[20:23], v[12:15]
	ds_read_b128 v[80:83], v221
	ds_read_b128 v[84:87], v222
	v_mfma_f32_16x16x32_bf16 v[8:11], v[104:107], v[20:23], v[8:11]
	v_mfma_f32_16x16x32_bf16 v[12:15], v[100:103], v[16:19], v[12:15]
	v_mfma_f32_16x16x32_bf16 v[8:11], v[96:99], v[16:19], v[8:11]
	v_mfma_f32_16x16x32_bf16 v[12:15], v[92:95], v[4:7], v[12:15]
	v_mfma_f32_16x16x32_bf16 v[4:7], v[88:91], v[4:7], v[8:11]
	s_waitcnt lgkmcnt(0)
	v_mfma_f32_16x16x32_bf16 v[12:15], v[84:87], v[0:3], v[12:15]
	v_mfma_f32_16x16x32_bf16 v[16:19], v[80:83], v[0:3], v[4:7]
	s_waitcnt vmcnt(0)
	s_waitcnt vmcnt(0)
	s_barrier
	global_load_dwordx4 v[84:87], v[124:125], off offset:512
	global_load_dwordx4 v[80:83], v[124:125], off offset:576
	global_load_dwordx4 v[20:23], v[124:125], off offset:640
	global_load_dwordx4 v[8:11], v[124:125], off offset:704
	ds_read_b128 v[0:3], v154
	ds_read_b128 v[4:7], v155
	s_waitcnt vmcnt(3) lgkmcnt(1)
	v_mfma_f32_16x16x32_bf16 v[0:3], v[0:3], v[84:87], v[24:27]
	s_nop 2
	ds_read_b128 v[24:27], v157
	s_waitcnt vmcnt(2) lgkmcnt(0)
	v_mfma_f32_16x16x32_bf16 v[0:3], v[24:27], v[80:83], v[0:3]
	ds_read_b128 v[24:27], v158
	v_mfma_f32_16x16x32_bf16 v[4:7], v[4:7], v[84:87], v[28:31]
	s_waitcnt lgkmcnt(0)
	v_mfma_f32_16x16x32_bf16 v[4:7], v[24:27], v[80:83], v[4:7]
	ds_read_b128 v[24:27], v159
	s_waitcnt vmcnt(1) lgkmcnt(0)
	v_mfma_f32_16x16x32_bf16 v[0:3], v[24:27], v[20:23], v[0:3]
	ds_read_b128 v[24:27], v160
	s_waitcnt lgkmcnt(0)
	v_mfma_f32_16x16x32_bf16 v[24:27], v[24:27], v[20:23], v[4:7]
	s_nop 2
	ds_read_b128 v[4:7], v161
	s_waitcnt vmcnt(0) lgkmcnt(0)
	v_mfma_f32_16x16x32_bf16 v[4:7], v[4:7], v[8:11], v[0:3]
	s_nop 2
	ds_read_b128 v[0:3], v162
	s_waitcnt lgkmcnt(0)
	v_mfma_f32_16x16x32_bf16 v[0:3], v[0:3], v[8:11], v[24:27]
	s_nop 2
	v_lshl_add_u64 v[24:25], v[122:123], 0, vcc
	s_mov_b64 vcc, 0x1c0300
	v_lshl_add_u64 v[26:27], v[122:123], 0, vcc
	s_mov_b64 vcc, 0x180300
	v_lshl_add_u64 v[28:29], v[122:123], 0, vcc
	s_mov_b64 vcc, 0x140300
	v_lshl_add_u64 v[30:31], v[122:123], 0, vcc
	s_mov_b64 vcc, 0x100300
	v_lshl_add_u64 v[88:89], v[122:123], 0, vcc
	s_mov_b64 vcc, 0xc0300
	v_lshl_add_u64 v[90:91], v[122:123], 0, vcc
	s_mov_b64 vcc, 0x80300
	v_lshl_add_u64 v[92:93], v[122:123], 0, vcc
	s_mov_b64 vcc, 0x40300
	v_lshl_add_u64 v[94:95], v[122:123], 0, vcc
	global_load_lds_dwordx4 v[24:25], off
	s_mov_b32 m0, s86
	s_nop 0
	global_load_lds_dwordx4 v[94:95], off
	s_mov_b32 m0, s85
	s_nop 0
	global_load_lds_dwordx4 v[92:93], off
	s_mov_b32 m0, s84
	s_nop 0
	global_load_lds_dwordx4 v[90:91], off
	s_mov_b32 m0, s83
	s_nop 0
	global_load_lds_dwordx4 v[88:89], off
	s_mov_b32 m0, s82
	s_nop 0
	global_load_lds_dwordx4 v[30:31], off
	s_mov_b32 m0, s81
	s_nop 0
	global_load_lds_dwordx4 v[28:29], off
	s_mov_b32 m0, s80
	s_mov_b64 s[80:81], 0x1000
	global_load_lds_dwordx4 v[26:27], off
	ds_read_b128 v[24:27], v154 offset:8192
	ds_read_b128 v[28:31], v155 offset:8192
	s_waitcnt lgkmcnt(0)
	v_mfma_f32_16x16x32_bf16 v[24:27], v[24:27], v[84:87], v[72:75]
	s_nop 2
	ds_read_b128 v[72:75], v157 offset:8192
	s_mov_b32 m0, s0
	s_waitcnt lgkmcnt(0)
	v_mfma_f32_16x16x32_bf16 v[24:27], v[72:75], v[80:83], v[24:27]
	ds_read_b128 v[72:75], v158 offset:8192
	v_mfma_f32_16x16x32_bf16 v[28:31], v[28:31], v[84:87], v[76:79]
	s_waitcnt lgkmcnt(0)
	v_mfma_f32_16x16x32_bf16 v[28:31], v[72:75], v[80:83], v[28:31]
	ds_read_b128 v[72:75], v159 offset:8192
	s_waitcnt lgkmcnt(0)
	v_mfma_f32_16x16x32_bf16 v[24:27], v[72:75], v[20:23], v[24:27]
	ds_read_b128 v[72:75], v160 offset:8192
	s_waitcnt lgkmcnt(0)
	v_mfma_f32_16x16x32_bf16 v[28:31], v[72:75], v[20:23], v[28:31]
	ds_read_b128 v[72:75], v161 offset:8192
	s_waitcnt lgkmcnt(0)
	v_mfma_f32_16x16x32_bf16 v[96:99], v[72:75], v[8:11], v[24:27]
	s_nop 2
	ds_read_b128 v[24:27], v162 offset:8192
	s_waitcnt lgkmcnt(0)
	v_mfma_f32_16x16x32_bf16 v[100:103], v[24:27], v[8:11], v[28:31]
	s_nop 2
	ds_read_b128 v[28:31], v162 offset:16384
	ds_read_b128 v[24:27], v161 offset:16384
	ds_read_b128 v[72:75], v160 offset:16384
	ds_read_b128 v[76:79], v159 offset:16384
	ds_read_b128 v[88:91], v158 offset:16384
	ds_read_b128 v[92:95], v157 offset:16384
	ds_read_b128 v[104:107], v155 offset:16384
	ds_read_b128 v[108:111], v154 offset:16384
	s_waitcnt lgkmcnt(0)
	v_mfma_f32_16x16x32_bf16 v[68:71], v[108:111], v[84:87], v[68:71]
	v_mfma_f32_16x16x32_bf16 v[64:67], v[104:107], v[84:87], v[64:67]
	v_mfma_f32_16x16x32_bf16 v[68:71], v[92:95], v[80:83], v[68:71]
	v_mfma_f32_16x16x32_bf16 v[64:67], v[88:91], v[80:83], v[64:67]
	v_mfma_f32_16x16x32_bf16 v[68:71], v[76:79], v[20:23], v[68:71]
	v_mfma_f32_16x16x32_bf16 v[64:67], v[72:75], v[20:23], v[64:67]
	v_mfma_f32_16x16x32_bf16 v[24:27], v[24:27], v[8:11], v[68:71]
	v_mfma_f32_16x16x32_bf16 v[28:31], v[28:31], v[8:11], v[64:67]
	s_nop 4
	ds_read_b128 v[68:71], v162 offset:24576
	ds_read_b128 v[64:67], v161 offset:24576
	ds_read_b128 v[72:75], v160 offset:24576
	ds_read_b128 v[76:79], v159 offset:24576
	ds_read_b128 v[88:91], v158 offset:24576
	ds_read_b128 v[92:95], v157 offset:24576
	ds_read_b128 v[104:107], v155 offset:24576
	ds_read_b128 v[108:111], v154 offset:24576
	s_waitcnt lgkmcnt(0)
	v_mfma_f32_16x16x32_bf16 v[60:63], v[108:111], v[84:87], v[60:63]
	v_mfma_f32_16x16x32_bf16 v[56:59], v[104:107], v[84:87], v[56:59]
	v_mfma_f32_16x16x32_bf16 v[60:63], v[92:95], v[80:83], v[60:63]
	v_mfma_f32_16x16x32_bf16 v[56:59], v[88:91], v[80:83], v[56:59]
	v_mfma_f32_16x16x32_bf16 v[60:63], v[76:79], v[20:23], v[60:63]
	v_mfma_f32_16x16x32_bf16 v[56:59], v[72:75], v[20:23], v[56:59]
	v_mfma_f32_16x16x32_bf16 v[64:67], v[64:67], v[8:11], v[60:63]
	v_mfma_f32_16x16x32_bf16 v[68:71], v[68:71], v[8:11], v[56:59]
	s_nop 5
	ds_read_b128 v[56:59], v162 offset:32768
	ds_read_b128 v[60:63], v161 offset:32768
	ds_read_b128 v[72:75], v160 offset:32768
	ds_read_b128 v[76:79], v159 offset:32768
	ds_read_b128 v[88:91], v158 offset:32768
	ds_read_b128 v[92:95], v157 offset:32768
	ds_read_b128 v[104:107], v155 offset:32768
	ds_read_b128 v[108:111], v154 offset:32768
	s_waitcnt lgkmcnt(0)
	v_mfma_f32_16x16x32_bf16 v[52:55], v[108:111], v[84:87], v[52:55]
	v_mfma_f32_16x16x32_bf16 v[48:51], v[104:107], v[84:87], v[48:51]
	v_mfma_f32_16x16x32_bf16 v[52:55], v[92:95], v[80:83], v[52:55]
	v_mfma_f32_16x16x32_bf16 v[48:51], v[88:91], v[80:83], v[48:51]
	v_mfma_f32_16x16x32_bf16 v[52:55], v[76:79], v[20:23], v[52:55]
	v_mfma_f32_16x16x32_bf16 v[48:51], v[72:75], v[20:23], v[48:51]
	v_mfma_f32_16x16x32_bf16 v[72:75], v[60:63], v[8:11], v[52:55]
	v_mfma_f32_16x16x32_bf16 v[76:79], v[56:59], v[8:11], v[48:51]
	s_nop 5
	ds_read_b128 v[48:51], v162 offset:40960
	ds_read_b128 v[52:55], v161 offset:40960
	ds_read_b128 v[56:59], v160 offset:40960
	ds_read_b128 v[60:63], v159 offset:40960
	ds_read_b128 v[88:91], v158 offset:40960
	ds_read_b128 v[92:95], v157 offset:40960
	ds_read_b128 v[104:107], v155 offset:40960
	ds_read_b128 v[108:111], v154 offset:40960
	s_waitcnt lgkmcnt(0)
	v_mfma_f32_16x16x32_bf16 v[44:47], v[108:111], v[84:87], v[44:47]
	v_mfma_f32_16x16x32_bf16 v[40:43], v[104:107], v[84:87], v[40:43]
	v_mfma_f32_16x16x32_bf16 v[44:47], v[92:95], v[80:83], v[44:47]
	v_mfma_f32_16x16x32_bf16 v[40:43], v[88:91], v[80:83], v[40:43]
	v_mfma_f32_16x16x32_bf16 v[44:47], v[60:63], v[20:23], v[44:47]
	v_mfma_f32_16x16x32_bf16 v[40:43], v[56:59], v[20:23], v[40:43]
	v_mfma_f32_16x16x32_bf16 v[88:91], v[52:55], v[8:11], v[44:47]
	v_mfma_f32_16x16x32_bf16 v[92:95], v[48:51], v[8:11], v[40:43]
	s_nop 5
	ds_read_b128 v[40:43], v162 offset:49152
	ds_read_b128 v[44:47], v161 offset:49152
	ds_read_b128 v[48:51], v160 offset:49152
	ds_read_b128 v[52:55], v159 offset:49152
	ds_read_b128 v[56:59], v158 offset:49152
	ds_read_b128 v[60:63], v157 offset:49152
	ds_read_b128 v[104:107], v155 offset:49152
	ds_read_b128 v[108:111], v154 offset:49152
	s_waitcnt lgkmcnt(0)
	v_mfma_f32_16x16x32_bf16 v[36:39], v[108:111], v[84:87], v[36:39]
	v_mfma_f32_16x16x32_bf16 v[32:35], v[104:107], v[84:87], v[32:35]
	v_mfma_f32_16x16x32_bf16 v[36:39], v[60:63], v[80:83], v[36:39]
	v_mfma_f32_16x16x32_bf16 v[32:35], v[56:59], v[80:83], v[32:35]
	v_mfma_f32_16x16x32_bf16 v[36:39], v[52:55], v[20:23], v[36:39]
	v_mfma_f32_16x16x32_bf16 v[32:35], v[48:51], v[20:23], v[32:35]
	v_mfma_f32_16x16x32_bf16 v[104:107], v[44:47], v[8:11], v[36:39]
	v_mfma_f32_16x16x32_bf16 v[108:111], v[40:43], v[8:11], v[32:35]
	s_nop 5
	ds_read_b128 v[32:35], v162 offset:57344
	ds_read_b128 v[36:39], v161 offset:57344
	ds_read_b128 v[40:43], v160 offset:57344
	ds_read_b128 v[44:47], v159 offset:57344
	ds_read_b128 v[48:51], v158 offset:57344
	ds_read_b128 v[52:55], v157 offset:57344
	ds_read_b128 v[56:59], v155 offset:57344
	ds_read_b128 v[60:63], v154 offset:57344
	s_waitcnt lgkmcnt(0)
	v_mfma_f32_16x16x32_bf16 v[12:15], v[60:63], v[84:87], v[12:15]
	v_mfma_f32_16x16x32_bf16 v[16:19], v[56:59], v[84:87], v[16:19]
	v_mfma_f32_16x16x32_bf16 v[12:15], v[52:55], v[80:83], v[12:15]
	v_mfma_f32_16x16x32_bf16 v[16:19], v[48:51], v[80:83], v[16:19]
	v_mfma_f32_16x16x32_bf16 v[12:15], v[44:47], v[20:23], v[12:15]
	v_mfma_f32_16x16x32_bf16 v[16:19], v[40:43], v[20:23], v[16:19]
	v_mfma_f32_16x16x32_bf16 v[80:83], v[36:39], v[8:11], v[12:15]
	v_mfma_f32_16x16x32_bf16 v[84:87], v[32:35], v[8:11], v[16:19]
	s_waitcnt vmcnt(0)
	s_waitcnt vmcnt(0)
	s_barrier
	global_load_dwordx4 v[158:161], v[124:125], off offset:768
	global_load_dwordx4 v[230:233], v[124:125], off offset:832
	global_load_dwordx4 v[234:237], v[124:125], off offset:896
	global_load_dwordx4 v[238:241], v[124:125], off offset:960
	ds_read_b128 v[8:11], v163
	s_waitcnt vmcnt(3) lgkmcnt(0)
	v_mfma_f32_16x16x32_bf16 v[4:7], v[8:11], v[158:161], v[4:7]
	ds_read_b128 v[8:11], v164
	v_lshl_add_u64 v[12:13], v[122:123], 0, s[80:81]
	v_lshl_add_u64 v[14:15], v[122:123], 0, s[18:19]
	s_waitcnt lgkmcnt(0)
	v_mfma_f32_16x16x32_bf16 v[0:3], v[8:11], v[158:161], v[0:3]
	ds_read_b128 v[8:11], v165
	s_waitcnt vmcnt(2) lgkmcnt(0)
	v_mfma_f32_16x16x32_bf16 v[4:7], v[8:11], v[230:233], v[4:7]
	ds_read_b128 v[8:11], v166
	s_waitcnt lgkmcnt(0)
	v_mfma_f32_16x16x32_bf16 v[0:3], v[8:11], v[230:233], v[0:3]
	ds_read_b128 v[8:11], v167
	s_waitcnt vmcnt(1) lgkmcnt(0)
	v_mfma_f32_16x16x32_bf16 v[4:7], v[8:11], v[234:237], v[4:7]
	ds_read_b128 v[8:11], v168
	s_waitcnt lgkmcnt(0)
	v_mfma_f32_16x16x32_bf16 v[0:3], v[8:11], v[234:237], v[0:3]
	ds_read_b128 v[8:11], v169
	s_waitcnt vmcnt(0) lgkmcnt(0)
	v_mfma_f32_16x16x32_bf16 v[60:63], v[8:11], v[238:241], v[4:7]
	s_nop 2
	ds_read_b128 v[4:7], v170
	v_lshl_add_u64 v[10:11], v[122:123], 0, s[16:17]
	v_lshl_add_u64 v[8:9], v[122:123], 0, s[14:15]
	s_waitcnt lgkmcnt(0)
	v_mfma_f32_16x16x32_bf16 v[52:55], v[4:7], v[238:241], v[0:3]
	global_load_lds_dwordx4 v[12:13], off
	s_mov_b32 m0, s64
	v_lshl_add_u64 v[6:7], v[122:123], 0, s[12:13]
	global_load_lds_dwordx4 v[14:15], off
	s_mov_b32 m0, s65
	v_lshl_add_u64 v[4:5], v[122:123], 0, s[10:11]
	global_load_lds_dwordx4 v[10:11], off
	s_mov_b32 m0, s66
	v_lshl_add_u64 v[2:3], v[122:123], 0, s[8:9]
	global_load_lds_dwordx4 v[8:9], off
	s_mov_b32 m0, s67
	v_lshl_add_u64 v[0:1], v[122:123], 0, s[4:5]
	global_load_lds_dwordx4 v[6:7], off
	s_mov_b32 m0, s69
	s_nop 0
	global_load_lds_dwordx4 v[4:5], off
	s_mov_b32 m0, s71
	s_nop 0
	global_load_lds_dwordx4 v[2:3], off
	s_mov_b32 m0, s77
	s_nop 0
	global_load_lds_dwordx4 v[0:1], off
	ds_read_b128 v[0:3], v171
	ds_read_b128 v[4:7], v172
	ds_read_b128 v[8:11], v173
	s_waitcnt lgkmcnt(0)
	v_mfma_f32_16x16x32_bf16 v[0:3], v[0:3], v[158:161], v[96:99]
	v_mfma_f32_16x16x32_bf16 v[0:3], v[8:11], v[230:233], v[0:3]
	ds_read_b128 v[8:11], v174
	v_mfma_f32_16x16x32_bf16 v[4:7], v[4:7], v[158:161], v[100:103]
	s_waitcnt lgkmcnt(0)
	v_mfma_f32_16x16x32_bf16 v[4:7], v[8:11], v[230:233], v[4:7]
	ds_read_b128 v[8:11], v175
	s_waitcnt lgkmcnt(0)
	v_mfma_f32_16x16x32_bf16 v[0:3], v[8:11], v[234:237], v[0:3]
	ds_read_b128 v[8:11], v176
	s_waitcnt lgkmcnt(0)
	v_mfma_f32_16x16x32_bf16 v[4:7], v[8:11], v[234:237], v[4:7]
	ds_read_b128 v[8:11], v177
	s_waitcnt lgkmcnt(0)
	v_mfma_f32_16x16x32_bf16 v[56:59], v[8:11], v[238:241], v[0:3]
	s_nop 2
	ds_read_b128 v[0:3], v178
	s_waitcnt lgkmcnt(0)
	v_mfma_f32_16x16x32_bf16 v[48:51], v[0:3], v[238:241], v[4:7]
	ds_read_b128 v[0:3], v179
	s_nop 1
	ds_read_b128 v[4:7], v180
	ds_read_b128 v[8:11], v181
	ds_read_b128 v[12:15], v182
	ds_read_b128 v[16:19], v183
	ds_read_b128 v[20:23], v184
	ds_read_b128 v[32:35], v185
	ds_read_b128 v[36:39], v186
	s_waitcnt lgkmcnt(0)
	v_mfma_f32_16x16x32_bf16 v[24:27], v[36:39], v[158:161], v[24:27]
	v_mfma_f32_16x16x32_bf16 v[28:31], v[32:35], v[158:161], v[28:31]
	v_mfma_f32_16x16x32_bf16 v[20:23], v[20:23], v[230:233], v[24:27]
	v_mfma_f32_16x16x32_bf16 v[16:19], v[16:19], v[230:233], v[28:31]
	v_mfma_f32_16x16x32_bf16 v[12:15], v[12:15], v[234:237], v[20:23]
	v_mfma_f32_16x16x32_bf16 v[8:11], v[8:11], v[234:237], v[16:19]
	v_mfma_f32_16x16x32_bf16 v[44:47], v[4:7], v[238:241], v[12:15]
	v_mfma_f32_16x16x32_bf16 v[40:43], v[0:3], v[238:241], v[8:11]
	ds_read_b128 v[0:3], v187
	ds_read_b128 v[4:7], v188
	s_nop 3
	ds_read_b128 v[8:11], v189
	ds_read_b128 v[12:15], v192
	ds_read_b128 v[16:19], v193
	ds_read_b128 v[20:23], v194
	ds_read_b128 v[24:27], v195
	ds_read_b128 v[28:31], v196
	s_waitcnt lgkmcnt(0)
	v_mfma_f32_16x16x32_bf16 v[28:31], v[28:31], v[158:161], v[64:67]
	v_mfma_f32_16x16x32_bf16 v[24:27], v[24:27], v[158:161], v[68:71]
	v_mfma_f32_16x16x32_bf16 v[20:23], v[20:23], v[230:233], v[28:31]
	v_mfma_f32_16x16x32_bf16 v[16:19], v[16:19], v[230:233], v[24:27]
	v_mfma_f32_16x16x32_bf16 v[12:15], v[12:15], v[234:237], v[20:23]
	v_mfma_f32_16x16x32_bf16 v[8:11], v[8:11], v[234:237], v[16:19]
	v_mfma_f32_16x16x32_bf16 v[36:39], v[4:7], v[238:241], v[12:15]
	v_mfma_f32_16x16x32_bf16 v[32:35], v[0:3], v[238:241], v[8:11]
	ds_read_b128 v[0:3], v197
	ds_read_b128 v[4:7], v198
	s_nop 3
	ds_read_b128 v[8:11], v199
	ds_read_b128 v[12:15], v200
	ds_read_b128 v[16:19], v201
	ds_read_b128 v[20:23], v202
	ds_read_b128 v[24:27], v203
	ds_read_b128 v[28:31], v204
	s_waitcnt lgkmcnt(0)
	v_mfma_f32_16x16x32_bf16 v[28:31], v[28:31], v[158:161], v[72:75]
	v_mfma_f32_16x16x32_bf16 v[24:27], v[24:27], v[158:161], v[76:79]
	v_mfma_f32_16x16x32_bf16 v[20:23], v[20:23], v[230:233], v[28:31]
	v_mfma_f32_16x16x32_bf16 v[16:19], v[16:19], v[230:233], v[24:27]
	v_mfma_f32_16x16x32_bf16 v[12:15], v[12:15], v[234:237], v[20:23]
	v_mfma_f32_16x16x32_bf16 v[8:11], v[8:11], v[234:237], v[16:19]
	v_mfma_f32_16x16x32_bf16 v[28:31], v[4:7], v[238:241], v[12:15]
	v_mfma_f32_16x16x32_bf16 v[24:27], v[0:3], v[238:241], v[8:11]
	ds_read_b128 v[0:3], v205
	ds_read_b128 v[4:7], v207
	s_nop 3
	ds_read_b128 v[8:11], v208
	ds_read_b128 v[12:15], v209
	ds_read_b128 v[16:19], v210
	ds_read_b128 v[20:23], v211
	ds_read_b128 v[64:67], v206
	ds_read_b128 v[68:71], v212
	s_waitcnt lgkmcnt(0)
	v_mfma_f32_16x16x32_bf16 v[68:71], v[68:71], v[158:161], v[88:91]
	v_mfma_f32_16x16x32_bf16 v[64:67], v[64:67], v[158:161], v[92:95]
	v_mfma_f32_16x16x32_bf16 v[20:23], v[20:23], v[230:233], v[68:71]
	v_mfma_f32_16x16x32_bf16 v[16:19], v[16:19], v[230:233], v[64:67]
	v_mfma_f32_16x16x32_bf16 v[12:15], v[12:15], v[234:237], v[20:23]
	v_mfma_f32_16x16x32_bf16 v[8:11], v[8:11], v[234:237], v[16:19]
	v_mfma_f32_16x16x32_bf16 v[20:23], v[4:7], v[238:241], v[12:15]
	v_mfma_f32_16x16x32_bf16 v[16:19], v[0:3], v[238:241], v[8:11]
	ds_read_b128 v[0:3], v213
	ds_read_b128 v[4:7], v214
	s_nop 3
	ds_read_b128 v[8:11], v215
	ds_read_b128 v[12:15], v216
	ds_read_b128 v[64:67], v217
	ds_read_b128 v[68:71], v218
	ds_read_b128 v[72:75], v219
	ds_read_b128 v[76:79], v220
	s_waitcnt lgkmcnt(0)
	v_mfma_f32_16x16x32_bf16 v[76:79], v[76:79], v[158:161], v[104:107]
	v_mfma_f32_16x16x32_bf16 v[72:75], v[72:75], v[158:161], v[108:111]
	v_mfma_f32_16x16x32_bf16 v[68:71], v[68:71], v[230:233], v[76:79]
	v_mfma_f32_16x16x32_bf16 v[64:67], v[64:67], v[230:233], v[72:75]
	v_mfma_f32_16x16x32_bf16 v[12:15], v[12:15], v[234:237], v[68:71]
	v_mfma_f32_16x16x32_bf16 v[8:11], v[8:11], v[234:237], v[64:67]
	v_mfma_f32_16x16x32_bf16 v[12:15], v[4:7], v[238:241], v[12:15]
	v_mfma_f32_16x16x32_bf16 v[8:11], v[0:3], v[238:241], v[8:11]
	ds_read_b128 v[0:3], v221
	ds_read_b128 v[4:7], v222
	s_nop 1
	ds_read_b128 v[64:67], v223
	ds_read_b128 v[68:71], v224
	ds_read_b128 v[72:75], v225
	ds_read_b128 v[76:79], v226
	ds_read_b128 v[88:91], v227
	ds_read_b128 v[92:95], v228
	s_waitcnt lgkmcnt(0)
	v_mfma_f32_16x16x32_bf16 v[84:87], v[88:91], v[158:161], v[84:87]
	v_mfma_f32_16x16x32_bf16 v[72:75], v[72:75], v[230:233], v[84:87]
	v_mfma_f32_16x16x32_bf16 v[64:67], v[64:67], v[234:237], v[72:75]
	v_mfma_f32_16x16x32_bf16 v[0:3], v[0:3], v[238:241], v[64:67]
	v_mfma_f32_16x16x32_bf16 v[80:83], v[92:95], v[158:161], v[80:83]
	s_nop 5
	v_max_f32_e32 v64, v63, v63
	v_max_f32_e32 v65, v62, v62
	v_max_f32_e32 v64, v65, v64
	v_max_f32_e32 v65, v55, v55
	v_max_f32_e32 v66, v54, v54
	v_max_f32_e32 v65, v66, v65
	v_max3_f32 v64, v60, v61, v64
	v_max3_f32 v65, v52, v53, v65
	v_max3_f32 v64, v64, s57, v65
	v_max_f32_e32 v65, v59, v59
	v_max_f32_e32 v66, v58, v58
	v_max_f32_e32 v65, v66, v65
	v_max_f32_e32 v66, v51, v51
	v_max_f32_e32 v67, v50, v50
	v_max_f32_e32 v66, v67, v66
	v_max3_f32 v65, v56, v57, v65
	v_max3_f32 v66, v48, v49, v66
	v_max3_f32 v64, v64, v65, v66
	v_max_f32_e32 v65, v47, v47
	v_max_f32_e32 v66, v46, v46
	v_max_f32_e32 v65, v66, v65
	v_max_f32_e32 v66, v43, v43
	v_max_f32_e32 v67, v42, v42
	v_max_f32_e32 v66, v67, v66
	v_max3_f32 v65, v44, v45, v65
	v_max3_f32 v66, v40, v41, v66
	v_max3_f32 v64, v64, v65, v66
	v_max_f32_e32 v65, v39, v39
	v_max_f32_e32 v66, v38, v38
	v_max_f32_e32 v65, v66, v65
	v_max_f32_e32 v66, v35, v35
	v_max_f32_e32 v67, v34, v34
	v_max_f32_e32 v66, v67, v66
	v_max3_f32 v65, v36, v37, v65
	v_max3_f32 v66, v32, v33, v66
	v_max3_f32 v64, v64, v65, v66
	v_max_f32_e32 v65, v31, v31
	v_max_f32_e32 v66, v30, v30
	v_max_f32_e32 v65, v66, v65
	v_max_f32_e32 v66, v27, v27
	v_max_f32_e32 v67, v26, v26
	v_max_f32_e32 v66, v67, v66
	v_mfma_f32_16x16x32_bf16 v[76:79], v[76:79], v[230:233], v[80:83]
	v_max3_f32 v65, v28, v29, v65
	v_max3_f32 v66, v24, v25, v66
	v_max3_f32 v64, v64, v65, v66
	v_max_f32_e32 v65, v23, v23
	v_max_f32_e32 v66, v22, v22
	v_max_f32_e32 v65, v66, v65
	v_max_f32_e32 v66, v19, v19
	v_max_f32_e32 v67, v18, v18
	v_max_f32_e32 v66, v67, v66
	v_mfma_f32_16x16x32_bf16 v[68:71], v[68:71], v[234:237], v[76:79]
	v_max3_f32 v65, v20, v21, v65
	v_max3_f32 v66, v16, v17, v66
	v_max3_f32 v64, v64, v65, v66
	v_max_f32_e32 v65, v15, v15
	v_max_f32_e32 v66, v14, v14
	v_max_f32_e32 v65, v66, v65
	v_max_f32_e32 v66, v11, v11
	v_max_f32_e32 v67, v10, v10
	v_max_f32_e32 v66, v67, v66
	v_mfma_f32_16x16x32_bf16 v[4:7], v[4:7], v[238:241], v[68:71]
	v_max3_f32 v65, v12, v13, v65
	v_max3_f32 v66, v8, v9, v66
	v_max3_f32 v64, v64, v65, v66
	v_max_f32_e32 v67, v2, v2
	s_nop 3
	v_max_f32_e32 v65, v7, v7
	v_max_f32_e32 v66, v6, v6
	v_max_f32_e32 v65, v66, v65
	v_max_f32_e32 v66, v3, v3
	v_max_f32_e32 v66, v67, v66
	v_max3_f32 v65, v4, v5, v65
	v_max3_f32 v66, v0, v1, v66
	v_max3_f32 v65, v64, v65, v66
	v_and_b32_e32 v66, 64, v156
	v_xor_b32_e32 v64, 16, v156
	v_add_u32_e32 v66, 64, v66
	v_cmp_lt_i32_e32 vcc, v64, v66
	s_waitcnt vmcnt(0)
	s_waitcnt vmcnt(0)
	s_barrier
	v_cndmask_b32_e32 v64, v156, v64, vcc
	v_lshlrev_b32_e32 v64, 2, v64
	ds_bpermute_b32 v67, v64, v65
	s_waitcnt lgkmcnt(0)
	v_max_f32_e32 v67, v67, v67
	v_max_f32_e32 v67, v65, v67
	v_xor_b32_e32 v65, 32, v156
	v_cmp_lt_i32_e32 vcc, v65, v66
	s_nop 1
	v_cndmask_b32_e32 v65, v156, v65, vcc
	v_lshlrev_b32_e32 v65, 2, v65
	ds_bpermute_b32 v66, v65, v67
	s_waitcnt lgkmcnt(0)
	v_max_f32_e32 v66, v66, v66
	v_max_f32_e32 v66, v67, v66
	v_sub_f32_e32 v60, v60, v66
	v_mul_f32_e32 v60, 0x3d3504f3, v60
	v_sub_f32_e32 v61, v61, v66
	v_mul_f32_e32 v60, 0x3fb8aa3b, v60
	v_mul_f32_e32 v61, 0x3d3504f3, v61
	v_sub_f32_e32 v62, v62, v66
	v_exp_f32_e32 v60, v60
	v_mul_f32_e32 v61, 0x3fb8aa3b, v61
	v_mul_f32_e32 v62, 0x3d3504f3, v62
	v_sub_f32_e32 v63, v63, v66
	v_exp_f32_e32 v61, v61
	v_mul_f32_e32 v62, 0x3fb8aa3b, v62
	v_mul_f32_e32 v63, 0x3d3504f3, v63
	v_sub_f32_e32 v52, v52, v66
	v_exp_f32_e32 v62, v62
	v_mul_f32_e32 v63, 0x3fb8aa3b, v63
	v_mul_f32_e32 v52, 0x3d3504f3, v52
	v_sub_f32_e32 v53, v53, v66
	v_exp_f32_e32 v63, v63
	v_mul_f32_e32 v52, 0x3fb8aa3b, v52
	v_mul_f32_e32 v53, 0x3d3504f3, v53
	v_sub_f32_e32 v54, v54, v66
	v_add_f32_e32 v67, 0, v60
	v_exp_f32_e32 v52, v52
	v_mul_f32_e32 v53, 0x3fb8aa3b, v53
	v_mul_f32_e32 v54, 0x3d3504f3, v54
	v_sub_f32_e32 v55, v55, v66
	v_add_f32_e32 v67, v61, v67
	v_exp_f32_e32 v53, v53
	v_mul_f32_e32 v54, 0x3fb8aa3b, v54
	v_mul_f32_e32 v55, 0x3d3504f3, v55
	v_sub_f32_e32 v56, v56, v66
	v_add_f32_e32 v67, v62, v67
	v_exp_f32_e32 v54, v54
	v_mul_f32_e32 v55, 0x3fb8aa3b, v55
	v_mul_f32_e32 v56, 0x3d3504f3, v56
	v_sub_f32_e32 v57, v57, v66
	v_add_f32_e32 v67, v63, v67
	v_exp_f32_e32 v55, v55
	v_mul_f32_e32 v56, 0x3fb8aa3b, v56
	v_mul_f32_e32 v57, 0x3d3504f3, v57
	v_sub_f32_e32 v58, v58, v66
	v_add_f32_e32 v67, v52, v67
	v_exp_f32_e32 v56, v56
	v_mul_f32_e32 v57, 0x3fb8aa3b, v57
	v_mul_f32_e32 v58, 0x3d3504f3, v58
	v_sub_f32_e32 v59, v59, v66
	v_add_f32_e32 v67, v53, v67
	v_exp_f32_e32 v57, v57
	v_mul_f32_e32 v58, 0x3fb8aa3b, v58
	v_mul_f32_e32 v59, 0x3d3504f3, v59
	v_sub_f32_e32 v48, v48, v66
	v_add_f32_e32 v67, v54, v67
	v_exp_f32_e32 v58, v58
	v_mul_f32_e32 v59, 0x3fb8aa3b, v59
	v_mul_f32_e32 v48, 0x3d3504f3, v48
	v_sub_f32_e32 v49, v49, v66
	v_add_f32_e32 v67, v55, v67
	v_exp_f32_e32 v59, v59
	v_mul_f32_e32 v48, 0x3fb8aa3b, v48
	v_mul_f32_e32 v49, 0x3d3504f3, v49
	v_sub_f32_e32 v50, v50, v66
	v_add_f32_e32 v67, v56, v67
	v_exp_f32_e32 v48, v48
	v_mul_f32_e32 v49, 0x3fb8aa3b, v49
	v_mul_f32_e32 v50, 0x3d3504f3, v50
	v_sub_f32_e32 v51, v51, v66
	v_add_f32_e32 v67, v57, v67
	v_exp_f32_e32 v49, v49
	v_mul_f32_e32 v50, 0x3fb8aa3b, v50
	v_mul_f32_e32 v51, 0x3d3504f3, v51
	v_sub_f32_e32 v44, v44, v66
	v_add_f32_e32 v67, v58, v67
	v_exp_f32_e32 v50, v50
	v_mul_f32_e32 v51, 0x3fb8aa3b, v51
	v_mul_f32_e32 v44, 0x3d3504f3, v44
	v_sub_f32_e32 v45, v45, v66
	v_add_f32_e32 v67, v59, v67
	v_exp_f32_e32 v51, v51
	v_mul_f32_e32 v44, 0x3fb8aa3b, v44
	v_mul_f32_e32 v45, 0x3d3504f3, v45
	v_sub_f32_e32 v46, v46, v66
	v_add_f32_e32 v67, v48, v67
	v_exp_f32_e32 v44, v44
	v_mul_f32_e32 v45, 0x3fb8aa3b, v45
	v_mul_f32_e32 v46, 0x3d3504f3, v46
	v_sub_f32_e32 v47, v47, v66
	v_add_f32_e32 v67, v49, v67
	v_exp_f32_e32 v45, v45
	v_mul_f32_e32 v46, 0x3fb8aa3b, v46
	v_mul_f32_e32 v47, 0x3d3504f3, v47
	v_sub_f32_e32 v40, v40, v66
	v_add_f32_e32 v67, v50, v67
	v_exp_f32_e32 v46, v46
	v_mul_f32_e32 v47, 0x3fb8aa3b, v47
	v_mul_f32_e32 v40, 0x3d3504f3, v40
	v_sub_f32_e32 v41, v41, v66
	v_add_f32_e32 v67, v51, v67
	v_exp_f32_e32 v47, v47
	v_mul_f32_e32 v40, 0x3fb8aa3b, v40
	v_mul_f32_e32 v41, 0x3d3504f3, v41
	v_sub_f32_e32 v42, v42, v66
	v_add_f32_e32 v67, v44, v67
	v_exp_f32_e32 v40, v40
	v_mul_f32_e32 v41, 0x3fb8aa3b, v41
	v_mul_f32_e32 v42, 0x3d3504f3, v42
	v_sub_f32_e32 v43, v43, v66
	v_add_f32_e32 v67, v45, v67
	v_exp_f32_e32 v41, v41
	v_mul_f32_e32 v42, 0x3fb8aa3b, v42
	v_mul_f32_e32 v43, 0x3d3504f3, v43
	v_sub_f32_e32 v36, v36, v66
	v_add_f32_e32 v67, v46, v67
	v_exp_f32_e32 v42, v42
	v_mul_f32_e32 v43, 0x3fb8aa3b, v43
	v_mul_f32_e32 v36, 0x3d3504f3, v36
	v_sub_f32_e32 v37, v37, v66
	v_add_f32_e32 v67, v47, v67
	v_exp_f32_e32 v43, v43
	v_mul_f32_e32 v36, 0x3fb8aa3b, v36
	v_mul_f32_e32 v37, 0x3d3504f3, v37
	v_sub_f32_e32 v38, v38, v66
	v_add_f32_e32 v67, v40, v67
	v_exp_f32_e32 v36, v36
	v_mul_f32_e32 v37, 0x3fb8aa3b, v37
	v_mul_f32_e32 v38, 0x3d3504f3, v38
	v_sub_f32_e32 v39, v39, v66
	v_add_f32_e32 v67, v41, v67
	v_exp_f32_e32 v37, v37
	v_mul_f32_e32 v38, 0x3fb8aa3b, v38
	v_mul_f32_e32 v39, 0x3d3504f3, v39
	v_sub_f32_e32 v32, v32, v66
	v_add_f32_e32 v67, v42, v67
	v_exp_f32_e32 v38, v38
	v_mul_f32_e32 v39, 0x3fb8aa3b, v39
	v_mul_f32_e32 v32, 0x3d3504f3, v32
	v_sub_f32_e32 v33, v33, v66
	v_add_f32_e32 v67, v43, v67
	v_exp_f32_e32 v39, v39
	v_mul_f32_e32 v32, 0x3fb8aa3b, v32
	v_mul_f32_e32 v33, 0x3d3504f3, v33
	v_sub_f32_e32 v34, v34, v66
	v_add_f32_e32 v67, v36, v67
	v_exp_f32_e32 v32, v32
	v_mul_f32_e32 v33, 0x3fb8aa3b, v33
	v_mul_f32_e32 v34, 0x3d3504f3, v34
	v_sub_f32_e32 v35, v35, v66
	v_add_f32_e32 v67, v37, v67
	v_exp_f32_e32 v33, v33
	v_mul_f32_e32 v34, 0x3fb8aa3b, v34
	v_mul_f32_e32 v35, 0x3d3504f3, v35
	v_sub_f32_e32 v28, v28, v66
	v_add_f32_e32 v67, v38, v67
	v_exp_f32_e32 v34, v34
	v_mul_f32_e32 v35, 0x3fb8aa3b, v35
	v_mul_f32_e32 v28, 0x3d3504f3, v28
	v_add_f32_e32 v67, v39, v67
	v_exp_f32_e32 v35, v35
	v_mul_f32_e32 v28, 0x3fb8aa3b, v28
	v_add_f32_e32 v67, v32, v67
	v_exp_f32_e32 v68, v28
	v_add_f32_e32 v67, v33, v67
	v_sub_f32_e32 v29, v29, v66
	v_add_f32_e32 v67, v34, v67
	v_mul_f32_e32 v29, 0x3d3504f3, v29
	v_add_f32_e32 v67, v35, v67
	v_mul_f32_e32 v29, 0x3fb8aa3b, v29
	v_add_f32_e32 v28, v68, v67
	v_exp_f32_e32 v67, v29
	v_sub_f32_e32 v29, v30, v66
	v_mul_f32_e32 v29, 0x3d3504f3, v29
	v_sub_f32_e32 v25, v25, v66
	v_mul_f32_e32 v29, 0x3fb8aa3b, v29
	v_mul_f32_e32 v25, 0x3d3504f3, v25
	v_exp_f32_e32 v69, v29
	v_sub_f32_e32 v29, v31, v66
	v_mul_f32_e32 v25, 0x3fb8aa3b, v25
	v_mul_f32_e32 v29, 0x3d3504f3, v29
	v_sub_f32_e32 v24, v24, v66
	v_exp_f32_e32 v72, v25
	v_sub_f32_e32 v25, v26, v66
	v_mul_f32_e32 v29, 0x3fb8aa3b, v29
	v_mul_f32_e32 v24, 0x3d3504f3, v24
	v_mul_f32_e32 v25, 0x3d3504f3, v25
	v_sub_f32_e32 v21, v21, v66
	v_exp_f32_e32 v70, v29
	v_mul_f32_e32 v24, 0x3fb8aa3b, v24
	v_mul_f32_e32 v25, 0x3fb8aa3b, v25
	v_mul_f32_e32 v21, 0x3d3504f3, v21
	v_exp_f32_e32 v71, v24
	v_exp_f32_e32 v73, v25
	v_sub_f32_e32 v25, v27, v66
	v_mul_f32_e32 v21, 0x3fb8aa3b, v21
	v_add_f32_e32 v28, v67, v28
	v_mul_f32_e32 v25, 0x3d3504f3, v25
	v_sub_f32_e32 v20, v20, v66
	v_exp_f32_e32 v76, v21
	v_sub_f32_e32 v21, v22, v66
	v_add_f32_e32 v28, v69, v28
	v_mul_f32_e32 v25, 0x3fb8aa3b, v25
	v_mul_f32_e32 v20, 0x3d3504f3, v20
	v_mul_f32_e32 v21, 0x3d3504f3, v21
	v_sub_f32_e32 v17, v17, v66
	v_add_f32_e32 v28, v70, v28
	v_exp_f32_e32 v74, v25
	v_mul_f32_e32 v20, 0x3fb8aa3b, v20
	v_mul_f32_e32 v21, 0x3fb8aa3b, v21
	v_mul_f32_e32 v17, 0x3d3504f3, v17
	v_add_f32_e32 v24, v71, v28
	v_exp_f32_e32 v75, v20
	v_exp_f32_e32 v77, v21
	v_sub_f32_e32 v21, v23, v66
	v_mul_f32_e32 v17, 0x3fb8aa3b, v17
	v_add_f32_e32 v24, v72, v24
	v_mul_f32_e32 v21, 0x3d3504f3, v21
	v_sub_f32_e32 v16, v16, v66
	v_exp_f32_e32 v80, v17
	v_sub_f32_e32 v17, v18, v66
	v_add_f32_e32 v24, v73, v24
	v_mul_f32_e32 v21, 0x3fb8aa3b, v21
	v_mul_f32_e32 v16, 0x3d3504f3, v16
	v_mul_f32_e32 v17, 0x3d3504f3, v17
	v_add_f32_e32 v24, v74, v24
	v_exp_f32_e32 v78, v21
	v_mul_f32_e32 v16, 0x3fb8aa3b, v16
	v_mul_f32_e32 v17, 0x3fb8aa3b, v17
	v_add_f32_e32 v20, v75, v24
	v_exp_f32_e32 v79, v16
	v_exp_f32_e32 v81, v17
	v_sub_f32_e32 v17, v19, v66
	v_add_f32_e32 v20, v76, v20
	v_mul_f32_e32 v17, 0x3d3504f3, v17
	v_sub_f32_e32 v12, v12, v66
	v_add_f32_e32 v20, v77, v20
	v_mul_f32_e32 v17, 0x3fb8aa3b, v17
	v_mul_f32_e32 v12, 0x3d3504f3, v12
	v_sub_f32_e32 v13, v13, v66
	v_sub_f32_e32 v9, v9, v66
	v_add_f32_e32 v20, v78, v20
	v_exp_f32_e32 v82, v17
	v_mul_f32_e32 v12, 0x3fb8aa3b, v12
	v_mul_f32_e32 v13, 0x3d3504f3, v13
	v_sub_f32_e32 v14, v14, v66
	v_mul_f32_e32 v9, 0x3d3504f3, v9
	v_add_f32_e32 v16, v79, v20
	v_exp_f32_e32 v12, v12
	v_mul_f32_e32 v13, 0x3fb8aa3b, v13
	v_mul_f32_e32 v14, 0x3d3504f3, v14
	v_sub_f32_e32 v15, v15, v66
	v_mul_f32_e32 v9, 0x3fb8aa3b, v9
	v_add_f32_e32 v16, v80, v16
	v_exp_f32_e32 v13, v13
	v_mul_f32_e32 v14, 0x3fb8aa3b, v14
	v_mul_f32_e32 v15, 0x3d3504f3, v15
	v_sub_f32_e32 v8, v8, v66
	v_exp_f32_e32 v84, v9
	v_sub_f32_e32 v9, v10, v66
	v_add_f32_e32 v16, v81, v16
	v_exp_f32_e32 v14, v14
	v_mul_f32_e32 v15, 0x3fb8aa3b, v15
	v_mul_f32_e32 v8, 0x3d3504f3, v8
	v_mul_f32_e32 v9, 0x3d3504f3, v9
	v_sub_f32_e32 v5, v5, v66
	v_add_f32_e32 v16, v82, v16
	v_exp_f32_e32 v15, v15
	v_mul_f32_e32 v8, 0x3fb8aa3b, v8
	v_mul_f32_e32 v9, 0x3fb8aa3b, v9
	v_mul_f32_e32 v5, 0x3d3504f3, v5
	v_add_f32_e32 v16, v12, v16
	v_exp_f32_e32 v83, v8
	v_exp_f32_e32 v85, v9
	v_sub_f32_e32 v9, v11, v66
	v_mul_f32_e32 v5, 0x3fb8aa3b, v5
	v_add_f32_e32 v16, v13, v16
	v_mul_f32_e32 v9, 0x3d3504f3, v9
	v_sub_f32_e32 v4, v4, v66
	v_exp_f32_e32 v88, v5
	v_sub_f32_e32 v5, v6, v66
	v_add_f32_e32 v16, v14, v16
	v_mul_f32_e32 v9, 0x3fb8aa3b, v9
	v_mul_f32_e32 v4, 0x3d3504f3, v4
	v_mul_f32_e32 v5, 0x3d3504f3, v5
	v_sub_f32_e32 v1, v1, v66
	v_add_f32_e32 v16, v15, v16
	v_exp_f32_e32 v86, v9
	v_mul_f32_e32 v4, 0x3fb8aa3b, v4
	v_mul_f32_e32 v5, 0x3fb8aa3b, v5
	v_mul_f32_e32 v1, 0x3d3504f3, v1
	v_add_f32_e32 v8, v83, v16
	v_exp_f32_e32 v87, v4
	v_exp_f32_e32 v89, v5
	v_sub_f32_e32 v5, v7, v66
	v_mul_f32_e32 v1, 0x3fb8aa3b, v1
	v_add_f32_e32 v8, v84, v8
	v_mul_f32_e32 v5, 0x3d3504f3, v5
	v_sub_f32_e32 v0, v0, v66
	v_exp_f32_e32 v92, v1
	v_sub_f32_e32 v1, v2, v66
	v_add_f32_e32 v8, v85, v8
	v_mul_f32_e32 v5, 0x3fb8aa3b, v5
	v_mul_f32_e32 v0, 0x3d3504f3, v0
	v_mul_f32_e32 v1, 0x3d3504f3, v1
	v_add_f32_e32 v8, v86, v8
	v_exp_f32_e32 v90, v5
	v_mul_f32_e32 v0, 0x3fb8aa3b, v0
	v_mul_f32_e32 v1, 0x3fb8aa3b, v1
	v_add_f32_e32 v4, v87, v8
	v_exp_f32_e32 v91, v0
	v_exp_f32_e32 v93, v1
	v_sub_f32_e32 v1, v3, v66
	v_add_f32_e32 v4, v88, v4
	v_mul_f32_e32 v1, 0x3d3504f3, v1
	v_add_f32_e32 v4, v89, v4
	v_mul_f32_e32 v1, 0x3fb8aa3b, v1
	v_add_f32_e32 v4, v90, v4
	v_exp_f32_e32 v3, v1
	v_add_f32_e32 v0, v91, v4
	v_add_f32_e32 v0, v92, v0
	v_add_f32_e32 v0, v93, v0
	v_add_f32_e32 v0, v3, v0
	ds_bpermute_b32 v1, v64, v0
	v_cvt_pk_bf16_f32 v18, v32, v33
	v_cvt_pk_bf16_f32 v19, v34, v35
	v_cvt_pk_bf16_f32 v16, v36, v37
	v_cvt_pk_bf16_f32 v24, v60, v61
	s_waitcnt lgkmcnt(0)
	v_add_f32_e32 v0, v0, v1
	ds_bpermute_b32 v1, v65, v0
	v_cvt_pk_bf16_f32 v25, v62, v63
	v_cvt_pk_bf16_f32 v26, v52, v53
	v_cvt_pk_bf16_f32 v27, v54, v55
	v_cvt_pk_bf16_f32 v28, v56, v57
	s_waitcnt lgkmcnt(0)
	v_add_f32_e32 v64, v0, v1
	v_div_scale_f32 v32, s[64:65], v64, v64, 1.0
	v_rcp_f32_e32 v33, v32
	v_cvt_pk_bf16_f32 v29, v58, v59
	v_cvt_pk_bf16_f32 v30, v48, v49
	v_cvt_pk_bf16_f32 v31, v50, v51
	v_fma_f32 v34, -v32, v33, 1.0
	v_fmac_f32_e32 v33, v34, v33
	v_div_scale_f32 v34, vcc, 1.0, v64, 1.0
	v_mul_f32_e32 v35, v34, v33
	v_fma_f32 v36, -v32, v35, v34
	v_fmac_f32_e32 v35, v36, v33
	v_fma_f32 v32, -v32, v35, v34
	v_lshl_add_u64 v[36:37], s[44:45], 0, v[112:113]
	v_div_fmas_f32 v32, v32, v33, v35
	v_lshl_or_b32 v34, s63, 15, v153
	v_lshlrev_b64 v[36:37], 12, v[36:37]
	v_div_fixup_f32 v32, v32, v64, 1.0
	v_add_u32_e32 v34, v34, v119
	v_mov_b32_e32 v35, v113
	v_or_b32_e32 v36, s62, v36
	v_cvt_pk_bf16_f32 v20, v44, v45
	v_cvt_pk_bf16_f32 v21, v46, v47
	v_cvt_pk_bf16_f32 v22, v40, v41
	v_cvt_pk_bf16_f32 v23, v42, v43
	v_cvt_pk_bf16_f32 v17, v38, v39
	v_cvt_pk_bf16_f32 v4, v68, v67
	v_cvt_pk_bf16_f32 v5, v69, v70
	v_cvt_pk_bf16_f32 v6, v71, v72
	v_cvt_pk_bf16_f32 v7, v73, v74
	v_cvt_pk_bf16_f32 v8, v75, v76
	v_cvt_pk_bf16_f32 v9, v77, v78
	v_cvt_pk_bf16_f32 v10, v79, v80
	v_cvt_pk_bf16_f32 v11, v81, v82
	v_cvt_pk_bf16_f32 v12, v12, v13
	v_cvt_pk_bf16_f32 v13, v14, v15
	v_cvt_pk_bf16_f32 v14, v83, v84
	v_cvt_pk_bf16_f32 v15, v85, v86
	v_cvt_pk_bf16_f32 v0, v87, v88
	v_cvt_pk_bf16_f32 v1, v89, v90
	v_cvt_pk_bf16_f32 v2, v91, v92
	v_cvt_pk_bf16_f32 v3, v93, v3
	v_mov_b32_e32 v33, v32
	v_lshl_add_u64 v[34:35], s[48:49], 0, v[34:35]
	v_lshl_add_u64 v[36:37], v[114:115], 0, v[36:37]
	s_mov_b64 s[44:45], 0
.LBB0_1839:
	s_and_b32 s47, s46, 0x10000
	s_add_i32 s46, s46, 0x10000
	s_and_b32 s48, s46, 0x10000
	v_lshl_add_u64 v[38:39], v[34:35], 0, s[44:45]
	s_add_i32 s48, s0, s48
	v_lshl_add_u64 v[40:41], v[38:39], 0, s[20:21]
	s_mov_b32 m0, s48
	v_lshl_add_u64 v[42:43], v[38:39], 0, s[28:29]
	global_load_lds_dwordx4 v[40:41], off
	s_add_i32 m0, s48, 0x2000
	v_lshl_add_u64 v[44:45], v[38:39], 0, s[30:31]
	global_load_lds_dwordx4 v[42:43], off
	s_add_i32 m0, s48, 0x4000
	v_lshl_add_u64 v[46:47], v[38:39], 0, s[34:35]
	global_load_lds_dwordx4 v[44:45], off
	s_add_i32 m0, s48, 0x6000
	v_lshl_add_u64 v[48:49], v[38:39], 0, s[36:37]
	global_load_lds_dwordx4 v[46:47], off
	s_add_i32 m0, s48, 0x8000
	v_lshl_add_u64 v[50:51], v[38:39], 0, s[38:39]
	global_load_lds_dwordx4 v[48:49], off
	s_add_i32 m0, s48, 0xa000
	v_lshl_add_u64 v[52:53], v[38:39], 0, s[40:41]
	global_load_lds_dwordx4 v[50:51], off
	s_add_i32 m0, s48, 0xc000
	s_add_i32 s47, s47, 0
	v_lshl_add_u64 v[38:39], v[38:39], 0, s[42:43]
	global_load_lds_dwordx4 v[52:53], off
	s_add_i32 m0, s48, 0xe000
	v_add_u32_e32 v56, s47, v133
	global_load_lds_dwordx4 v[38:39], off
	v_add_u32_e32 v58, s47, v145
	ds_read_b64_tr_b16 v[38:39], v56
	ds_read_b64_tr_b16 v[40:41], v58
	ds_read_b64_tr_b16 v[44:45], v58 offset:8192
	ds_read_b64_tr_b16 v[42:43], v56 offset:8192
	ds_read_b64_tr_b16 v[46:47], v56 offset:16384
	ds_read_b64_tr_b16 v[50:51], v56 offset:24576
	ds_read_b64_tr_b16 v[48:49], v58 offset:16384
	ds_read_b64_tr_b16 v[52:53], v58 offset:24576
	s_waitcnt lgkmcnt(0)
	v_mfma_f32_16x16x32_bf16 v[38:41], v[38:41], v[24:27], 0
	v_add_u32_e32 v60, s47, v146
	v_mfma_f32_16x16x32_bf16 v[38:41], v[42:45], v[28:31], v[38:41]
	ds_read_b64_tr_b16 v[42:43], v56 offset:32768
	ds_read_b64_tr_b16 v[44:45], v58 offset:32768
	v_mfma_f32_16x16x32_bf16 v[38:41], v[46:49], v[20:23], v[38:41]
	ds_read_b64_tr_b16 v[48:49], v58 offset:40960
	ds_read_b64_tr_b16 v[46:47], v56 offset:40960
	ds_read_b64_tr_b16 v[54:55], v56 offset:49152
	v_mfma_f32_16x16x32_bf16 v[38:41], v[50:53], v[16:19], v[38:41]
	ds_read_b64_tr_b16 v[50:51], v56 offset:57344
	ds_read_b64_tr_b16 v[56:57], v58 offset:49152
	ds_read_b64_tr_b16 v[52:53], v58 offset:57344
	v_add_u32_e32 v58, s47, v134
	s_waitcnt lgkmcnt(0)
	v_mfma_f32_16x16x32_bf16 v[38:41], v[42:45], v[4:7], v[38:41]
	v_mfma_f32_16x16x32_bf16 v[38:41], v[46:49], v[8:11], v[38:41]
	v_mfma_f32_16x16x32_bf16 v[40:43], v[54:57], v[12:15], v[38:41]
	v_mfma_f32_16x16x32_bf16 v[40:43], v[50:53], v[0:3], v[40:43]
	s_nop 5
	v_lshl_add_u64 v[38:39], v[36:37], 0, s[44:45]
	s_add_u32 s44, s44, 0x100
	s_addc_u32 s45, s45, 0
	s_cmpk_lg_i32 s44, 0x300
	v_pk_mul_f32 v[40:41], v[32:33], v[40:41]
	v_pk_mul_f32 v[42:43], v[32:33], v[42:43]
	v_cvt_pk_bf16_f32 v40, v40, v41
	v_cvt_pk_bf16_f32 v41, v42, v43
	global_store_dwordx2 v[38:39], v[40:41], off offset:-128
	ds_read_b64_tr_b16 v[40:41], v58
	ds_read_b64_tr_b16 v[42:43], v60
	ds_read_b64_tr_b16 v[46:47], v60 offset:8192
	ds_read_b64_tr_b16 v[44:45], v58 offset:8192
	ds_read_b64_tr_b16 v[48:49], v58 offset:16384
	ds_read_b64_tr_b16 v[52:53], v58 offset:24576
	ds_read_b64_tr_b16 v[50:51], v60 offset:16384
	ds_read_b64_tr_b16 v[54:55], v60 offset:24576
	s_waitcnt lgkmcnt(0)
	v_mfma_f32_16x16x32_bf16 v[40:43], v[40:43], v[24:27], 0
	v_mfma_f32_16x16x32_bf16 v[40:43], v[44:47], v[28:31], v[40:43]
	ds_read_b64_tr_b16 v[44:45], v58 offset:32768
	ds_read_b64_tr_b16 v[46:47], v60 offset:32768
	v_mfma_f32_16x16x32_bf16 v[40:43], v[48:51], v[20:23], v[40:43]
	ds_read_b64_tr_b16 v[50:51], v60 offset:40960
	ds_read_b64_tr_b16 v[48:49], v58 offset:40960
	ds_read_b64_tr_b16 v[56:57], v58 offset:49152
	v_mfma_f32_16x16x32_bf16 v[40:43], v[52:55], v[16:19], v[40:43]
	ds_read_b64_tr_b16 v[52:53], v58 offset:57344
	ds_read_b64_tr_b16 v[58:59], v60 offset:49152
	ds_read_b64_tr_b16 v[54:55], v60 offset:57344
	v_add_u32_e32 v60, s47, v147
	s_waitcnt lgkmcnt(0)
	v_mfma_f32_16x16x32_bf16 v[40:43], v[44:47], v[4:7], v[40:43]
	v_mfma_f32_16x16x32_bf16 v[40:43], v[48:51], v[8:11], v[40:43]
	v_mfma_f32_16x16x32_bf16 v[40:43], v[56:59], v[12:15], v[40:43]
	v_add_u32_e32 v58, s47, v135
	v_mfma_f32_16x16x32_bf16 v[40:43], v[52:55], v[0:3], v[40:43]
	s_nop 7
	v_pk_mul_f32 v[40:41], v[32:33], v[40:41]
	v_pk_mul_f32 v[42:43], v[32:33], v[42:43]
	v_cvt_pk_bf16_f32 v40, v40, v41
	v_cvt_pk_bf16_f32 v41, v42, v43
	global_store_dwordx2 v[38:39], v[40:41], off offset:-96
	ds_read_b64_tr_b16 v[40:41], v58
	ds_read_b64_tr_b16 v[42:43], v60
	ds_read_b64_tr_b16 v[46:47], v60 offset:8192
	ds_read_b64_tr_b16 v[44:45], v58 offset:8192
	ds_read_b64_tr_b16 v[48:49], v58 offset:16384
	ds_read_b64_tr_b16 v[52:53], v58 offset:24576
	ds_read_b64_tr_b16 v[50:51], v60 offset:16384
	ds_read_b64_tr_b16 v[54:55], v60 offset:24576
	s_waitcnt lgkmcnt(0)
	v_mfma_f32_16x16x32_bf16 v[40:43], v[40:43], v[24:27], 0
	v_mfma_f32_16x16x32_bf16 v[40:43], v[44:47], v[28:31], v[40:43]
	ds_read_b64_tr_b16 v[44:45], v58 offset:32768
	ds_read_b64_tr_b16 v[46:47], v60 offset:32768
	v_mfma_f32_16x16x32_bf16 v[40:43], v[48:51], v[20:23], v[40:43]
	ds_read_b64_tr_b16 v[50:51], v60 offset:40960
	ds_read_b64_tr_b16 v[48:49], v58 offset:40960
	ds_read_b64_tr_b16 v[56:57], v58 offset:49152
	v_mfma_f32_16x16x32_bf16 v[40:43], v[52:55], v[16:19], v[40:43]
	ds_read_b64_tr_b16 v[52:53], v58 offset:57344
	ds_read_b64_tr_b16 v[58:59], v60 offset:49152
	ds_read_b64_tr_b16 v[54:55], v60 offset:57344
	v_add_u32_e32 v60, s47, v148
	s_waitcnt lgkmcnt(0)
	v_mfma_f32_16x16x32_bf16 v[40:43], v[44:47], v[4:7], v[40:43]
	v_mfma_f32_16x16x32_bf16 v[40:43], v[48:51], v[8:11], v[40:43]
	v_mfma_f32_16x16x32_bf16 v[40:43], v[56:59], v[12:15], v[40:43]
	v_add_u32_e32 v58, s47, v136
	v_mfma_f32_16x16x32_bf16 v[40:43], v[52:55], v[0:3], v[40:43]
	s_nop 7
	v_pk_mul_f32 v[40:41], v[32:33], v[40:41]
	v_pk_mul_f32 v[42:43], v[32:33], v[42:43]
	v_cvt_pk_bf16_f32 v40, v40, v41
	v_cvt_pk_bf16_f32 v41, v42, v43
	global_store_dwordx2 v[38:39], v[40:41], off offset:-64
	ds_read_b64_tr_b16 v[40:41], v58
	ds_read_b64_tr_b16 v[42:43], v60
	ds_read_b64_tr_b16 v[46:47], v60 offset:8192
	ds_read_b64_tr_b16 v[44:45], v58 offset:8192
	ds_read_b64_tr_b16 v[48:49], v58 offset:16384
	ds_read_b64_tr_b16 v[52:53], v58 offset:24576
	ds_read_b64_tr_b16 v[50:51], v60 offset:16384
	ds_read_b64_tr_b16 v[54:55], v60 offset:24576
	s_waitcnt lgkmcnt(0)
	v_mfma_f32_16x16x32_bf16 v[40:43], v[40:43], v[24:27], 0
	v_mfma_f32_16x16x32_bf16 v[40:43], v[44:47], v[28:31], v[40:43]
	ds_read_b64_tr_b16 v[44:45], v58 offset:32768
	ds_read_b64_tr_b16 v[46:47], v60 offset:32768
	v_mfma_f32_16x16x32_bf16 v[40:43], v[48:51], v[20:23], v[40:43]
	ds_read_b64_tr_b16 v[50:51], v60 offset:40960
	ds_read_b64_tr_b16 v[48:49], v58 offset:40960
	ds_read_b64_tr_b16 v[56:57], v58 offset:49152
	v_mfma_f32_16x16x32_bf16 v[40:43], v[52:55], v[16:19], v[40:43]
	ds_read_b64_tr_b16 v[52:53], v58 offset:57344
	ds_read_b64_tr_b16 v[58:59], v60 offset:49152
	ds_read_b64_tr_b16 v[54:55], v60 offset:57344
	v_add_u32_e32 v60, s47, v149
	s_waitcnt lgkmcnt(0)
	v_mfma_f32_16x16x32_bf16 v[40:43], v[44:47], v[4:7], v[40:43]
	v_mfma_f32_16x16x32_bf16 v[40:43], v[48:51], v[8:11], v[40:43]
	v_mfma_f32_16x16x32_bf16 v[40:43], v[56:59], v[12:15], v[40:43]
	v_add_u32_e32 v58, s47, v137
	v_mfma_f32_16x16x32_bf16 v[40:43], v[52:55], v[0:3], v[40:43]
	s_nop 7
	v_pk_mul_f32 v[40:41], v[32:33], v[40:41]
	v_pk_mul_f32 v[42:43], v[32:33], v[42:43]
	v_cvt_pk_bf16_f32 v40, v40, v41
	v_cvt_pk_bf16_f32 v41, v42, v43
	global_store_dwordx2 v[38:39], v[40:41], off offset:-32
	ds_read_b64_tr_b16 v[40:41], v58
	ds_read_b64_tr_b16 v[42:43], v60
	ds_read_b64_tr_b16 v[46:47], v60 offset:8192
	ds_read_b64_tr_b16 v[44:45], v58 offset:8192
	ds_read_b64_tr_b16 v[48:49], v58 offset:16384
	ds_read_b64_tr_b16 v[52:53], v58 offset:24576
	ds_read_b64_tr_b16 v[50:51], v60 offset:16384
	ds_read_b64_tr_b16 v[54:55], v60 offset:24576
	s_waitcnt lgkmcnt(0)
	v_mfma_f32_16x16x32_bf16 v[40:43], v[40:43], v[24:27], 0
	v_mfma_f32_16x16x32_bf16 v[40:43], v[44:47], v[28:31], v[40:43]
	ds_read_b64_tr_b16 v[44:45], v58 offset:32768
	ds_read_b64_tr_b16 v[46:47], v60 offset:32768
	v_mfma_f32_16x16x32_bf16 v[40:43], v[48:51], v[20:23], v[40:43]
	ds_read_b64_tr_b16 v[50:51], v60 offset:40960
	ds_read_b64_tr_b16 v[48:49], v58 offset:40960
	ds_read_b64_tr_b16 v[56:57], v58 offset:49152
	v_mfma_f32_16x16x32_bf16 v[40:43], v[52:55], v[16:19], v[40:43]
	ds_read_b64_tr_b16 v[52:53], v58 offset:57344
	ds_read_b64_tr_b16 v[58:59], v60 offset:49152
	ds_read_b64_tr_b16 v[54:55], v60 offset:57344
	v_add_u32_e32 v60, s47, v150
	s_waitcnt lgkmcnt(0)
	v_mfma_f32_16x16x32_bf16 v[40:43], v[44:47], v[4:7], v[40:43]
	v_mfma_f32_16x16x32_bf16 v[40:43], v[48:51], v[8:11], v[40:43]
	v_mfma_f32_16x16x32_bf16 v[40:43], v[56:59], v[12:15], v[40:43]
	v_add_u32_e32 v58, s47, v138
	v_mfma_f32_16x16x32_bf16 v[40:43], v[52:55], v[0:3], v[40:43]
	s_nop 7
	v_pk_mul_f32 v[40:41], v[32:33], v[40:41]
	v_pk_mul_f32 v[42:43], v[32:33], v[42:43]
	v_cvt_pk_bf16_f32 v40, v40, v41
	v_cvt_pk_bf16_f32 v41, v42, v43
	global_store_dwordx2 v[38:39], v[40:41], off
	ds_read_b64_tr_b16 v[40:41], v58
	ds_read_b64_tr_b16 v[42:43], v60
	ds_read_b64_tr_b16 v[46:47], v60 offset:8192
	ds_read_b64_tr_b16 v[44:45], v58 offset:8192
	ds_read_b64_tr_b16 v[48:49], v58 offset:16384
	ds_read_b64_tr_b16 v[52:53], v58 offset:24576
	ds_read_b64_tr_b16 v[50:51], v60 offset:16384
	ds_read_b64_tr_b16 v[54:55], v60 offset:24576
	s_waitcnt lgkmcnt(0)
	v_mfma_f32_16x16x32_bf16 v[40:43], v[40:43], v[24:27], 0
	v_mfma_f32_16x16x32_bf16 v[40:43], v[44:47], v[28:31], v[40:43]
	ds_read_b64_tr_b16 v[44:45], v58 offset:32768
	ds_read_b64_tr_b16 v[46:47], v60 offset:32768
	v_mfma_f32_16x16x32_bf16 v[40:43], v[48:51], v[20:23], v[40:43]
	ds_read_b64_tr_b16 v[50:51], v60 offset:40960
	ds_read_b64_tr_b16 v[48:49], v58 offset:40960
	ds_read_b64_tr_b16 v[56:57], v58 offset:49152
	v_mfma_f32_16x16x32_bf16 v[40:43], v[52:55], v[16:19], v[40:43]
	ds_read_b64_tr_b16 v[52:53], v58 offset:57344
	ds_read_b64_tr_b16 v[58:59], v60 offset:49152
	ds_read_b64_tr_b16 v[54:55], v60 offset:57344
	v_add_u32_e32 v60, s47, v151
	s_waitcnt lgkmcnt(0)
	v_mfma_f32_16x16x32_bf16 v[40:43], v[44:47], v[4:7], v[40:43]
	v_mfma_f32_16x16x32_bf16 v[40:43], v[48:51], v[8:11], v[40:43]
	v_mfma_f32_16x16x32_bf16 v[40:43], v[56:59], v[12:15], v[40:43]
	v_add_u32_e32 v58, s47, v139
	v_mfma_f32_16x16x32_bf16 v[40:43], v[52:55], v[0:3], v[40:43]
	s_nop 7
	v_pk_mul_f32 v[40:41], v[32:33], v[40:41]
	v_pk_mul_f32 v[42:43], v[32:33], v[42:43]
	v_cvt_pk_bf16_f32 v40, v40, v41
	v_cvt_pk_bf16_f32 v41, v42, v43
	global_store_dwordx2 v[38:39], v[40:41], off offset:32
	ds_read_b64_tr_b16 v[40:41], v58
	ds_read_b64_tr_b16 v[42:43], v60
	ds_read_b64_tr_b16 v[46:47], v60 offset:8192
	ds_read_b64_tr_b16 v[44:45], v58 offset:8192
	ds_read_b64_tr_b16 v[48:49], v58 offset:16384
	ds_read_b64_tr_b16 v[52:53], v58 offset:24576
	ds_read_b64_tr_b16 v[50:51], v60 offset:16384
	ds_read_b64_tr_b16 v[54:55], v60 offset:24576
	s_waitcnt lgkmcnt(0)
	v_mfma_f32_16x16x32_bf16 v[40:43], v[40:43], v[24:27], 0
	v_mfma_f32_16x16x32_bf16 v[40:43], v[44:47], v[28:31], v[40:43]
	ds_read_b64_tr_b16 v[44:45], v58 offset:32768
	ds_read_b64_tr_b16 v[46:47], v60 offset:32768
	v_mfma_f32_16x16x32_bf16 v[40:43], v[48:51], v[20:23], v[40:43]
	ds_read_b64_tr_b16 v[50:51], v60 offset:40960
	ds_read_b64_tr_b16 v[48:49], v58 offset:40960
	ds_read_b64_tr_b16 v[56:57], v58 offset:49152
	v_mfma_f32_16x16x32_bf16 v[40:43], v[52:55], v[16:19], v[40:43]
	ds_read_b64_tr_b16 v[52:53], v58 offset:57344
	ds_read_b64_tr_b16 v[58:59], v60 offset:49152
	ds_read_b64_tr_b16 v[54:55], v60 offset:57344
	v_add_u32_e32 v60, s47, v152
	s_waitcnt lgkmcnt(0)
	v_mfma_f32_16x16x32_bf16 v[40:43], v[44:47], v[4:7], v[40:43]
	v_mfma_f32_16x16x32_bf16 v[40:43], v[48:51], v[8:11], v[40:43]
	v_mfma_f32_16x16x32_bf16 v[40:43], v[56:59], v[12:15], v[40:43]
	v_add_u32_e32 v58, s47, v140
	v_mfma_f32_16x16x32_bf16 v[40:43], v[52:55], v[0:3], v[40:43]
	s_nop 7
	v_pk_mul_f32 v[40:41], v[32:33], v[40:41]
	v_pk_mul_f32 v[42:43], v[32:33], v[42:43]
	v_cvt_pk_bf16_f32 v40, v40, v41
	v_cvt_pk_bf16_f32 v41, v42, v43
	global_store_dwordx2 v[38:39], v[40:41], off offset:64
	ds_read_b64_tr_b16 v[40:41], v58
	ds_read_b64_tr_b16 v[42:43], v60
	ds_read_b64_tr_b16 v[46:47], v60 offset:8192
	ds_read_b64_tr_b16 v[44:45], v58 offset:8192
	ds_read_b64_tr_b16 v[48:49], v58 offset:16384
	ds_read_b64_tr_b16 v[52:53], v58 offset:24576
	ds_read_b64_tr_b16 v[50:51], v60 offset:16384
	ds_read_b64_tr_b16 v[54:55], v60 offset:24576
	s_waitcnt lgkmcnt(0)
	v_mfma_f32_16x16x32_bf16 v[40:43], v[40:43], v[24:27], 0
	v_mfma_f32_16x16x32_bf16 v[40:43], v[44:47], v[28:31], v[40:43]
	ds_read_b64_tr_b16 v[44:45], v58 offset:32768
	ds_read_b64_tr_b16 v[46:47], v60 offset:32768
	v_mfma_f32_16x16x32_bf16 v[40:43], v[48:51], v[20:23], v[40:43]
	ds_read_b64_tr_b16 v[50:51], v60 offset:40960
	ds_read_b64_tr_b16 v[48:49], v58 offset:40960
	ds_read_b64_tr_b16 v[56:57], v58 offset:49152
	v_mfma_f32_16x16x32_bf16 v[40:43], v[52:55], v[16:19], v[40:43]
	ds_read_b64_tr_b16 v[52:53], v58 offset:57344
	ds_read_b64_tr_b16 v[58:59], v60 offset:49152
	ds_read_b64_tr_b16 v[54:55], v60 offset:57344
	s_waitcnt lgkmcnt(0)
	v_mfma_f32_16x16x32_bf16 v[40:43], v[44:47], v[4:7], v[40:43]
	v_mfma_f32_16x16x32_bf16 v[40:43], v[48:51], v[8:11], v[40:43]
	v_mfma_f32_16x16x32_bf16 v[40:43], v[56:59], v[12:15], v[40:43]
	v_mfma_f32_16x16x32_bf16 v[40:43], v[52:55], v[0:3], v[40:43]
	s_nop 7
	v_pk_mul_f32 v[40:41], v[32:33], v[40:41]
	v_pk_mul_f32 v[42:43], v[32:33], v[42:43]
	v_cvt_pk_bf16_f32 v40, v40, v41
	v_cvt_pk_bf16_f32 v41, v42, v43
	global_store_dwordx2 v[38:39], v[40:41], off offset:96
	s_waitcnt vmcnt(0)
	s_waitcnt vmcnt(0)
	s_barrier
	s_cbranch_scc1 .LBB0_1839
	v_add_u32_e32 v50, s56, v133
	ds_read_b64_tr_b16 v[34:35], v50
	v_add_u32_e32 v52, s56, v145
	ds_read_b64_tr_b16 v[36:37], v52
	ds_read_b64_tr_b16 v[40:41], v52 offset:8192
	ds_read_b64_tr_b16 v[38:39], v50 offset:8192
	ds_read_b64_tr_b16 v[42:43], v50 offset:16384
	ds_read_b64_tr_b16 v[46:47], v50 offset:24576
	ds_read_b64_tr_b16 v[44:45], v52 offset:16384
	ds_read_b64_tr_b16 v[48:49], v52 offset:24576
	s_lshl_b32 s0, s59, 1
	v_mov_b32_e32 v119, v113
	v_add_u32_e32 v54, s56, v134
	v_add_u32_e32 v55, s56, v146
	v_add_u32_e32 v56, s56, v135
	v_add_u32_e32 v57, s56, v147
	s_waitcnt lgkmcnt(6)
	v_mfma_f32_16x16x32_bf16 v[34:37], v[34:37], v[24:27], 0
	s_add_i32 s98, s98, s94
	s_nop 0
	s_nop 0
	s_waitcnt lgkmcnt(4)
	v_mfma_f32_16x16x32_bf16 v[34:37], v[38:41], v[28:31], v[34:37]
	ds_read_b64_tr_b16 v[38:39], v50 offset:32768
	s_cmpk_gt_i32 s98, 0x1ff
	s_waitcnt lgkmcnt(2)
	v_mfma_f32_16x16x32_bf16 v[34:37], v[42:45], v[20:23], v[34:37]
	ds_read_b64_tr_b16 v[40:41], v52 offset:32768
	ds_read_b64_tr_b16 v[44:45], v52 offset:40960
	s_waitcnt lgkmcnt(3)
	v_mfma_f32_16x16x32_bf16 v[34:37], v[46:49], v[16:19], v[34:37]
	ds_read_b64_tr_b16 v[42:43], v50 offset:40960
	ds_read_b64_tr_b16 v[46:47], v50 offset:49152
	ds_read_b64_tr_b16 v[50:51], v50 offset:57344
	ds_read_b64_tr_b16 v[48:49], v52 offset:49152
	ds_read_b64_tr_b16 v[52:53], v52 offset:57344
	s_waitcnt lgkmcnt(6)
	v_mfma_f32_16x16x32_bf16 v[34:37], v[38:41], v[4:7], v[34:37]
	v_lshl_add_u64 v[40:41], v[120:121], 1, s[60:61]
	s_waitcnt lgkmcnt(4)
	v_mfma_f32_16x16x32_bf16 v[34:37], v[42:45], v[8:11], v[34:37]
	s_waitcnt lgkmcnt(1)
	v_mfma_f32_16x16x32_bf16 v[36:39], v[46:49], v[12:15], v[34:37]
	s_waitcnt lgkmcnt(0)
	v_mfma_f32_16x16x32_bf16 v[36:39], v[50:53], v[0:3], v[36:39]
	s_nop 3
	v_lshl_add_u64 v[34:35], v[40:41], 0, s[0:1]
	v_lshl_add_u64 v[34:35], v[34:35], 0, v[118:119]
	s_nop 1
	v_pk_mul_f32 v[36:37], v[32:33], v[36:37]
	v_pk_mul_f32 v[38:39], v[32:33], v[38:39]
	v_cvt_pk_bf16_f32 v36, v36, v37
	v_cvt_pk_bf16_f32 v37, v38, v39
	global_store_dwordx2 v[34:35], v[36:37], off offset:768
	ds_read_b64_tr_b16 v[36:37], v54
	ds_read_b64_tr_b16 v[38:39], v55
	ds_read_b64_tr_b16 v[42:43], v55 offset:8192
	ds_read_b64_tr_b16 v[40:41], v54 offset:8192
	ds_read_b64_tr_b16 v[44:45], v54 offset:16384
	ds_read_b64_tr_b16 v[48:49], v54 offset:24576
	ds_read_b64_tr_b16 v[46:47], v55 offset:16384
	ds_read_b64_tr_b16 v[50:51], v55 offset:24576
	s_waitcnt lgkmcnt(6)
	v_mfma_f32_16x16x32_bf16 v[36:39], v[36:39], v[24:27], 0
	s_waitcnt lgkmcnt(4)
	v_mfma_f32_16x16x32_bf16 v[36:39], v[40:43], v[28:31], v[36:39]
	ds_read_b64_tr_b16 v[40:41], v54 offset:32768
	s_waitcnt lgkmcnt(2)
	v_mfma_f32_16x16x32_bf16 v[36:39], v[44:47], v[20:23], v[36:39]
	ds_read_b64_tr_b16 v[42:43], v55 offset:32768
	ds_read_b64_tr_b16 v[46:47], v55 offset:40960
	s_waitcnt lgkmcnt(3)
	v_mfma_f32_16x16x32_bf16 v[36:39], v[48:51], v[16:19], v[36:39]
	ds_read_b64_tr_b16 v[44:45], v54 offset:40960
	ds_read_b64_tr_b16 v[48:49], v54 offset:49152
	ds_read_b64_tr_b16 v[52:53], v54 offset:57344
	ds_read_b64_tr_b16 v[50:51], v55 offset:49152
	ds_read_b64_tr_b16 v[54:55], v55 offset:57344
	s_waitcnt lgkmcnt(6)
	v_mfma_f32_16x16x32_bf16 v[36:39], v[40:43], v[4:7], v[36:39]
	s_waitcnt lgkmcnt(4)
	v_mfma_f32_16x16x32_bf16 v[36:39], v[44:47], v[8:11], v[36:39]
	s_waitcnt lgkmcnt(1)
	v_mfma_f32_16x16x32_bf16 v[36:39], v[48:51], v[12:15], v[36:39]
	s_waitcnt lgkmcnt(0)
	v_mfma_f32_16x16x32_bf16 v[36:39], v[52:55], v[0:3], v[36:39]
	s_nop 7
	v_pk_mul_f32 v[36:37], v[32:33], v[36:37]
	v_pk_mul_f32 v[38:39], v[32:33], v[38:39]
	v_cvt_pk_bf16_f32 v36, v36, v37
	v_cvt_pk_bf16_f32 v37, v38, v39
	global_store_dwordx2 v[34:35], v[36:37], off offset:800
	ds_read_b64_tr_b16 v[36:37], v56
	ds_read_b64_tr_b16 v[38:39], v57
	ds_read_b64_tr_b16 v[42:43], v57 offset:8192
	ds_read_b64_tr_b16 v[40:41], v56 offset:8192
	ds_read_b64_tr_b16 v[44:45], v56 offset:16384
	ds_read_b64_tr_b16 v[48:49], v56 offset:24576
	ds_read_b64_tr_b16 v[46:47], v57 offset:16384
	ds_read_b64_tr_b16 v[50:51], v57 offset:24576
	s_waitcnt lgkmcnt(6)
	v_mfma_f32_16x16x32_bf16 v[36:39], v[36:39], v[24:27], 0
	s_waitcnt lgkmcnt(4)
	v_mfma_f32_16x16x32_bf16 v[36:39], v[40:43], v[28:31], v[36:39]
	ds_read_b64_tr_b16 v[40:41], v56 offset:32768
	s_waitcnt lgkmcnt(2)
	v_mfma_f32_16x16x32_bf16 v[36:39], v[44:47], v[20:23], v[36:39]
	ds_read_b64_tr_b16 v[42:43], v57 offset:32768
	ds_read_b64_tr_b16 v[46:47], v57 offset:40960
	s_waitcnt lgkmcnt(3)
	v_mfma_f32_16x16x32_bf16 v[36:39], v[48:51], v[16:19], v[36:39]
	ds_read_b64_tr_b16 v[44:45], v56 offset:40960
	ds_read_b64_tr_b16 v[48:49], v56 offset:49152
	ds_read_b64_tr_b16 v[52:53], v56 offset:57344
	ds_read_b64_tr_b16 v[50:51], v57 offset:49152
	ds_read_b64_tr_b16 v[54:55], v57 offset:57344
	v_add_u32_e32 v56, s56, v136
	v_add_u32_e32 v57, s56, v148
	s_waitcnt lgkmcnt(6)
	v_mfma_f32_16x16x32_bf16 v[36:39], v[40:43], v[4:7], v[36:39]
	s_waitcnt lgkmcnt(4)
	v_mfma_f32_16x16x32_bf16 v[36:39], v[44:47], v[8:11], v[36:39]
	s_waitcnt lgkmcnt(1)
	v_mfma_f32_16x16x32_bf16 v[36:39], v[48:51], v[12:15], v[36:39]
	s_waitcnt lgkmcnt(0)
	v_mfma_f32_16x16x32_bf16 v[36:39], v[52:55], v[0:3], v[36:39]
	s_nop 7
	v_pk_mul_f32 v[36:37], v[32:33], v[36:37]
	v_pk_mul_f32 v[38:39], v[32:33], v[38:39]
	v_cvt_pk_bf16_f32 v36, v36, v37
	v_cvt_pk_bf16_f32 v37, v38, v39
	global_store_dwordx2 v[34:35], v[36:37], off offset:832
	ds_read_b64_tr_b16 v[36:37], v56
	ds_read_b64_tr_b16 v[38:39], v57
	ds_read_b64_tr_b16 v[42:43], v57 offset:8192
	ds_read_b64_tr_b16 v[40:41], v56 offset:8192
	ds_read_b64_tr_b16 v[44:45], v56 offset:16384
	ds_read_b64_tr_b16 v[48:49], v56 offset:24576
	ds_read_b64_tr_b16 v[46:47], v57 offset:16384
	ds_read_b64_tr_b16 v[50:51], v57 offset:24576
	s_waitcnt lgkmcnt(6)
	v_mfma_f32_16x16x32_bf16 v[36:39], v[36:39], v[24:27], 0
	s_waitcnt lgkmcnt(4)
	v_mfma_f32_16x16x32_bf16 v[36:39], v[40:43], v[28:31], v[36:39]
	ds_read_b64_tr_b16 v[40:41], v56 offset:32768
	s_waitcnt lgkmcnt(2)
	v_mfma_f32_16x16x32_bf16 v[36:39], v[44:47], v[20:23], v[36:39]
	ds_read_b64_tr_b16 v[42:43], v57 offset:32768
	ds_read_b64_tr_b16 v[46:47], v57 offset:40960
	s_waitcnt lgkmcnt(3)
	v_mfma_f32_16x16x32_bf16 v[36:39], v[48:51], v[16:19], v[36:39]
	ds_read_b64_tr_b16 v[44:45], v56 offset:40960
	ds_read_b64_tr_b16 v[48:49], v56 offset:49152
	ds_read_b64_tr_b16 v[52:53], v56 offset:57344
	ds_read_b64_tr_b16 v[50:51], v57 offset:49152
	ds_read_b64_tr_b16 v[54:55], v57 offset:57344
	v_add_u32_e32 v56, s56, v137
	v_add_u32_e32 v57, s56, v149
	s_waitcnt lgkmcnt(6)
	v_mfma_f32_16x16x32_bf16 v[36:39], v[40:43], v[4:7], v[36:39]
	s_waitcnt lgkmcnt(4)
	v_mfma_f32_16x16x32_bf16 v[36:39], v[44:47], v[8:11], v[36:39]
	s_waitcnt lgkmcnt(1)
	v_mfma_f32_16x16x32_bf16 v[36:39], v[48:51], v[12:15], v[36:39]
	s_waitcnt lgkmcnt(0)
	v_mfma_f32_16x16x32_bf16 v[36:39], v[52:55], v[0:3], v[36:39]
	s_nop 7
	v_pk_mul_f32 v[36:37], v[32:33], v[36:37]
	v_pk_mul_f32 v[38:39], v[32:33], v[38:39]
	v_cvt_pk_bf16_f32 v36, v36, v37
	v_cvt_pk_bf16_f32 v37, v38, v39
	global_store_dwordx2 v[34:35], v[36:37], off offset:864
	ds_read_b64_tr_b16 v[36:37], v56
	ds_read_b64_tr_b16 v[38:39], v57
	ds_read_b64_tr_b16 v[42:43], v57 offset:8192
	ds_read_b64_tr_b16 v[40:41], v56 offset:8192
	ds_read_b64_tr_b16 v[44:45], v56 offset:16384
	ds_read_b64_tr_b16 v[48:49], v56 offset:24576
	ds_read_b64_tr_b16 v[46:47], v57 offset:16384
	ds_read_b64_tr_b16 v[50:51], v57 offset:24576
	s_waitcnt lgkmcnt(6)
	v_mfma_f32_16x16x32_bf16 v[36:39], v[36:39], v[24:27], 0
	s_waitcnt lgkmcnt(4)
	v_mfma_f32_16x16x32_bf16 v[36:39], v[40:43], v[28:31], v[36:39]
	ds_read_b64_tr_b16 v[40:41], v56 offset:32768
	s_waitcnt lgkmcnt(2)
	v_mfma_f32_16x16x32_bf16 v[36:39], v[44:47], v[20:23], v[36:39]
	ds_read_b64_tr_b16 v[42:43], v57 offset:32768
	ds_read_b64_tr_b16 v[46:47], v57 offset:40960
	s_waitcnt lgkmcnt(3)
	v_mfma_f32_16x16x32_bf16 v[36:39], v[48:51], v[16:19], v[36:39]
	ds_read_b64_tr_b16 v[44:45], v56 offset:40960
	ds_read_b64_tr_b16 v[48:49], v56 offset:49152
	ds_read_b64_tr_b16 v[52:53], v56 offset:57344
	ds_read_b64_tr_b16 v[50:51], v57 offset:49152
	ds_read_b64_tr_b16 v[54:55], v57 offset:57344
	v_add_u32_e32 v56, s56, v138
	v_add_u32_e32 v57, s56, v150
	s_waitcnt lgkmcnt(6)
	v_mfma_f32_16x16x32_bf16 v[36:39], v[40:43], v[4:7], v[36:39]
	s_waitcnt lgkmcnt(4)
	v_mfma_f32_16x16x32_bf16 v[36:39], v[44:47], v[8:11], v[36:39]
	s_waitcnt lgkmcnt(1)
	v_mfma_f32_16x16x32_bf16 v[36:39], v[48:51], v[12:15], v[36:39]
	s_waitcnt lgkmcnt(0)
	v_mfma_f32_16x16x32_bf16 v[36:39], v[52:55], v[0:3], v[36:39]
	s_nop 7
	v_pk_mul_f32 v[36:37], v[32:33], v[36:37]
	v_pk_mul_f32 v[38:39], v[32:33], v[38:39]
	v_cvt_pk_bf16_f32 v36, v36, v37
	v_cvt_pk_bf16_f32 v37, v38, v39
	global_store_dwordx2 v[34:35], v[36:37], off offset:896
	ds_read_b64_tr_b16 v[36:37], v56
	ds_read_b64_tr_b16 v[38:39], v57
	ds_read_b64_tr_b16 v[42:43], v57 offset:8192
	ds_read_b64_tr_b16 v[40:41], v56 offset:8192
	ds_read_b64_tr_b16 v[44:45], v56 offset:16384
	ds_read_b64_tr_b16 v[48:49], v56 offset:24576
	ds_read_b64_tr_b16 v[46:47], v57 offset:16384
	ds_read_b64_tr_b16 v[50:51], v57 offset:24576
	s_waitcnt lgkmcnt(6)
	v_mfma_f32_16x16x32_bf16 v[36:39], v[36:39], v[24:27], 0
	s_waitcnt lgkmcnt(4)
	v_mfma_f32_16x16x32_bf16 v[36:39], v[40:43], v[28:31], v[36:39]
	ds_read_b64_tr_b16 v[40:41], v56 offset:32768
	s_waitcnt lgkmcnt(2)
	v_mfma_f32_16x16x32_bf16 v[36:39], v[44:47], v[20:23], v[36:39]
	ds_read_b64_tr_b16 v[42:43], v57 offset:32768
	ds_read_b64_tr_b16 v[46:47], v57 offset:40960
	s_waitcnt lgkmcnt(3)
	v_mfma_f32_16x16x32_bf16 v[36:39], v[48:51], v[16:19], v[36:39]
	ds_read_b64_tr_b16 v[44:45], v56 offset:40960
	ds_read_b64_tr_b16 v[48:49], v56 offset:49152
	ds_read_b64_tr_b16 v[52:53], v56 offset:57344
	ds_read_b64_tr_b16 v[50:51], v57 offset:49152
	ds_read_b64_tr_b16 v[54:55], v57 offset:57344
	v_add_u32_e32 v56, s56, v139
	v_add_u32_e32 v57, s56, v151
	s_waitcnt lgkmcnt(6)
	v_mfma_f32_16x16x32_bf16 v[36:39], v[40:43], v[4:7], v[36:39]
	s_waitcnt lgkmcnt(4)
	v_mfma_f32_16x16x32_bf16 v[36:39], v[44:47], v[8:11], v[36:39]
	s_waitcnt lgkmcnt(1)
	v_mfma_f32_16x16x32_bf16 v[36:39], v[48:51], v[12:15], v[36:39]
	s_waitcnt lgkmcnt(0)
	v_mfma_f32_16x16x32_bf16 v[36:39], v[52:55], v[0:3], v[36:39]
	s_nop 7
	v_pk_mul_f32 v[36:37], v[32:33], v[36:37]
	v_pk_mul_f32 v[38:39], v[32:33], v[38:39]
	v_cvt_pk_bf16_f32 v36, v36, v37
	v_cvt_pk_bf16_f32 v37, v38, v39
	global_store_dwordx2 v[34:35], v[36:37], off offset:928
	ds_read_b64_tr_b16 v[36:37], v56
	ds_read_b64_tr_b16 v[38:39], v57
	ds_read_b64_tr_b16 v[42:43], v57 offset:8192
	ds_read_b64_tr_b16 v[40:41], v56 offset:8192
	ds_read_b64_tr_b16 v[44:45], v56 offset:16384
	ds_read_b64_tr_b16 v[48:49], v56 offset:24576
	ds_read_b64_tr_b16 v[46:47], v57 offset:16384
	ds_read_b64_tr_b16 v[50:51], v57 offset:24576
	s_waitcnt lgkmcnt(6)
	v_mfma_f32_16x16x32_bf16 v[36:39], v[36:39], v[24:27], 0
	s_waitcnt lgkmcnt(4)
	v_mfma_f32_16x16x32_bf16 v[36:39], v[40:43], v[28:31], v[36:39]
	ds_read_b64_tr_b16 v[40:41], v56 offset:32768
	s_waitcnt lgkmcnt(2)
	v_mfma_f32_16x16x32_bf16 v[36:39], v[44:47], v[20:23], v[36:39]
	ds_read_b64_tr_b16 v[42:43], v57 offset:32768
	ds_read_b64_tr_b16 v[46:47], v57 offset:40960
	s_waitcnt lgkmcnt(3)
	v_mfma_f32_16x16x32_bf16 v[36:39], v[48:51], v[16:19], v[36:39]
	ds_read_b64_tr_b16 v[44:45], v56 offset:40960
	ds_read_b64_tr_b16 v[48:49], v56 offset:49152
	ds_read_b64_tr_b16 v[52:53], v56 offset:57344
	ds_read_b64_tr_b16 v[50:51], v57 offset:49152
	ds_read_b64_tr_b16 v[54:55], v57 offset:57344
	v_add_u32_e32 v56, s56, v140
	v_add_u32_e32 v57, s56, v152
	s_waitcnt lgkmcnt(6)
	v_mfma_f32_16x16x32_bf16 v[36:39], v[40:43], v[4:7], v[36:39]
	s_waitcnt lgkmcnt(4)
	v_mfma_f32_16x16x32_bf16 v[36:39], v[44:47], v[8:11], v[36:39]
	s_waitcnt lgkmcnt(1)
	v_mfma_f32_16x16x32_bf16 v[36:39], v[48:51], v[12:15], v[36:39]
	s_waitcnt lgkmcnt(0)
	v_mfma_f32_16x16x32_bf16 v[36:39], v[52:55], v[0:3], v[36:39]
	s_nop 7
	v_pk_mul_f32 v[36:37], v[32:33], v[36:37]
	v_pk_mul_f32 v[38:39], v[32:33], v[38:39]
	v_cvt_pk_bf16_f32 v36, v36, v37
	v_cvt_pk_bf16_f32 v37, v38, v39
	global_store_dwordx2 v[34:35], v[36:37], off offset:960
	ds_read_b64_tr_b16 v[36:37], v56
	ds_read_b64_tr_b16 v[38:39], v57
	ds_read_b64_tr_b16 v[42:43], v57 offset:8192
	ds_read_b64_tr_b16 v[40:41], v56 offset:8192
	ds_read_b64_tr_b16 v[44:45], v56 offset:16384
	ds_read_b64_tr_b16 v[48:49], v56 offset:24576
	ds_read_b64_tr_b16 v[46:47], v57 offset:16384
	ds_read_b64_tr_b16 v[50:51], v57 offset:24576
	s_waitcnt lgkmcnt(6)
	v_mfma_f32_16x16x32_bf16 v[24:27], v[36:39], v[24:27], 0
	s_waitcnt lgkmcnt(4)
	v_mfma_f32_16x16x32_bf16 v[24:27], v[40:43], v[28:31], v[24:27]
	ds_read_b64_tr_b16 v[28:29], v56 offset:32768
	s_waitcnt lgkmcnt(2)
	v_mfma_f32_16x16x32_bf16 v[20:23], v[44:47], v[20:23], v[24:27]
	ds_read_b64_tr_b16 v[30:31], v57 offset:32768
	s_nop 3
	ds_read_b64_tr_b16 v[24:25], v57 offset:40960
	s_waitcnt lgkmcnt(3)
	v_mfma_f32_16x16x32_bf16 v[16:19], v[48:51], v[16:19], v[20:23]
	s_nop 2
	ds_read_b64_tr_b16 v[22:23], v56 offset:40960
	ds_read_b64_tr_b16 v[36:37], v56 offset:49152
	ds_read_b64_tr_b16 v[40:41], v56 offset:57344
	ds_read_b64_tr_b16 v[38:39], v57 offset:49152
	ds_read_b64_tr_b16 v[42:43], v57 offset:57344
	s_waitcnt lgkmcnt(6)
	v_mfma_f32_16x16x32_bf16 v[4:7], v[28:31], v[4:7], v[16:19]
	s_waitcnt lgkmcnt(4)
	v_mfma_f32_16x16x32_bf16 v[4:7], v[22:25], v[8:11], v[4:7]
	s_waitcnt lgkmcnt(1)
	v_mfma_f32_16x16x32_bf16 v[4:7], v[36:39], v[12:15], v[4:7]
	s_waitcnt lgkmcnt(0)
	v_mfma_f32_16x16x32_bf16 v[0:3], v[40:43], v[0:3], v[4:7]
	s_nop 7
	v_pk_mul_f32 v[0:1], v[32:33], v[0:1]
	v_pk_mul_f32 v[2:3], v[32:33], v[2:3]
	v_cvt_pk_bf16_f32 v0, v0, v1
	v_cvt_pk_bf16_f32 v1, v2, v3
	global_store_dwordx2 v[34:35], v[0:1], off offset:992
	s_waitcnt vmcnt(0)
	s_barrier
	s_cbranch_scc0 .LBB0_1838

	.amdhsa_kernel _Z8mega_fwd6Params
		.amdhsa_group_segment_fixed_size 0
		.amdhsa_private_segment_fixed_size 0
		.amdhsa_kernarg_size 568
		.amdhsa_user_sgpr_count 2
		.amdhsa_user_sgpr_dispatch_ptr 0
		.amdhsa_user_sgpr_queue_ptr 0
		.amdhsa_user_sgpr_kernarg_segment_ptr 1
		.amdhsa_user_sgpr_dispatch_id 0
		.amdhsa_user_sgpr_kernarg_preload_length 0
		.amdhsa_user_sgpr_kernarg_preload_offset 0
		.amdhsa_user_sgpr_private_segment_size 0
		.amdhsa_uses_dynamic_stack 0
		.amdhsa_enable_private_segment 0
		.amdhsa_system_sgpr_workgroup_id_x 1
		.amdhsa_system_sgpr_workgroup_id_y 0
		.amdhsa_system_sgpr_workgroup_id_z 0
		.amdhsa_system_sgpr_workgroup_info 0
		.amdhsa_system_vgpr_workitem_id 2
		.amdhsa_next_free_vgpr 245
		.amdhsa_next_free_sgpr 101
		.amdhsa_accum_offset 248
		.amdhsa_reserve_vcc 1
		.amdhsa_float_round_mode_32 0
		.amdhsa_float_round_mode_16_64 0
		.amdhsa_float_denorm_mode_32 3
		.amdhsa_float_denorm_mode_16_64 3
		.amdhsa_dx10_clamp 1
		.amdhsa_ieee_mode 1
		.amdhsa_fp16_overflow 0
		.amdhsa_tg_split 0
		.amdhsa_exception_fp_ieee_invalid_op 0
		.amdhsa_exception_fp_denorm_src 0
		.amdhsa_exception_fp_ieee_div_zero 0
		.amdhsa_exception_fp_ieee_overflow 0
		.amdhsa_exception_fp_ieee_underflow 0
		.amdhsa_exception_fp_ieee_inexact 0
		.amdhsa_exception_int_div_zero 0
	.end_amdhsa_kernel

amdhsa.kernels:
  - .agpr_count:     0
    .args:
      - .offset:         0
        .size:           312
        .value_kind:     by_value
      - .offset:         312
        .size:           4
        .value_kind:     hidden_block_count_x
      - .offset:         316
        .size:           4
        .value_kind:     hidden_block_count_y
      - .offset:         320
        .size:           4
        .value_kind:     hidden_block_count_z
      - .offset:         324
        .size:           2
        .value_kind:     hidden_group_size_x
      - .offset:         326
        .size:           2
        .value_kind:     hidden_group_size_y
      - .offset:         328
        .size:           2
        .value_kind:     hidden_group_size_z
      - .offset:         330
        .size:           2
        .value_kind:     hidden_remainder_x
      - .offset:         332
        .size:           2
        .value_kind:     hidden_remainder_y
      - .offset:         334
        .size:           2
        .value_kind:     hidden_remainder_z
      - .offset:         352
        .size:           8
        .value_kind:     hidden_global_offset_x
      - .offset:         360
        .size:           8
        .value_kind:     hidden_global_offset_y
      - .offset:         368
        .size:           8
        .value_kind:     hidden_global_offset_z
      - .offset:         376
        .size:           2
        .value_kind:     hidden_grid_dims
      - .offset:         400
        .size:           8
        .value_kind:     hidden_multigrid_sync_arg
      - .offset:         432
        .size:           4
        .value_kind:     hidden_dynamic_lds_size
    .group_segment_fixed_size: 0
    .kernarg_segment_align: 8
    .kernarg_segment_size: 568
    .language:       OpenCL C
    .language_version:
      - 2
      - 0
    .max_flat_workgroup_size: 512
    .name:           _Z8mega_fwd6Params
    .private_segment_fixed_size: 0
    .sgpr_count:     107
    .sgpr_spill_count: 63
    .symbol:         _Z8mega_fwd6Params.kd
    .uniform_work_group_size: 1
    .uses_dynamic_stack: false
    .vgpr_count:     245
    .vgpr_spill_count: 0
    .wavefront_size: 64
